# speedup vs baseline: 1.0001x; 1.0001x over previous
; #define LAS __attribute__((address_space(3)))
; __device__ __forceinline__ int opaque_tid() { int t; asm volatile("v_mov_b32 %0, %1" : "=v"(t) : "v"(threadIdx.x)); return t; }
; __device__ __forceinline__ int v_rd_base(int lane) { return ((lane & 3) << 3) | (((lane >> 2) & 3) << 6) | (((lane >> 4) & 1) << 5) | (((lane >> 5) & 1) << 8); }
; __device__ __forceinline__ void attn_body256(const bf16_t* __restrict__ Qb, const bf16_t* __restrict__ Kh, const bf16_t* __restrict__ Vh,
;                                              bf16_t* Ob, int seq, unsigned char* lds, float lam, int MODE, bf16_t* Ab, const float* wsub) {
;   const int tid = opaque_tid(), wid = __builtin_amdgcn_readfirstlane(tid >> 6), lane = tid & 63, r32 = lane & 31, hi = lane >> 5;
;   LAS unsigned char* ldsl = (LAS unsigned char*)lds;
;   float* ws = (float*)(lds + A2_WS) + wid * 64; float* li_l = ws; float* al_l = ws + 32;
;   unsigned koff[2], voff[4];
; #pragma unroll
;   for (int i = 0; i < 2; ++i) { const int o = i * 8192 + tid * 16; const int row = o >> 8; const int colB = (o & 255) ^ ((row & 7) << 4);
;     koff[i] = (unsigned)(row * LDK + (colB >> 1));
;     const int sub = o >> 9, kk = (sub >> 2) * 8 + ((o & 511) >> 6), c = (sub & 3) * 32 + (((o & 511) >> 1) & 31);
;     const int k = (kk & ~0xC) | ((kk & 4) << 1) | ((kk & 8) >> 1);
;     voff[i] = (unsigned)(k * LDK + c); voff[2 + i] = (unsigned)(k * LDK + 128 + c); }
;     ...
;   const int NT = seq / KVBLK;
;   A2_DMA(0, 0); A2_DMA(1, 1);
;   float m_reg = -1e30f, l_reg = 0; f32x16 o[8] = {}; bf16x8 qr[8];
;   const bf16_t* Qw = Qb + (long)(wid * QBLK + r32) * LDQ + hi * 8;
; #pragma unroll
;   for (int d0 = 0; d0 < 8; ++d0) qr[d0] = *reinterpret_cast<const bf16x8*>(Qw + d0 * 16);
;   const int vb0 = (int)(uintptr_t)lds + v_rd_base(lane);
;   asm volatile("s_waitcnt vmcnt(0)" ::: "memory"); __syncthreads();
.LBB0_669:
	s_and_b32 s2, s18, 1
	s_lshl_b64 s[10:11], s[62:63], 11
	s_lshl_b64 s[6:7], s[62:63], 12
	s_add_u32 s9, s96, s6
	s_addc_u32 s12, s97, s7
	s_lshl_b32 s16, s8, 8
	s_lshl_b32 s6, s2, 7
	s_or_b32 s6, s16, s6
	s_ashr_i32 s7, s6, 31
	s_lshl_b64 s[14:15], s[6:7], 1
	s_add_u32 s6, s9, s14
	s_addc_u32 s7, s12, s15
	s_lshl_b64 s[8:9], s[0:1], 1
	s_add_u32 s0, s60, s8
	s_addc_u32 s1, s53, s9
	s_add_u32 s12, s0, s14
	s_addc_u32 s13, s1, s15
	v_mov_b32 v16, v231
	s_add_u32 s20, s61, s8
	v_lshlrev_b32_e32 v17, 4, v16
	v_add_u32_e32 v6, 0x2000, v17
	s_addc_u32 s21, s68, s9
	s_ashr_i32 s17, s16, 31
	v_ashrrev_i32_e32 v8, 8, v6
	s_lshl_b64 s[0:1], s[16:17], 1
	v_and_b32_e32 v3, 0xf0, v17
	v_lshlrev_b32_e32 v6, 4, v8
	s_movk_i32 s26, 0x70
	s_add_u32 s16, s20, s0
	v_lshrrev_b32_e32 v0, 1, v16
	v_ashrrev_i32_e32 v2, 4, v16
	v_bitop3_b32 v3, v6, v3, s26 bitop3:0x6c
	s_addc_u32 s17, s21, s1
	v_readfirstlane_b32 s20, v16
	v_and_b32_e32 v22, 8, v0
	v_and_b32_e32 v0, 0x70, v16
	s_movk_i32 s21, 0xf0
	v_lshrrev_b32_e32 v4, 1, v2
	v_lshrrev_b32_e32 v3, 1, v3
	s_ashr_i32 s23, s20, 6
	v_bfe_u32 v18, v16, 2, 2
	v_lshlrev_b32_e32 v20, 3, v16
	v_bitop3_b32 v0, v17, v0, s21 bitop3:0x6c
	v_and_b32_e32 v4, 4, v4
	v_lshl_or_b32 v6, v8, 11, v3
	v_and_b32_e32 v3, 0x1ffff0, v8
	v_lshrrev_b32_e32 v8, 1, v8
	v_and_b32_e32 v19, 0x60, v16
	v_and_b32_e32 v21, 24, v20
	v_or_b32_e32 v7, v22, v18
	v_lshrrev_b32_e32 v0, 1, v0
	v_and_or_b32 v23, v2, -16, v4
	v_and_b32_e32 v8, 4, v8
	s_lshl_b32 s21, s23, 10
	v_or_b32_e32 v5, v21, v19
	v_lshl_or_b32 v0, v2, 11, v0
	v_or_b32_e32 v2, v7, v23
	v_or3_b32 v3, v3, v8, v7
	s_add_i32 s21, s21, 0
	v_lshl_or_b32 v2, v2, 11, v5
	v_lshlrev_b32_e32 v24, 11, v3
	s_add_i32 s22, s21, 0x10000
	v_lshlrev_b64 v[12:13], 1, v[0:1]
	v_mov_b32_e32 v3, v1
	v_or_b32_e32 v4, 0x80, v2
	v_lshl_add_u64 v[14:15], s[12:13], 0, v[12:13]
	s_mov_b32 m0, s22
	v_lshlrev_b64 v[2:3], 1, v[2:3]
	s_add_i32 s24, s21, 0x4000
	global_load_lds_dwordx4 v[14:15], off
	v_lshl_add_u64 v[14:15], s[16:17], 0, v[2:3]
	s_mov_b32 m0, s21
	s_mov_b64 s[30:31], 0x100
	v_mov_b32_e32 v7, v1
	s_and_b32 s20, s20, 0x3fffffc0
	v_or_b32_e32 v8, v24, v5
	global_load_lds_dwordx4 v[14:15], off
	v_lshl_add_u64 v[14:15], v[14:15], 0, s[30:31]
	s_mov_b32 m0, s24
	v_lshlrev_b64 v[6:7], 1, v[6:7]
	v_mov_b32_e32 v9, v1
	s_lshl_b32 s20, s20, 2
	v_or_b32_e32 v10, 0x80, v8
	global_load_lds_dwordx4 v[14:15], off
	v_lshl_add_u64 v[14:15], s[12:13], 0, v[6:7]
	s_add_i32 m0, s21, 0x12000
	v_lshlrev_b64 v[8:9], 1, v[8:9]
	s_add_i32 s20, s20, 0
	global_load_lds_dwordx4 v[14:15], off
	v_lshl_add_u64 v[14:15], s[16:17], 0, v[8:9]
	s_add_i32 m0, s21, 0x2000
	s_add_i32 s20, s20, 0x18000
	global_load_lds_dwordx4 v[14:15], off
	s_add_i32 m0, s21, 0x6000
	s_add_u32 s12, s12, 0x40000
	s_addc_u32 s13, s13, 0
	v_lshl_add_u64 v[14:15], v[14:15], 0, s[30:31]
	s_add_u32 s16, s16, 0x40000
	global_load_lds_dwordx4 v[14:15], off
	s_addc_u32 s17, s17, 0
	s_add_i32 m0, s21, 0x14000
	s_add_i32 s24, s21, 0x8000
	v_lshl_add_u64 v[14:15], s[12:13], 0, v[12:13]
	v_mov_b32_e32 v5, v1
	s_add_i32 s25, s21, 0xc000
	global_load_lds_dwordx4 v[14:15], off
	v_lshl_add_u64 v[2:3], s[16:17], 0, v[2:3]
	s_mov_b32 m0, s24
	v_mov_b32_e32 v11, v1
	global_load_lds_dwordx4 v[2:3], off
	v_lshl_add_u64 v[2:3], v[4:5], 1, s[16:17]
	s_mov_b32 m0, s25
	v_and_b32_e32 v228, 31, v16
	global_load_lds_dwordx4 v[2:3], off
	v_lshl_add_u64 v[2:3], s[12:13], 0, v[6:7]
	s_add_i32 m0, s21, 0x16000
	s_lshl_b32 s12, s23, 5
	global_load_lds_dwordx4 v[2:3], off
	v_lshl_add_u64 v[2:3], s[16:17], 0, v[8:9]
	s_add_i32 m0, s21, 0xa000
	v_bfe_u32 v229, v16, 5, 1
	global_load_lds_dwordx4 v[2:3], off
	v_lshl_add_u64 v[2:3], v[10:11], 1, s[16:17]
	s_add_i32 m0, s21, 0xe000
	v_lshlrev_b32_e32 v0, 4, v229
	global_load_lds_dwordx4 v[2:3], off
	v_and_b32_e32 v2, 15, v231
	v_or_b32_e32 v2, s12, v2
	v_mov_b32_e32 v3, 0
	v_lshlrev_b64 v[2:3], 12, v[2:3]
	v_lshl_add_u64 v[2:3], s[6:7], 0, v[2:3]
	v_bfe_u32 v194, v231, 4, 2
	v_lshlrev_b32_e32 v194, 4, v194
	v_mov_b32_e32 v195, 0
	v_lshl_add_u64 v[2:3], v[2:3], 0, v[194:195]
	global_load_dwordx4 v[162:165], v[2:3], off
	global_load_dwordx4 v[166:169], v[2:3], off offset:64
	global_load_dwordx4 v[170:173], v[2:3], off offset:128
	global_load_dwordx4 v[174:177], v[2:3], off offset:192
	v_mov_b32_e32 v194, 0x10000
	v_lshl_add_u64 v[2:3], v[2:3], 0, v[194:195]
	global_load_dwordx4 v[178:181], v[2:3], off
	global_load_dwordx4 v[182:185], v[2:3], off offset:64
	global_load_dwordx4 v[186:189], v[2:3], off offset:128
	global_load_dwordx4 v[190:193], v[2:3], off offset:192
	v_and_b32_e32 v8, 0x70, v17
	s_movk_i32 s6, 0x60
	v_bitop3_b32 v236, v0, v8, s6 bitop3:0x36
	s_movk_i32 s6, 0x80
	v_bitop3_b32 v237, v0, v8, s6 bitop3:0x36
	s_movk_i32 s6, 0xa0
	v_bitop3_b32 v240, v0, v8, s6 bitop3:0x36
	s_movk_i32 s6, 0xc0
	s_cmp_lg_u32 0, -1
	v_and_b32_e32 v2, 63, v16
	v_lshlrev_b32_e32 v3, 1, v16
	v_and_b32_e32 v4, 0x118, v20
	v_bitop3_b32 v241, v0, v8, s6 bitop3:0x36
	s_movk_i32 s6, 0xe0
	s_cselect_b32 s16, 0, 0
	s_lshl_b32 s23, s19, 18
	v_and_b32_e32 v5, 0xc0, v17
	v_bitop3_b32 v247, v0, v8, s6 bitop3:0x36
	v_cmp_gt_u32_e64 s[6:7], 32, v2
	v_and_or_b32 v2, v3, 32, v4
	s_add_u32 s14, s8, s14
	v_add3_u32 v248, v5, s16, v2
	s_addc_u32 s15, s9, s15
	v_readlane_b32 s16, v254, 41
	s_add_u32 s14, s16, s14
	v_readlane_b32 s16, v254, 42
	s_addc_u32 s15, s16, s15
	s_add_u32 s8, s8, s0
	s_addc_u32 s9, s9, s1
	v_or3_b32 v2, v23, v22, v18
	v_lshlrev_b32_e32 v2, 11, v2
	s_add_u32 s8, s88, s8
	v_or3_b32 v2, v2, v19, v21
	v_mov_b32_e32 v3, v1
	s_addc_u32 s9, s89, s9
	s_waitcnt vmcnt(0)
; #define SBAR() __builtin_amdgcn_sched_barrier(0)
; __device__ __forceinline__ int v_rd_base(int lane) { return ((lane & 3) << 3) | (((lane >> 2) & 3) << 6) | (((lane >> 4) & 1) << 5) | (((lane >> 5) & 1) << 8); }
; __device__ __forceinline__ void qkt(f32x16& p0, f32x16& p1, const bf16_t* Ks, const bf16x8* qr, int r32, int hi) {
;   p0 = f32x16{}; p1 = f32x16{};
;   for (int d0 = 0; d0 < 8; ++d0) { int cb = (d0 * 16 + hi * 8) * 2;
;     bf16x8 b0 = *reinterpret_cast<const bf16x8*>((const char*)Ks + KSWZ(r32, cb));
;     bf16x8 b1 = *reinterpret_cast<const bf16x8*>((const char*)Ks + KSWZ(32 + r32, cb));
;     p0 = __builtin_amdgcn_mfma_f32_32x32x16_bf16(b0, qr[d0], p0, 0, 0, 0);
;     p1 = __builtin_amdgcn_mfma_f32_32x32x16_bf16(b1, qr[d0], p1, 0, 0, 0); }
; }
; __device__ __forceinline__ void attn_body256(const bf16_t* __restrict__ Qb, const bf16_t* __restrict__ Kh, const bf16_t* __restrict__ Vh,
;                                              bf16_t* Ob, int seq, unsigned char* lds, float lam, int MODE, bf16_t* Ab, const float* wsub) {
;     ...
;   float m_reg = -1e30f, l_reg = 0; f32x16 o[8] = {}; bf16x8 qr[8];
;   const bf16_t* Qw = Qb + (long)(wid * QBLK + r32) * LDQ + hi * 8;
; #pragma unroll
;   for (int d0 = 0; d0 < 8; ++d0) qr[d0] = *reinterpret_cast<const bf16x8*>(Qw + d0 * 16);
;   const int vb0 = (int)(uintptr_t)lds + v_rd_base(lane);
;   asm volatile("s_waitcnt vmcnt(0)" ::: "memory"); __syncthreads();
;   for (int j = 0; j < NT; ++j) {
;     const int b = j & 1;
;     f32x16 p0, p1; float mn, alpha; bf16x8 pa0, pa1, pa2, pa3;
;     SBAR(); qkt(p0, p1, (const bf16_t*)(lds + A2_KOFF + b * A2_KBUF), qr, r32, hi);
	v_bitop3_b32 v232, v0, v17, s26 bitop3:0x78
	v_lshl_add_u64 v[224:225], v[2:3], 1, s[8:9]
	v_or3_b32 v2, v24, v19, v21
	v_mov_b32_e32 v16, v1
	v_mov_b32_e32 v17, v1
	v_bitop3_b32 v233, v0, v8, 32 bitop3:0x36
	v_bitop3_b32 v234, v0, v8, 64 bitop3:0x36
	v_lshl_add_u64 v[220:221], s[14:15], 0, v[12:13]
	v_lshl_add_u64 v[222:223], s[14:15], 0, v[6:7]
	v_lshl_add_u64 v[226:227], v[2:3], 1, s[8:9]
	v_mov_b32_e32 v2, v1
	v_mov_b32_e32 v4, v1
	v_mov_b32_e32 v5, v1
	v_mov_b32_e32 v6, v1
	v_mov_b32_e32 v7, v1
	v_mov_b32_e32 v8, v1
	v_mov_b32_e32 v9, v1
	v_mov_b32_e32 v10, v1
	v_mov_b32_e32 v12, v1
	v_mov_b32_e32 v13, v1
	v_mov_b32_e32 v14, v1
	v_mov_b32_e32 v15, v1
	v_mov_b64_e32 v[128:129], v[16:17]
	v_mov_b64_e32 v[112:113], v[16:17]
	v_mov_b64_e32 v[96:97], v[16:17]
	v_mov_b64_e32 v[80:81], v[16:17]
	v_mov_b64_e32 v[64:65], v[16:17]
	v_mov_b64_e32 v[48:49], v[16:17]
	v_mov_b64_e32 v[32:33], v[16:17]
	s_mov_b32 s13, 2
	v_lshlrev_b32_e32 v230, 8, v228
	v_lshl_add_u32 v238, v228, 2, s20
	v_mov_b32_e32 v250, 0
	v_mov_b32_e32 v249, 0xf149f2ca
	s_mov_b64 s[14:15], 0
	v_mov_b64_e32 v[126:127], v[14:15]
	v_mov_b64_e32 v[124:125], v[12:13]
	v_mov_b64_e32 v[122:123], v[10:11]
	v_mov_b64_e32 v[120:121], v[8:9]
	v_mov_b64_e32 v[118:119], v[6:7]
	v_mov_b64_e32 v[116:117], v[4:5]
	v_mov_b64_e32 v[114:115], v[2:3]
	v_mov_b64_e32 v[110:111], v[14:15]
	v_mov_b64_e32 v[108:109], v[12:13]
	v_mov_b64_e32 v[106:107], v[10:11]
	v_mov_b64_e32 v[104:105], v[8:9]
	v_mov_b64_e32 v[102:103], v[6:7]
	v_mov_b64_e32 v[100:101], v[4:5]
	v_mov_b64_e32 v[98:99], v[2:3]
	v_mov_b64_e32 v[94:95], v[14:15]
	v_mov_b64_e32 v[92:93], v[12:13]
	v_mov_b64_e32 v[90:91], v[10:11]
	v_mov_b64_e32 v[88:89], v[8:9]
	v_mov_b64_e32 v[86:87], v[6:7]
	v_mov_b64_e32 v[84:85], v[4:5]
	v_mov_b64_e32 v[82:83], v[2:3]
	v_mov_b64_e32 v[78:79], v[14:15]
	v_mov_b64_e32 v[76:77], v[12:13]
	v_mov_b64_e32 v[74:75], v[10:11]
	v_mov_b64_e32 v[72:73], v[8:9]
	v_mov_b64_e32 v[70:71], v[6:7]
	v_mov_b64_e32 v[68:69], v[4:5]
	v_mov_b64_e32 v[66:67], v[2:3]
	v_mov_b64_e32 v[62:63], v[14:15]
	v_mov_b64_e32 v[60:61], v[12:13]
	v_mov_b64_e32 v[58:59], v[10:11]
	v_mov_b64_e32 v[56:57], v[8:9]
	v_mov_b64_e32 v[54:55], v[6:7]
	v_mov_b64_e32 v[52:53], v[4:5]
	v_mov_b64_e32 v[50:51], v[2:3]
	v_mov_b64_e32 v[46:47], v[14:15]
	v_mov_b64_e32 v[44:45], v[12:13]
	v_mov_b64_e32 v[42:43], v[10:11]
	v_mov_b64_e32 v[40:41], v[8:9]
	v_mov_b64_e32 v[38:39], v[6:7]
	v_mov_b64_e32 v[36:37], v[4:5]
	v_mov_b64_e32 v[34:35], v[2:3]
	v_mov_b64_e32 v[30:31], v[14:15]
	v_mov_b64_e32 v[28:29], v[12:13]
	v_mov_b64_e32 v[26:27], v[10:11]
	v_mov_b64_e32 v[24:25], v[8:9]
	v_mov_b64_e32 v[22:23], v[6:7]
	v_mov_b64_e32 v[20:21], v[4:5]
	v_mov_b64_e32 v[18:19], v[2:3]
	v_and_b32_e32 v237, 15, v231
	v_bfe_u32 v240, v231, 4, 2
	v_and_b32_e32 v241, 7, v237
	v_lshlrev_b32_e32 v241, 4, v241
	v_lshlrev_b32_e32 v247, 4, v240
	v_xor_b32_e32 v232, v247, v241
	v_add_u32_e32 v247, 64, v247
	v_xor_b32_e32 v233, v247, v241
	v_lshlrev_b32_e32 v247, 8, v237
	v_add_u32_e32 v232, v232, v247
	v_add_u32_e32 v233, v233, v247
	v_and_b32_e32 v247, 1, v240
	v_lshlrev_b32_e32 v248, 11, v247
	v_lshrrev_b32_e32 v247, 1, v240
	v_lshl_add_u32 v248, v247, 8, v248
	v_bfe_u32 v247, v231, 2, 2
	v_lshl_add_u32 v248, v247, 6, v248
	v_and_b32_e32 v247, 3, v231
	v_lshl_add_u32 v248, v247, 3, v248
	v_mov_b32_e32 v249, 0xf149f2ca
	v_mov_b32_e32 v246, 0xf149f2ca
	v_mov_b32_e32 v250, 0
	v_mov_b32_e32 v234, 0
	s_movk_i32 s62, 0x7fff
	s_waitcnt vmcnt(0) lgkmcnt(0)
	s_barrier
.Lat_top:
	s_add_i32 s8, s13, -2
	s_and_b32 s25, s8, 1
	s_lshl_b32 s24, s25, 14
	s_add_i32 s8, s24, 0x10000
	v_add_u32_e32 v230, s8, v232
	v_add_u32_e32 v247, s8, v233
	s_lshl_b32 s9, s25, 15
	v_add_u32_e32 v244, s9, v248
	ds_read_b128 v[194:197], v230
	ds_read_b128 v[198:201], v230 offset:4096
	ds_read_b128 v[202:205], v230 offset:8192
	ds_read_b128 v[206:209], v230 offset:12288
	ds_read_b128 v[210:213], v247
	ds_read_b128 v[214:217], v247 offset:4096
	s_waitcnt lgkmcnt(5)
	v_mfma_f32_16x16x32_bf16 v[130:133], v[194:197], v[162:165], 0
	v_mfma_f32_16x16x32_bf16 v[134:137], v[194:197], v[178:181], 0
	ds_read_b128 v[194:197], v247 offset:8192
	s_waitcnt lgkmcnt(5)
	v_mfma_f32_16x16x32_bf16 v[138:141], v[198:201], v[162:165], 0
	v_mfma_f32_16x16x32_bf16 v[142:145], v[198:201], v[178:181], 0
	ds_read_b128 v[198:201], v247 offset:12288
	s_waitcnt lgkmcnt(5)
	v_mfma_f32_16x16x32_bf16 v[146:149], v[202:205], v[162:165], 0
	v_mfma_f32_16x16x32_bf16 v[150:153], v[202:205], v[178:181], 0
	ds_read_b128 v[202:205], v230 offset:128
	s_waitcnt lgkmcnt(5)
	v_mfma_f32_16x16x32_bf16 v[154:157], v[206:209], v[162:165], 0
	v_mfma_f32_16x16x32_bf16 v[158:161], v[206:209], v[178:181], 0
	ds_read_b128 v[206:209], v230 offset:4224
	s_waitcnt lgkmcnt(5)
	v_mfma_f32_16x16x32_bf16 v[130:133], v[210:213], v[166:169], v[130:133]
	v_mfma_f32_16x16x32_bf16 v[134:137], v[210:213], v[182:185], v[134:137]
	ds_read_b128 v[210:213], v230 offset:8320
	s_waitcnt lgkmcnt(5)
	v_mfma_f32_16x16x32_bf16 v[138:141], v[214:217], v[166:169], v[138:141]
	v_mfma_f32_16x16x32_bf16 v[142:145], v[214:217], v[182:185], v[142:145]
	ds_read_b128 v[214:217], v230 offset:12416
	s_waitcnt lgkmcnt(5)
	v_mfma_f32_16x16x32_bf16 v[146:149], v[194:197], v[166:169], v[146:149]
	v_mfma_f32_16x16x32_bf16 v[150:153], v[194:197], v[182:185], v[150:153]
	ds_read_b128 v[194:197], v247 offset:128
	s_waitcnt lgkmcnt(5)
	v_mfma_f32_16x16x32_bf16 v[154:157], v[198:201], v[166:169], v[154:157]
	v_mfma_f32_16x16x32_bf16 v[158:161], v[198:201], v[182:185], v[158:161]
	ds_read_b128 v[198:201], v247 offset:4224
	s_waitcnt lgkmcnt(5)
; __device__ __forceinline__ int crow(int r, int hi) { return (r & 3) + 8 * (r >> 2) + 4 * hi; }
; __device__ __forceinline__ int crow(int r, int hi) { return (r & 3) + 8 * (r >> 2) + 4 * hi; }
; __device__ __forceinline__ void partialSM(f32x16& p0, f32x16& p1, float& m_reg, float& mn, float& alpha) {
;   constexpr float C = SCALE * 1.4426950408889634f;
;   float pmax = p0[0]; for (int r = 1; r < 16; ++r) pmax = fmaxf(pmax, p0[r]); for (int r = 0; r < 16; ++r) pmax = fmaxf(pmax, p1[r]);
;   { auto rr = __builtin_amdgcn_permlane32_swap(__float_as_uint(pmax), __float_as_uint(pmax), false, false);
;     pmax = fmaxf(__uint_as_float(rr[0]), __uint_as_float(rr[1])); }
;   if (__builtin_expect(__all(pmax - m_reg <= THR / SCALE), 1)) { mn = m_reg; alpha = 1.f; }
;   else { mn = fmaxf(m_reg, pmax); alpha = __builtin_amdgcn_exp2f((m_reg - mn) * C); m_reg = mn; }
;   float mnC = -mn * C;
;   for (int r = 0; r < 16; ++r) p0[r] = fmaf(p0[r], C, mnC); for (int r = 0; r < 16; ++r) p1[r] = fmaf(p1[r], C, mnC);
;   for (int r = 0; r < 16; ++r) p0[r] = __builtin_amdgcn_exp2f(p0[r]);
; }
; __device__ __forceinline__ void attn_body256(const bf16_t* __restrict__ Qb, const bf16_t* __restrict__ Kh, const bf16_t* __restrict__ Vh,
;                                              bf16_t* Ob, int seq, unsigned char* lds, float lam, int MODE, bf16_t* Ab, const float* wsub) {
;     ...
;     if (__any(alpha < 1.f)) { if (hi == 0) al_l[r32] = alpha; asm volatile("s_waitcnt lgkmcnt(0)" ::: "memory");
; #pragma unroll
;       for (int r = 0; r < 16; ++r) { const float a = al_l[crow(r, hi)];
; #pragma unroll
;         for (int d = 0; d < 8; ++d) o[d][r] *= a; } }
	v_mfma_f32_16x16x32_bf16 v[130:133], v[202:205], v[170:173], v[130:133]
	v_mfma_f32_16x16x32_bf16 v[134:137], v[202:205], v[186:189], v[134:137]
	ds_read_b128 v[202:205], v247 offset:8320
	s_waitcnt lgkmcnt(5)
	v_mfma_f32_16x16x32_bf16 v[138:141], v[206:209], v[170:173], v[138:141]
	v_mfma_f32_16x16x32_bf16 v[142:145], v[206:209], v[186:189], v[142:145]
	ds_read_b128 v[206:209], v247 offset:12416
	s_waitcnt lgkmcnt(5)
	v_mfma_f32_16x16x32_bf16 v[146:149], v[210:213], v[170:173], v[146:149]
	v_mfma_f32_16x16x32_bf16 v[150:153], v[210:213], v[186:189], v[150:153]
	s_waitcnt lgkmcnt(4)
	v_mfma_f32_16x16x32_bf16 v[154:157], v[214:217], v[170:173], v[154:157]
	v_mfma_f32_16x16x32_bf16 v[158:161], v[214:217], v[186:189], v[158:161]
	s_waitcnt lgkmcnt(3)
	v_mfma_f32_16x16x32_bf16 v[130:133], v[194:197], v[174:177], v[130:133]
	v_mfma_f32_16x16x32_bf16 v[134:137], v[194:197], v[190:193], v[134:137]
	s_waitcnt lgkmcnt(2)
	v_mfma_f32_16x16x32_bf16 v[138:141], v[198:201], v[174:177], v[138:141]
	v_mfma_f32_16x16x32_bf16 v[142:145], v[198:201], v[190:193], v[142:145]
	s_waitcnt lgkmcnt(1)
	v_mfma_f32_16x16x32_bf16 v[146:149], v[202:205], v[174:177], v[146:149]
	v_mfma_f32_16x16x32_bf16 v[150:153], v[202:205], v[190:193], v[150:153]
	s_waitcnt lgkmcnt(0)
	v_mfma_f32_16x16x32_bf16 v[154:157], v[206:209], v[174:177], v[154:157]
	v_mfma_f32_16x16x32_bf16 v[158:161], v[206:209], v[190:193], v[158:161]
	s_nop 7
	v_max3_f32 v194, v130, v131, v132
	v_max3_f32 v194, v194, v133, v138
	v_max3_f32 v194, v194, v139, v140
	v_max3_f32 v194, v194, v141, v146
	v_max3_f32 v194, v194, v147, v148
	v_max3_f32 v194, v194, v149, v154
	v_max3_f32 v194, v194, v155, v156
	v_max_f32_e32 v194, v194, v157
	v_max3_f32 v195, v134, v135, v136
	v_max3_f32 v195, v195, v137, v142
	v_max3_f32 v195, v195, v143, v144
	v_max3_f32 v195, v195, v145, v150
	v_max3_f32 v195, v195, v151, v152
	v_max3_f32 v195, v195, v153, v158
	v_max3_f32 v195, v195, v159, v160
	v_max_f32_e32 v195, v195, v161
	v_mov_b32_e32 v196, v194
	v_mov_b32_e32 v197, v195
	s_nop 1
	v_permlane32_swap_b32_e32 v194, v196
	v_permlane32_swap_b32_e32 v195, v197
	v_max_f32_e32 v194, v194, v196
	v_max_f32_e32 v195, v195, v197
	v_mov_b32_e32 v196, v194
	v_mov_b32_e32 v197, v195
	s_nop 1
	v_permlane16_swap_b32_e32 v194, v196
	v_permlane16_swap_b32_e32 v195, v197
	v_max_f32_e32 v194, v194, v196
	v_max_f32_e32 v195, v195, v197
	v_sub_f32_e32 v196, v194, v249
	v_sub_f32_e32 v197, v195, v246
	v_max_f32_e32 v196, v196, v197
	v_cmp_ge_f32_e32 vcc, 0x42b504f3, v196
	v_max_f32_e32 v198, v249, v194
	v_max_f32_e32 v199, v246, v195
	v_sub_f32_e32 v196, v249, v198
	v_sub_f32_e32 v197, v246, v199
	v_mul_f32_e32 v196, 0x3e0293ee, v196
	v_mul_f32_e32 v197, 0x3e0293ee, v197
	v_exp_f32_e32 v196, v196
	v_exp_f32_e32 v197, v197
	s_cmp_eq_u64 vcc, exec
	s_cselect_b64 s[8:9], -1, 0
	v_cndmask_b32_e64 v236, v196, 1.0, s[8:9]
	v_cndmask_b32_e64 v240, v197, 1.0, s[8:9]
	v_cndmask_b32_e64 v249, v198, v249, s[8:9]
	v_cndmask_b32_e64 v246, v199, v246, s[8:9]
	s_cbranch_scc1 .Lat_noresc
	v_pk_mul_f32 v[2:3], v[2:3], v[236:237] op_sel_hi:[1,0]
	v_pk_mul_f32 v[4:5], v[4:5], v[236:237] op_sel_hi:[1,0]
	v_pk_mul_f32 v[6:7], v[6:7], v[240:241] op_sel_hi:[1,0]
	v_pk_mul_f32 v[8:9], v[8:9], v[240:241] op_sel_hi:[1,0]
	v_pk_mul_f32 v[10:11], v[10:11], v[236:237] op_sel_hi:[1,0]
	v_pk_mul_f32 v[12:13], v[12:13], v[236:237] op_sel_hi:[1,0]
	v_pk_mul_f32 v[14:15], v[14:15], v[240:241] op_sel_hi:[1,0]
	v_pk_mul_f32 v[16:17], v[16:17], v[240:241] op_sel_hi:[1,0]
	v_pk_mul_f32 v[114:115], v[114:115], v[236:237] op_sel_hi:[1,0]
	v_pk_mul_f32 v[116:117], v[116:117], v[236:237] op_sel_hi:[1,0]
	v_pk_mul_f32 v[118:119], v[118:119], v[240:241] op_sel_hi:[1,0]
	v_pk_mul_f32 v[120:121], v[120:121], v[240:241] op_sel_hi:[1,0]
	v_pk_mul_f32 v[122:123], v[122:123], v[236:237] op_sel_hi:[1,0]
	v_pk_mul_f32 v[124:125], v[124:125], v[236:237] op_sel_hi:[1,0]
	v_pk_mul_f32 v[126:127], v[126:127], v[240:241] op_sel_hi:[1,0]
	v_pk_mul_f32 v[128:129], v[128:129], v[240:241] op_sel_hi:[1,0]
	v_pk_mul_f32 v[98:99], v[98:99], v[236:237] op_sel_hi:[1,0]
	v_pk_mul_f32 v[100:101], v[100:101], v[236:237] op_sel_hi:[1,0]
	v_pk_mul_f32 v[102:103], v[102:103], v[240:241] op_sel_hi:[1,0]
	v_pk_mul_f32 v[104:105], v[104:105], v[240:241] op_sel_hi:[1,0]
	v_pk_mul_f32 v[106:107], v[106:107], v[236:237] op_sel_hi:[1,0]
	v_pk_mul_f32 v[108:109], v[108:109], v[236:237] op_sel_hi:[1,0]
	v_pk_mul_f32 v[110:111], v[110:111], v[240:241] op_sel_hi:[1,0]
	v_pk_mul_f32 v[112:113], v[112:113], v[240:241] op_sel_hi:[1,0]
	v_pk_mul_f32 v[82:83], v[82:83], v[236:237] op_sel_hi:[1,0]
	v_pk_mul_f32 v[84:85], v[84:85], v[236:237] op_sel_hi:[1,0]
	v_pk_mul_f32 v[86:87], v[86:87], v[240:241] op_sel_hi:[1,0]
	v_pk_mul_f32 v[88:89], v[88:89], v[240:241] op_sel_hi:[1,0]
	v_pk_mul_f32 v[90:91], v[90:91], v[236:237] op_sel_hi:[1,0]
	v_pk_mul_f32 v[92:93], v[92:93], v[236:237] op_sel_hi:[1,0]
	v_pk_mul_f32 v[94:95], v[94:95], v[240:241] op_sel_hi:[1,0]
	v_pk_mul_f32 v[96:97], v[96:97], v[240:241] op_sel_hi:[1,0]
	v_pk_mul_f32 v[66:67], v[66:67], v[236:237] op_sel_hi:[1,0]
	v_pk_mul_f32 v[68:69], v[68:69], v[236:237] op_sel_hi:[1,0]
	v_pk_mul_f32 v[70:71], v[70:71], v[240:241] op_sel_hi:[1,0]
	v_pk_mul_f32 v[72:73], v[72:73], v[240:241] op_sel_hi:[1,0]
	v_pk_mul_f32 v[74:75], v[74:75], v[236:237] op_sel_hi:[1,0]
	v_pk_mul_f32 v[76:77], v[76:77], v[236:237] op_sel_hi:[1,0]
	v_pk_mul_f32 v[78:79], v[78:79], v[240:241] op_sel_hi:[1,0]
	v_pk_mul_f32 v[80:81], v[80:81], v[240:241] op_sel_hi:[1,0]
	v_pk_mul_f32 v[50:51], v[50:51], v[236:237] op_sel_hi:[1,0]
	v_pk_mul_f32 v[52:53], v[52:53], v[236:237] op_sel_hi:[1,0]
	v_pk_mul_f32 v[54:55], v[54:55], v[240:241] op_sel_hi:[1,0]
	v_pk_mul_f32 v[56:57], v[56:57], v[240:241] op_sel_hi:[1,0]
	v_pk_mul_f32 v[58:59], v[58:59], v[236:237] op_sel_hi:[1,0]
	v_pk_mul_f32 v[60:61], v[60:61], v[236:237] op_sel_hi:[1,0]
	v_pk_mul_f32 v[62:63], v[62:63], v[240:241] op_sel_hi:[1,0]
	v_pk_mul_f32 v[64:65], v[64:65], v[240:241] op_sel_hi:[1,0]
	v_pk_mul_f32 v[34:35], v[34:35], v[236:237] op_sel_hi:[1,0]
	v_pk_mul_f32 v[36:37], v[36:37], v[236:237] op_sel_hi:[1,0]
	v_pk_mul_f32 v[38:39], v[38:39], v[240:241] op_sel_hi:[1,0]
	v_pk_mul_f32 v[40:41], v[40:41], v[240:241] op_sel_hi:[1,0]
	v_pk_mul_f32 v[42:43], v[42:43], v[236:237] op_sel_hi:[1,0]
	v_pk_mul_f32 v[44:45], v[44:45], v[236:237] op_sel_hi:[1,0]
	v_pk_mul_f32 v[46:47], v[46:47], v[240:241] op_sel_hi:[1,0]
	v_pk_mul_f32 v[48:49], v[48:49], v[240:241] op_sel_hi:[1,0]
	v_pk_mul_f32 v[18:19], v[18:19], v[236:237] op_sel_hi:[1,0]
	v_pk_mul_f32 v[20:21], v[20:21], v[236:237] op_sel_hi:[1,0]
	v_pk_mul_f32 v[22:23], v[22:23], v[240:241] op_sel_hi:[1,0]
	v_pk_mul_f32 v[24:25], v[24:25], v[240:241] op_sel_hi:[1,0]
	v_pk_mul_f32 v[26:27], v[26:27], v[236:237] op_sel_hi:[1,0]
	v_pk_mul_f32 v[28:29], v[28:29], v[236:237] op_sel_hi:[1,0]
	v_pk_mul_f32 v[30:31], v[30:31], v[240:241] op_sel_hi:[1,0]
	v_pk_mul_f32 v[32:33], v[32:33], v[240:241] op_sel_hi:[1,0]
; #define SBAR() __builtin_amdgcn_sched_barrier(0)
; __device__ __forceinline__ void partialSM(f32x16& p0, f32x16& p1, float& m_reg, float& mn, float& alpha) {
;     ...
;   for (int r = 0; r < 16; ++r) p0[r] = fmaf(p0[r], C, mnC); for (int r = 0; r < 16; ++r) p1[r] = fmaf(p1[r], C, mnC);
;   for (int r = 0; r < 16; ++r) p0[r] = __builtin_amdgcn_exp2f(p0[r]);
; }
; __device__ __forceinline__ void finishSM(f32x16& p0, f32x16& p1, float alpha, float& l_reg, bf16x8& pa0, bf16x8& pa1, bf16x8& pa2, bf16x8& pa3) {
;   for (int r = 0; r < 16; ++r) p1[r] = __builtin_amdgcn_exp2f(p1[r]);
;   float ps = 0; for (int r = 0; r < 16; ++r) ps += p0[r]; for (int r = 0; r < 16; ++r) ps += p1[r];
;   { auto rr = __builtin_amdgcn_permlane32_swap(__float_as_uint(ps), __float_as_uint(ps), false, false);
;     ps = __uint_as_float(rr[0]) + __uint_as_float(rr[1]); }
;   l_reg = l_reg * alpha + ps;
;     ...
;   PK4(p0, 0, pa0); PK4(p0, 8, pa1); PK4(p1, 0, pa2); PK4(p1, 8, pa3);
; template <int B> __device__ __forceinline__ void pv_reads(VFrag& f, int vb) {
;   constexpr int base = (B >> 2) * 16384 + (B & 3) * 512;
;   f.l0 = tr_read<base + 0 * 4096>(vb); f.h0 = tr_read<base + 0 * 4096 + 2048>(vb); f.l1 = tr_read<base + 1 * 4096>(vb); f.h1 = tr_read<base + 1 * 4096 + 2048>(vb);
;   f.l2 = tr_read<base + 2 * 4096>(vb); f.h2 = tr_read<base + 2 * 4096 + 2048>(vb); f.l3 = tr_read<base + 3 * 4096>(vb); f.h3 = tr_read<base + 3 * 4096 + 2048>(vb);
; }
; __device__ __forceinline__ void pv_mma(f32x16& od, const VFrag& f, bf16x8 pa0, bf16x8 pa1, bf16x8 pa2, bf16x8 pa3) {
;     ...
;   od = __builtin_amdgcn_mfma_f32_32x32x16_bf16(pa0, PKV(f.l0, f.h0), od, 0, 0, 0);
;   od = __builtin_amdgcn_mfma_f32_32x32x16_bf16(pa1, PKV(f.l1, f.h1), od, 0, 0, 0);
;   od = __builtin_amdgcn_mfma_f32_32x32x16_bf16(pa2, PKV(f.l2, f.h2), od, 0, 0, 0);
;   od = __builtin_amdgcn_mfma_f32_32x32x16_bf16(pa3, PKV(f.l3, f.h3), od, 0, 0, 0);
;     ...
; }
; __device__ __forceinline__ void pv_all(f32x16* o, int vb, bf16x8 pa0, bf16x8 pa1, bf16x8 pa2, bf16x8 pa3) {
;   VFrag fc, fn;
;   pv_reads<0>(fc, vb);
;   PV_STEP(0); PV_STEP(1); PV_STEP(2); PV_STEP(3); PV_STEP(4); PV_STEP(5); PV_STEP(6);
;   asm volatile("s_waitcnt lgkmcnt(0)" ::: "memory"); SBAR(); pv_mma(o[7], fc, pa0, pa1, pa2, pa3);
; }
.Lat_noresc:
	v_mul_f32_e32 v198, 0xbe0293ee, v249
	v_mul_f32_e32 v199, 0xbe0293ee, v246
	v_fmamk_f32 v130, v130, 0x3e0293ee, v198
	v_fmamk_f32 v131, v131, 0x3e0293ee, v198
	v_fmamk_f32 v132, v132, 0x3e0293ee, v198
	v_fmamk_f32 v133, v133, 0x3e0293ee, v198
	v_fmamk_f32 v134, v134, 0x3e0293ee, v199
	v_fmamk_f32 v135, v135, 0x3e0293ee, v199
	v_fmamk_f32 v136, v136, 0x3e0293ee, v199
	v_fmamk_f32 v137, v137, 0x3e0293ee, v199
	v_fmamk_f32 v138, v138, 0x3e0293ee, v198
	v_fmamk_f32 v139, v139, 0x3e0293ee, v198
	v_fmamk_f32 v140, v140, 0x3e0293ee, v198
	v_fmamk_f32 v141, v141, 0x3e0293ee, v198
	v_fmamk_f32 v142, v142, 0x3e0293ee, v199
	v_fmamk_f32 v143, v143, 0x3e0293ee, v199
	v_fmamk_f32 v144, v144, 0x3e0293ee, v199
	v_fmamk_f32 v145, v145, 0x3e0293ee, v199
	v_fmamk_f32 v146, v146, 0x3e0293ee, v198
	v_fmamk_f32 v147, v147, 0x3e0293ee, v198
	v_fmamk_f32 v148, v148, 0x3e0293ee, v198
	v_fmamk_f32 v149, v149, 0x3e0293ee, v198
	v_fmamk_f32 v150, v150, 0x3e0293ee, v199
	v_fmamk_f32 v151, v151, 0x3e0293ee, v199
	v_fmamk_f32 v152, v152, 0x3e0293ee, v199
	v_fmamk_f32 v153, v153, 0x3e0293ee, v199
	v_fmamk_f32 v154, v154, 0x3e0293ee, v198
	v_fmamk_f32 v155, v155, 0x3e0293ee, v198
	v_fmamk_f32 v156, v156, 0x3e0293ee, v198
	v_fmamk_f32 v157, v157, 0x3e0293ee, v198
	v_fmamk_f32 v158, v158, 0x3e0293ee, v199
	v_fmamk_f32 v159, v159, 0x3e0293ee, v199
	v_fmamk_f32 v160, v160, 0x3e0293ee, v199
	v_fmamk_f32 v161, v161, 0x3e0293ee, v199
	v_exp_f32_e32 v130, v130
	v_exp_f32_e32 v131, v131
	v_exp_f32_e32 v132, v132
	v_exp_f32_e32 v133, v133
	v_exp_f32_e32 v134, v134
	v_exp_f32_e32 v135, v135
	v_exp_f32_e32 v136, v136
	v_exp_f32_e32 v137, v137
	v_exp_f32_e32 v138, v138
	v_exp_f32_e32 v139, v139
	v_exp_f32_e32 v140, v140
	v_exp_f32_e32 v141, v141
	v_exp_f32_e32 v142, v142
	v_exp_f32_e32 v143, v143
	v_exp_f32_e32 v144, v144
	v_exp_f32_e32 v145, v145
	v_exp_f32_e32 v146, v146
	v_exp_f32_e32 v147, v147
	v_exp_f32_e32 v148, v148
	v_exp_f32_e32 v149, v149
	v_exp_f32_e32 v150, v150
	v_exp_f32_e32 v151, v151
	v_exp_f32_e32 v152, v152
	v_exp_f32_e32 v153, v153
	v_exp_f32_e32 v154, v154
	v_exp_f32_e32 v155, v155
	v_exp_f32_e32 v156, v156
	v_exp_f32_e32 v157, v157
	v_exp_f32_e32 v158, v158
	v_exp_f32_e32 v159, v159
	v_exp_f32_e32 v160, v160
	v_exp_f32_e32 v161, v161
	v_add_f32_e32 v194, v130, v131
	v_add_f32_e32 v194, v194, v132
	v_add_f32_e32 v194, v194, v133
	v_add_f32_e32 v194, v194, v138
	v_add_f32_e32 v194, v194, v139
	v_add_f32_e32 v194, v194, v140
	v_add_f32_e32 v194, v194, v141
	v_add_f32_e32 v194, v194, v146
	v_add_f32_e32 v194, v194, v147
	v_add_f32_e32 v194, v194, v148
	v_add_f32_e32 v194, v194, v149
	v_add_f32_e32 v194, v194, v154
	v_add_f32_e32 v194, v194, v155
	v_add_f32_e32 v194, v194, v156
	v_add_f32_e32 v194, v194, v157
	v_add_f32_e32 v195, v134, v135
	v_add_f32_e32 v195, v195, v136
	v_add_f32_e32 v195, v195, v137
	v_add_f32_e32 v195, v195, v142
	v_add_f32_e32 v195, v195, v143
	v_add_f32_e32 v195, v195, v144
	v_add_f32_e32 v195, v195, v145
	v_add_f32_e32 v195, v195, v150
	v_add_f32_e32 v195, v195, v151
	v_add_f32_e32 v195, v195, v152
	v_add_f32_e32 v195, v195, v153
	v_add_f32_e32 v195, v195, v158
	v_add_f32_e32 v195, v195, v159
	v_add_f32_e32 v195, v195, v160
	v_add_f32_e32 v195, v195, v161
	v_fma_f32 v250, v250, v236, v194
	v_fma_f32 v234, v234, v240, v195
	v_cvt_pk_bf16_f32 v130, v130, v131
	v_cvt_pk_bf16_f32 v131, v132, v133
	v_cvt_pk_bf16_f32 v132, v138, v139
	v_cvt_pk_bf16_f32 v133, v140, v141
	v_cvt_pk_bf16_f32 v134, v134, v135
	v_cvt_pk_bf16_f32 v135, v136, v137
	v_cvt_pk_bf16_f32 v136, v142, v143
	v_cvt_pk_bf16_f32 v137, v144, v145
	v_cvt_pk_bf16_f32 v138, v146, v147
	v_cvt_pk_bf16_f32 v139, v148, v149
	v_cvt_pk_bf16_f32 v140, v154, v155
	v_cvt_pk_bf16_f32 v141, v156, v157
	v_cvt_pk_bf16_f32 v142, v150, v151
	v_cvt_pk_bf16_f32 v143, v152, v153
	v_cvt_pk_bf16_f32 v144, v158, v159
	v_cvt_pk_bf16_f32 v145, v160, v161
	ds_read_b64_tr_b16 v[146:147], v244
	ds_read_b64_tr_b16 v[148:149], v244 offset:4096
	ds_read_b64_tr_b16 v[150:151], v244 offset:8192
	ds_read_b64_tr_b16 v[152:153], v244 offset:12288
	ds_read_b64_tr_b16 v[154:155], v244 offset:32
	ds_read_b64_tr_b16 v[156:157], v244 offset:4128
	ds_read_b64_tr_b16 v[158:159], v244 offset:8224
	ds_read_b64_tr_b16 v[160:161], v244 offset:12320
	ds_read_b64_tr_b16 v[194:195], v244 offset:512
	ds_read_b64_tr_b16 v[196:197], v244 offset:4608
	ds_read_b64_tr_b16 v[198:199], v244 offset:8704
	ds_read_b64_tr_b16 v[200:201], v244 offset:12800
	s_waitcnt lgkmcnt(8)
	v_mfma_f32_16x16x32_bf16 v[2:5], v[146:149], v[130:133], v[2:5]
	v_mfma_f32_16x16x32_bf16 v[6:9], v[146:149], v[134:137], v[6:9]
	v_mfma_f32_16x16x32_bf16 v[2:5], v[150:153], v[138:141], v[2:5]
	v_mfma_f32_16x16x32_bf16 v[6:9], v[150:153], v[142:145], v[6:9]
	ds_read_b64_tr_b16 v[146:147], v244 offset:544
	ds_read_b64_tr_b16 v[148:149], v244 offset:4640
	ds_read_b64_tr_b16 v[150:151], v244 offset:8736
	ds_read_b64_tr_b16 v[152:153], v244 offset:12832
	s_waitcnt lgkmcnt(8)
	v_mfma_f32_16x16x32_bf16 v[10:13], v[154:157], v[130:133], v[10:13]
	v_mfma_f32_16x16x32_bf16 v[14:17], v[154:157], v[134:137], v[14:17]
	v_mfma_f32_16x16x32_bf16 v[10:13], v[158:161], v[138:141], v[10:13]
	v_mfma_f32_16x16x32_bf16 v[14:17], v[158:161], v[142:145], v[14:17]
	ds_read_b64_tr_b16 v[154:155], v244 offset:1024
	ds_read_b64_tr_b16 v[156:157], v244 offset:5120
	ds_read_b64_tr_b16 v[158:159], v244 offset:9216
	ds_read_b64_tr_b16 v[160:161], v244 offset:13312
	s_waitcnt lgkmcnt(8)
; #define SBAR() __builtin_amdgcn_sched_barrier(0)
; #define PV_STEP(B) do { pv_reads<(B) + 1>(fn, vb); asm volatile("s_waitcnt lgkmcnt(8)" ::: "memory"); SBAR(); pv_mma(o[B], fc, pa0, pa1, pa2, pa3); SBAR(); fc = fn; } while (0)
; template <int B> __device__ __forceinline__ void pv_reads(VFrag& f, int vb) {
;   constexpr int base = (B >> 2) * 16384 + (B & 3) * 512;
;   f.l0 = tr_read<base + 0 * 4096>(vb); f.h0 = tr_read<base + 0 * 4096 + 2048>(vb); f.l1 = tr_read<base + 1 * 4096>(vb); f.h1 = tr_read<base + 1 * 4096 + 2048>(vb);
;   f.l2 = tr_read<base + 2 * 4096>(vb); f.h2 = tr_read<base + 2 * 4096 + 2048>(vb); f.l3 = tr_read<base + 3 * 4096>(vb); f.h3 = tr_read<base + 3 * 4096 + 2048>(vb);
; }
; __device__ __forceinline__ void pv_mma(f32x16& od, const VFrag& f, bf16x8 pa0, bf16x8 pa1, bf16x8 pa2, bf16x8 pa3) {
;     ...
;   od = __builtin_amdgcn_mfma_f32_32x32x16_bf16(pa0, PKV(f.l0, f.h0), od, 0, 0, 0);
;   od = __builtin_amdgcn_mfma_f32_32x32x16_bf16(pa1, PKV(f.l1, f.h1), od, 0, 0, 0);
;   od = __builtin_amdgcn_mfma_f32_32x32x16_bf16(pa2, PKV(f.l2, f.h2), od, 0, 0, 0);
;   od = __builtin_amdgcn_mfma_f32_32x32x16_bf16(pa3, PKV(f.l3, f.h3), od, 0, 0, 0);
;     ...
; }
; __device__ __forceinline__ void pv_all(f32x16* o, int vb, bf16x8 pa0, bf16x8 pa1, bf16x8 pa2, bf16x8 pa3) {
;   VFrag fc, fn;
;   pv_reads<0>(fc, vb);
;   PV_STEP(0); PV_STEP(1); PV_STEP(2); PV_STEP(3); PV_STEP(4); PV_STEP(5); PV_STEP(6);
;   asm volatile("s_waitcnt lgkmcnt(0)" ::: "memory"); SBAR(); pv_mma(o[7], fc, pa0, pa1, pa2, pa3);
; }
; __device__ __forceinline__ void attn_body256(const bf16_t* __restrict__ Qb, const bf16_t* __restrict__ Kh, const bf16_t* __restrict__ Vh,
;                                              bf16_t* Ob, int seq, unsigned char* lds, float lam, int MODE, bf16_t* Ab, const float* wsub) {
;     ...
;     pv_all(o, vb0 + b * A2_VBUF, pa0, pa1, pa2, pa3);
;     asm volatile("s_waitcnt vmcnt(0)" ::: "memory"); __syncthreads();
	v_mfma_f32_16x16x32_bf16 v[114:117], v[194:197], v[130:133], v[114:117]
	v_mfma_f32_16x16x32_bf16 v[118:121], v[194:197], v[134:137], v[118:121]
	v_mfma_f32_16x16x32_bf16 v[114:117], v[198:201], v[138:141], v[114:117]
	v_mfma_f32_16x16x32_bf16 v[118:121], v[198:201], v[142:145], v[118:121]
	ds_read_b64_tr_b16 v[194:195], v244 offset:1056
	ds_read_b64_tr_b16 v[196:197], v244 offset:5152
	ds_read_b64_tr_b16 v[198:199], v244 offset:9248
	ds_read_b64_tr_b16 v[200:201], v244 offset:13344
	s_waitcnt lgkmcnt(8)
	v_mfma_f32_16x16x32_bf16 v[122:125], v[146:149], v[130:133], v[122:125]
	v_mfma_f32_16x16x32_bf16 v[126:129], v[146:149], v[134:137], v[126:129]
	v_mfma_f32_16x16x32_bf16 v[122:125], v[150:153], v[138:141], v[122:125]
	v_mfma_f32_16x16x32_bf16 v[126:129], v[150:153], v[142:145], v[126:129]
	ds_read_b64_tr_b16 v[146:147], v244 offset:1536
	ds_read_b64_tr_b16 v[148:149], v244 offset:5632
	ds_read_b64_tr_b16 v[150:151], v244 offset:9728
	ds_read_b64_tr_b16 v[152:153], v244 offset:13824
	s_waitcnt lgkmcnt(8)
	v_mfma_f32_16x16x32_bf16 v[98:101], v[154:157], v[130:133], v[98:101]
	v_mfma_f32_16x16x32_bf16 v[102:105], v[154:157], v[134:137], v[102:105]
	v_mfma_f32_16x16x32_bf16 v[98:101], v[158:161], v[138:141], v[98:101]
	v_mfma_f32_16x16x32_bf16 v[102:105], v[158:161], v[142:145], v[102:105]
	ds_read_b64_tr_b16 v[154:155], v244 offset:1568
	ds_read_b64_tr_b16 v[156:157], v244 offset:5664
	ds_read_b64_tr_b16 v[158:159], v244 offset:9760
	ds_read_b64_tr_b16 v[160:161], v244 offset:13856
	s_waitcnt lgkmcnt(8)
	v_mfma_f32_16x16x32_bf16 v[106:109], v[194:197], v[130:133], v[106:109]
	v_mfma_f32_16x16x32_bf16 v[110:113], v[194:197], v[134:137], v[110:113]
	v_mfma_f32_16x16x32_bf16 v[106:109], v[198:201], v[138:141], v[106:109]
	v_mfma_f32_16x16x32_bf16 v[110:113], v[198:201], v[142:145], v[110:113]
	ds_read_b64_tr_b16 v[194:195], v244 offset:16384
	ds_read_b64_tr_b16 v[196:197], v244 offset:20480
	ds_read_b64_tr_b16 v[198:199], v244 offset:24576
	ds_read_b64_tr_b16 v[200:201], v244 offset:28672
	s_waitcnt lgkmcnt(8)
	v_mfma_f32_16x16x32_bf16 v[82:85], v[146:149], v[130:133], v[82:85]
	v_mfma_f32_16x16x32_bf16 v[86:89], v[146:149], v[134:137], v[86:89]
	v_mfma_f32_16x16x32_bf16 v[82:85], v[150:153], v[138:141], v[82:85]
	v_mfma_f32_16x16x32_bf16 v[86:89], v[150:153], v[142:145], v[86:89]
	ds_read_b64_tr_b16 v[146:147], v244 offset:16416
	ds_read_b64_tr_b16 v[148:149], v244 offset:20512
	ds_read_b64_tr_b16 v[150:151], v244 offset:24608
	ds_read_b64_tr_b16 v[152:153], v244 offset:28704
	s_waitcnt lgkmcnt(8)
	v_mfma_f32_16x16x32_bf16 v[90:93], v[154:157], v[130:133], v[90:93]
	v_mfma_f32_16x16x32_bf16 v[94:97], v[154:157], v[134:137], v[94:97]
	v_mfma_f32_16x16x32_bf16 v[90:93], v[158:161], v[138:141], v[90:93]
	v_mfma_f32_16x16x32_bf16 v[94:97], v[158:161], v[142:145], v[94:97]
	ds_read_b64_tr_b16 v[154:155], v244 offset:16896
	ds_read_b64_tr_b16 v[156:157], v244 offset:20992
	ds_read_b64_tr_b16 v[158:159], v244 offset:25088
	ds_read_b64_tr_b16 v[160:161], v244 offset:29184
	s_waitcnt lgkmcnt(8)
	v_mfma_f32_16x16x32_bf16 v[66:69], v[194:197], v[130:133], v[66:69]
	v_mfma_f32_16x16x32_bf16 v[70:73], v[194:197], v[134:137], v[70:73]
	v_mfma_f32_16x16x32_bf16 v[66:69], v[198:201], v[138:141], v[66:69]
	v_mfma_f32_16x16x32_bf16 v[70:73], v[198:201], v[142:145], v[70:73]
	ds_read_b64_tr_b16 v[194:195], v244 offset:16928
	ds_read_b64_tr_b16 v[196:197], v244 offset:21024
	ds_read_b64_tr_b16 v[198:199], v244 offset:25120
	ds_read_b64_tr_b16 v[200:201], v244 offset:29216
	s_waitcnt lgkmcnt(8)
	v_mfma_f32_16x16x32_bf16 v[74:77], v[146:149], v[130:133], v[74:77]
	v_mfma_f32_16x16x32_bf16 v[78:81], v[146:149], v[134:137], v[78:81]
	v_mfma_f32_16x16x32_bf16 v[74:77], v[150:153], v[138:141], v[74:77]
	v_mfma_f32_16x16x32_bf16 v[78:81], v[150:153], v[142:145], v[78:81]
	ds_read_b64_tr_b16 v[146:147], v244 offset:17408
	ds_read_b64_tr_b16 v[148:149], v244 offset:21504
	ds_read_b64_tr_b16 v[150:151], v244 offset:25600
	ds_read_b64_tr_b16 v[152:153], v244 offset:29696
	s_waitcnt lgkmcnt(8)
	v_mfma_f32_16x16x32_bf16 v[50:53], v[154:157], v[130:133], v[50:53]
	v_mfma_f32_16x16x32_bf16 v[54:57], v[154:157], v[134:137], v[54:57]
	v_mfma_f32_16x16x32_bf16 v[50:53], v[158:161], v[138:141], v[50:53]
	v_mfma_f32_16x16x32_bf16 v[54:57], v[158:161], v[142:145], v[54:57]
	ds_read_b64_tr_b16 v[154:155], v244 offset:17440
	ds_read_b64_tr_b16 v[156:157], v244 offset:21536
	ds_read_b64_tr_b16 v[158:159], v244 offset:25632
	ds_read_b64_tr_b16 v[160:161], v244 offset:29728
	s_waitcnt lgkmcnt(8)
	v_mfma_f32_16x16x32_bf16 v[58:61], v[194:197], v[130:133], v[58:61]
	v_mfma_f32_16x16x32_bf16 v[62:65], v[194:197], v[134:137], v[62:65]
	v_mfma_f32_16x16x32_bf16 v[58:61], v[198:201], v[138:141], v[58:61]
	v_mfma_f32_16x16x32_bf16 v[62:65], v[198:201], v[142:145], v[62:65]
	ds_read_b64_tr_b16 v[194:195], v244 offset:17920
	ds_read_b64_tr_b16 v[196:197], v244 offset:22016
	ds_read_b64_tr_b16 v[198:199], v244 offset:26112
	ds_read_b64_tr_b16 v[200:201], v244 offset:30208
	s_waitcnt lgkmcnt(8)
	v_mfma_f32_16x16x32_bf16 v[34:37], v[146:149], v[130:133], v[34:37]
	v_mfma_f32_16x16x32_bf16 v[38:41], v[146:149], v[134:137], v[38:41]
	v_mfma_f32_16x16x32_bf16 v[34:37], v[150:153], v[138:141], v[34:37]
	v_mfma_f32_16x16x32_bf16 v[38:41], v[150:153], v[142:145], v[38:41]
	ds_read_b64_tr_b16 v[146:147], v244 offset:17952
	ds_read_b64_tr_b16 v[148:149], v244 offset:22048
	ds_read_b64_tr_b16 v[150:151], v244 offset:26144
	ds_read_b64_tr_b16 v[152:153], v244 offset:30240
	s_waitcnt lgkmcnt(8)
	v_mfma_f32_16x16x32_bf16 v[42:45], v[154:157], v[130:133], v[42:45]
	v_mfma_f32_16x16x32_bf16 v[46:49], v[154:157], v[134:137], v[46:49]
	v_mfma_f32_16x16x32_bf16 v[42:45], v[158:161], v[138:141], v[42:45]
	v_mfma_f32_16x16x32_bf16 v[46:49], v[158:161], v[142:145], v[46:49]
	s_waitcnt lgkmcnt(4)
	v_mfma_f32_16x16x32_bf16 v[18:21], v[194:197], v[130:133], v[18:21]
	v_mfma_f32_16x16x32_bf16 v[22:25], v[194:197], v[134:137], v[22:25]
	v_mfma_f32_16x16x32_bf16 v[18:21], v[198:201], v[138:141], v[18:21]
	v_mfma_f32_16x16x32_bf16 v[22:25], v[198:201], v[142:145], v[22:25]
	s_waitcnt lgkmcnt(0)
	v_mfma_f32_16x16x32_bf16 v[26:29], v[146:149], v[130:133], v[26:29]
	v_mfma_f32_16x16x32_bf16 v[30:33], v[146:149], v[134:137], v[30:33]
	v_mfma_f32_16x16x32_bf16 v[26:29], v[150:153], v[138:141], v[26:29]
	v_mfma_f32_16x16x32_bf16 v[30:33], v[150:153], v[142:145], v[30:33]
	s_waitcnt vmcnt(0)
	s_barrier
; __device__ __forceinline__ void attn_body256(const bf16_t* __restrict__ Qb, const bf16_t* __restrict__ Kh, const bf16_t* __restrict__ Vh,
;                                              bf16_t* Ob, int seq, unsigned char* lds, float lam, int MODE, bf16_t* Ab, const float* wsub) {
;     ...
;     asm volatile("s_waitcnt vmcnt(0)" ::: "memory"); __syncthreads();
;     if (j + 2 < NT) A2_DMA(j + 2, b);
;   }
;   if (hi == 0) li_l[r32] = l_reg; asm volatile("s_waitcnt lgkmcnt(0)" ::: "memory");
	s_cmp_ge_u32 s13, s19
	s_cbranch_scc1 .Lat_nodma
	s_lshl_b32 s8, s25, 15
	s_add_i32 s9, s22, s24
	v_lshl_add_u64 v[194:195], v[220:221], 0, s[14:15]
	s_mov_b32 m0, s9
	s_add_i32 s8, s21, s8
	global_load_lds_dwordx4 v[194:195], off
	v_lshl_add_u64 v[194:195], v[224:225], 0, s[14:15]
	s_add_i32 s16, s8, 0x4000
	v_lshl_add_u64 v[196:197], v[194:195], 0, s[54:55]
	s_mov_b32 m0, s8
	v_lshl_add_u64 v[194:195], v[194:195], 0, s[4:5]
	global_load_lds_dwordx4 v[196:197], off
	s_mov_b32 m0, s16
	s_nop 0
	global_load_lds_dwordx4 v[194:195], off
	v_lshl_add_u64 v[194:195], v[222:223], 0, s[14:15]
	s_add_i32 m0, s9, 0x2000
	s_nop 0
	global_load_lds_dwordx4 v[194:195], off
	v_lshl_add_u64 v[194:195], v[226:227], 0, s[14:15]
	v_lshl_add_u64 v[196:197], v[194:195], 0, s[54:55]
	s_add_i32 m0, s8, 0x2000
	v_lshl_add_u64 v[194:195], v[194:195], 0, s[4:5]
	global_load_lds_dwordx4 v[196:197], off
	s_add_i32 m0, s8, 0x6000
	s_nop 0
	global_load_lds_dwordx4 v[194:195], off
.Lat_nodma:
	s_add_u32 s14, s14, 0x40000
	s_addc_u32 s15, s15, 0
	s_add_i32 s13, s13, 1
	s_cmp_eq_u32 s23, s14
	s_cbranch_scc0 .Lat_top
	v_mov_b32_e32 v196, v250
	v_mov_b32_e32 v197, v234
	s_nop 1
	v_permlane32_swap_b32_e32 v250, v196
	v_permlane32_swap_b32_e32 v234, v197
	v_add_f32_e32 v250, v250, v196
	v_add_f32_e32 v234, v234, v197
	v_mov_b32_e32 v196, v250
	v_mov_b32_e32 v197, v234
	s_nop 1
	v_permlane16_swap_b32_e32 v250, v196
	v_permlane16_swap_b32_e32 v234, v197
	v_add_f32_e32 v250, v250, v196
	v_add_f32_e32 v234, v234, v197
	v_and_b32_e32 v194, 15, v231
	v_lshl_add_u32 v194, v194, 2, s20
	s_mov_b64 exec, 0xffff
	ds_write_b32 v194, v250
	ds_write_b32 v194, v234 offset:64
	s_mov_b64 exec, -1
	s_lshr_b32 s16, s21, 10
	s_mul_i32 s16, s16, 0x2200
	v_and_b32_e32 v194, 15, v231
	v_bfe_u32 v195, v231, 4, 2
	v_mul_u32_u24_e32 v194, 0x110, v194
	v_lshl_add_u32 v194, v195, 4, v194
	v_add_u32_e32 v194, s16, v194
	v_and_b32_e32 v195, 31, v231
	v_bfe_u32 v196, v231, 5, 1
	v_mul_u32_u24_e32 v196, 0x440, v196
	v_lshl_add_u32 v195, v195, 2, v196
	v_add_u32_e32 v195, s16, v195
	ds_write_b128 v194, v[2:5]
	ds_write_b128 v194, v[6:9] offset:4352
	ds_write_b128 v194, v[10:13] offset:64
	ds_write_b128 v194, v[14:17] offset:4416
	ds_write_b128 v194, v[114:117] offset:128
	ds_write_b128 v194, v[118:121] offset:4480
	ds_write_b128 v194, v[122:125] offset:192
	ds_write_b128 v194, v[126:129] offset:4544
	ds_read_b32 v2, v195
	ds_read_b32 v3, v195 offset:272
	ds_read_b32 v4, v195 offset:544
	ds_read_b32 v5, v195 offset:816
	ds_read_b32 v6, v195 offset:2176
	ds_read_b32 v7, v195 offset:2448
	ds_read_b32 v8, v195 offset:2720
	ds_read_b32 v9, v195 offset:2992
	ds_read_b32 v10, v195 offset:4352
	ds_read_b32 v11, v195 offset:4624
	ds_read_b32 v12, v195 offset:4896
	ds_read_b32 v13, v195 offset:5168
	ds_read_b32 v14, v195 offset:6528
	ds_read_b32 v15, v195 offset:6800
	ds_read_b32 v16, v195 offset:7072
	ds_read_b32 v17, v195 offset:7344
	ds_read_b32 v114, v195 offset:128
	ds_read_b32 v115, v195 offset:400
	ds_read_b32 v116, v195 offset:672
	ds_read_b32 v117, v195 offset:944
	ds_read_b32 v118, v195 offset:2304
	ds_read_b32 v119, v195 offset:2576
	ds_read_b32 v120, v195 offset:2848
	ds_read_b32 v121, v195 offset:3120
	ds_read_b32 v122, v195 offset:4480
	ds_read_b32 v123, v195 offset:4752
	ds_read_b32 v124, v195 offset:5024
	ds_read_b32 v125, v195 offset:5296
	ds_read_b32 v126, v195 offset:6656
	ds_read_b32 v127, v195 offset:6928
	ds_read_b32 v128, v195 offset:7200
	ds_read_b32 v129, v195 offset:7472
	s_waitcnt lgkmcnt(0)
	ds_write_b128 v194, v[98:101]
	ds_write_b128 v194, v[102:105] offset:4352
	ds_write_b128 v194, v[106:109] offset:64
	ds_write_b128 v194, v[110:113] offset:4416
	ds_write_b128 v194, v[82:85] offset:128
	ds_write_b128 v194, v[86:89] offset:4480
	ds_write_b128 v194, v[90:93] offset:192
	ds_write_b128 v194, v[94:97] offset:4544
	ds_read_b32 v98, v195
	ds_read_b32 v99, v195 offset:272
	ds_read_b32 v100, v195 offset:544
	ds_read_b32 v101, v195 offset:816
	ds_read_b32 v102, v195 offset:2176
	ds_read_b32 v103, v195 offset:2448
	ds_read_b32 v104, v195 offset:2720
	ds_read_b32 v105, v195 offset:2992
	ds_read_b32 v106, v195 offset:4352
	ds_read_b32 v107, v195 offset:4624
	ds_read_b32 v108, v195 offset:4896
	ds_read_b32 v109, v195 offset:5168
	ds_read_b32 v110, v195 offset:6528
	ds_read_b32 v111, v195 offset:6800
	ds_read_b32 v112, v195 offset:7072
	ds_read_b32 v113, v195 offset:7344
	ds_read_b32 v82, v195 offset:128
	ds_read_b32 v83, v195 offset:400
	ds_read_b32 v84, v195 offset:672
	ds_read_b32 v85, v195 offset:944
	ds_read_b32 v86, v195 offset:2304
	ds_read_b32 v87, v195 offset:2576
	ds_read_b32 v88, v195 offset:2848
	ds_read_b32 v89, v195 offset:3120
	ds_read_b32 v90, v195 offset:4480
	ds_read_b32 v91, v195 offset:4752
	ds_read_b32 v92, v195 offset:5024
	ds_read_b32 v93, v195 offset:5296
	ds_read_b32 v94, v195 offset:6656
	ds_read_b32 v95, v195 offset:6928
	ds_read_b32 v96, v195 offset:7200
	ds_read_b32 v97, v195 offset:7472
	s_waitcnt lgkmcnt(0)
; __device__ __forceinline__ bf16_t f2bf(float x) { return (bf16_t)(cvt_pk_bf16(x, x) & 0xffffu); }
; __device__ __forceinline__ int crow(int r, int hi) { return (r & 3) + 8 * (r >> 2) + 4 * hi; }
; __device__ __forceinline__ int crow(int r, int hi) { return (r & 3) + 8 * (r >> 2) + 4 * hi; }
; __device__ __forceinline__ void attn_body256(const bf16_t* __restrict__ Qb, const bf16_t* __restrict__ Kh, const bf16_t* __restrict__ Vh,
;                                              bf16_t* Ob, int seq, unsigned char* lds, float lam, int MODE, bf16_t* Ab, const float* wsub) {
;     ...
;   if (hi == 0) li_l[r32] = l_reg; asm volatile("s_waitcnt lgkmcnt(0)" ::: "memory");
;   float rli[16];
; #pragma unroll
;   for (int r = 0; r < 16; ++r) rli[r] = __builtin_amdgcn_rcpf(li_l[crow(r, hi)]);
;   bf16_t* Ow = Ob + (long)(wid * QBLK) * LDO;
;   if (MODE == 0) {
; #pragma unroll
;     for (int r = 0; r < 16; ++r) { const int orow = crow(r, hi);
; #pragma unroll
;       for (int d0 = 0; d0 < 8; ++d0) Ow[(long)orow * LDO + d0 * 32 + r32] = f2bf(o[d0][r] * rli[r]); }
;   } else {
;     bf16_t* Aw = Ab + (long)(wid * QBLK) * LDO;
;     float wv[8];
; #pragma unroll
;     for (int d0 = 0; d0 < 8; ++d0) wv[d0] = wsub[d0 * 32 + r32] * (1.f - LAMBDA_INIT);
	ds_write_b128 v194, v[66:69]
	ds_write_b128 v194, v[70:73] offset:4352
	ds_write_b128 v194, v[74:77] offset:64
	ds_write_b128 v194, v[78:81] offset:4416
	ds_write_b128 v194, v[50:53] offset:128
	ds_write_b128 v194, v[54:57] offset:4480
	ds_write_b128 v194, v[58:61] offset:192
	ds_write_b128 v194, v[62:65] offset:4544
	ds_read_b32 v66, v195
	ds_read_b32 v67, v195 offset:272
	ds_read_b32 v68, v195 offset:544
	ds_read_b32 v69, v195 offset:816
	ds_read_b32 v70, v195 offset:2176
	ds_read_b32 v71, v195 offset:2448
	ds_read_b32 v72, v195 offset:2720
	ds_read_b32 v73, v195 offset:2992
	ds_read_b32 v74, v195 offset:4352
	ds_read_b32 v75, v195 offset:4624
	ds_read_b32 v76, v195 offset:4896
	ds_read_b32 v77, v195 offset:5168
	ds_read_b32 v78, v195 offset:6528
	ds_read_b32 v79, v195 offset:6800
	ds_read_b32 v80, v195 offset:7072
	ds_read_b32 v81, v195 offset:7344
	ds_read_b32 v50, v195 offset:128
	ds_read_b32 v51, v195 offset:400
	ds_read_b32 v52, v195 offset:672
	ds_read_b32 v53, v195 offset:944
	ds_read_b32 v54, v195 offset:2304
	ds_read_b32 v55, v195 offset:2576
	ds_read_b32 v56, v195 offset:2848
	ds_read_b32 v57, v195 offset:3120
	ds_read_b32 v58, v195 offset:4480
	ds_read_b32 v59, v195 offset:4752
	ds_read_b32 v60, v195 offset:5024
	ds_read_b32 v61, v195 offset:5296
	ds_read_b32 v62, v195 offset:6656
	ds_read_b32 v63, v195 offset:6928
	ds_read_b32 v64, v195 offset:7200
	ds_read_b32 v65, v195 offset:7472
	s_waitcnt lgkmcnt(0)
	ds_write_b128 v194, v[34:37]
	ds_write_b128 v194, v[38:41] offset:4352
	ds_write_b128 v194, v[42:45] offset:64
	ds_write_b128 v194, v[46:49] offset:4416
	ds_write_b128 v194, v[18:21] offset:128
	ds_write_b128 v194, v[22:25] offset:4480
	ds_write_b128 v194, v[26:29] offset:192
	ds_write_b128 v194, v[30:33] offset:4544
	ds_read_b32 v34, v195
	ds_read_b32 v35, v195 offset:272
	ds_read_b32 v36, v195 offset:544
	ds_read_b32 v37, v195 offset:816
	ds_read_b32 v38, v195 offset:2176
	ds_read_b32 v39, v195 offset:2448
	ds_read_b32 v40, v195 offset:2720
	ds_read_b32 v41, v195 offset:2992
	ds_read_b32 v42, v195 offset:4352
	ds_read_b32 v43, v195 offset:4624
	ds_read_b32 v44, v195 offset:4896
	ds_read_b32 v45, v195 offset:5168
	ds_read_b32 v46, v195 offset:6528
	ds_read_b32 v47, v195 offset:6800
	ds_read_b32 v48, v195 offset:7072
	ds_read_b32 v49, v195 offset:7344
	ds_read_b32 v18, v195 offset:128
	ds_read_b32 v19, v195 offset:400
	ds_read_b32 v20, v195 offset:672
	ds_read_b32 v21, v195 offset:944
	ds_read_b32 v22, v195 offset:2304
	ds_read_b32 v23, v195 offset:2576
	ds_read_b32 v24, v195 offset:2848
	ds_read_b32 v25, v195 offset:3120
	ds_read_b32 v26, v195 offset:4480
	ds_read_b32 v27, v195 offset:4752
	ds_read_b32 v28, v195 offset:5024
	ds_read_b32 v29, v195 offset:5296
	ds_read_b32 v30, v195 offset:6656
	ds_read_b32 v31, v195 offset:6928
	ds_read_b32 v32, v195 offset:7200
	ds_read_b32 v33, v195 offset:7472
	s_waitcnt lgkmcnt(0)
	s_branch .Lat_epi
.Lat_epi:
	v_add_u32_e32 v0, s20, v0
	ds_read_b128 v[130:133], v0
	ds_read_b128 v[134:137], v0 offset:32
	s_lshl_b64 s[8:9], s[10:11], 1
	s_add_u32 s6, s92, s8
	ds_read_b128 v[146:149], v0 offset:96
	s_waitcnt lgkmcnt(0)
	v_rcp_f32_e32 v144, v130
	v_rcp_f32_e32 v145, v131
	v_rcp_f32_e32 v142, v132
	v_rcp_f32_e32 v143, v133
	ds_read_b128 v[130:133], v0 offset:64
	s_addc_u32 s7, s93, s9
	s_add_u32 s10, s6, s0
	s_addc_u32 s11, s7, s1
	s_ashr_i32 s13, s12, 31
	v_rcp_f32_e32 v140, v134
	v_rcp_f32_e32 v141, v135
	v_rcp_f32_e32 v138, v136
	v_rcp_f32_e32 v139, v137
	s_waitcnt lgkmcnt(0)
	v_rcp_f32_e32 v136, v130
	v_rcp_f32_e32 v137, v131
	v_rcp_f32_e32 v134, v132
	v_rcp_f32_e32 v135, v133
	v_rcp_f32_e32 v132, v146
	v_rcp_f32_e32 v133, v147
	v_rcp_f32_e32 v130, v148
	v_rcp_f32_e32 v131, v149
	s_lshl_b64 s[6:7], s[12:13], 12
	s_add_u32 s6, s10, s6
	s_addc_u32 s7, s11, s7
	s_cmp_lg_u32 s2, 0
	s_mov_b64 s[10:11], -1
	v_lshlrev_b32_e32 v146, 14, v229
	v_lshlrev_b32_e32 v0, 1, v228
	s_cbranch_scc0 .LBB0_682
	s_lshl_b64 s[10:11], s[12:13], 11
	s_add_u32 s2, s76, s8
	s_addc_u32 s8, s77, s9
	v_readlane_b32 s72, v252, 22
	v_readlane_b32 s76, v252, 26
	v_readlane_b32 s77, v252, 27
	v_readlane_b32 s78, v252, 28
	v_readlane_b32 s79, v252, 29
	v_readlane_b32 s80, v252, 30
	v_readlane_b32 s81, v252, 31
	v_readlane_b32 s82, v252, 32
	v_readlane_b32 s83, v252, 33
	v_readlane_b32 s84, v252, 34
	v_readlane_b32 s85, v252, 35
	s_mov_b64 s[20:21], s[76:77]
	v_lshlrev_b32_e32 v147, 2, v228
	s_mov_b64 s[28:29], s[84:85]
	global_load_dword v148, v147, s[28:29]
	v_lshl_add_u64 v[150:151], s[6:7], 0, v[0:1]
	v_mov_b32_e32 v160, v66
	v_mov_b32_e32 v161, v50
	v_pk_mul_f32 v[160:161], v[160:161], v[144:145] op_sel_hi:[1,0]
	s_add_u32 s2, s2, s0
	s_addc_u32 s8, s8, s1
	s_lshl_b64 s[0:1], s[10:11], 1
	s_add_u32 s0, s2, s0
	s_addc_u32 s1, s8, s1
	v_or_b32_e32 v162, 0x1000, v146
	v_mov_b32_e32 v163, v1
	v_lshl_add_u64 v[184:185], v[150:151], 0, v[162:163]
	v_mov_b32_e32 v154, v98
	v_mov_b32_e32 v155, v82
	v_pk_mul_f32 v[154:155], v[154:155], v[144:145] op_sel_hi:[1,0]
	v_mov_b32_e32 v166, v99
	v_mov_b32_e32 v167, v83
	v_mov_b32_e32 v178, v145
	v_mov_b32_e32 v182, v67
	v_mov_b32_e32 v183, v51
	v_mov_b32_e32 v186, v35
	v_mov_b32_e32 v187, v19
	s_mov_b32 s2, 0x3b800000
	v_mov_b32_e32 v200, v37
	v_mov_b32_e32 v201, v21
	v_readlane_b32 s73, v252, 23
	v_readlane_b32 s74, v252, 24
	v_readlane_b32 s75, v252, 25
	v_readlane_b32 s72, v254, 62
	v_readlane_b32 s74, v254, 53
	s_mov_b64 s[22:23], s[78:79]
	s_mov_b64 s[24:25], s[80:81]
	s_mov_b64 s[26:27], s[82:83]
	v_readlane_b32 s80, v255, 2
	v_readlane_b32 s78, v255, 0
	v_readlane_b32 s84, v254, 60
	v_readlane_b32 s82, v254, 58
	v_readlane_b32 s76, v254, 55
	v_readlane_b32 s86, v252, 36
	v_readlane_b32 s87, v252, 37
	v_readlane_b32 s73, v254, 63
	v_readlane_b32 s75, v254, 54
	v_readlane_b32 s81, v255, 3
	v_readlane_b32 s79, v255, 1
	v_readlane_b32 s85, v254, 61
	v_readlane_b32 s83, v254, 59
	v_readlane_b32 s77, v254, 56
	s_mov_b64 s[10:11], 0
	s_waitcnt vmcnt(0)
; __device__ __forceinline__ bf16_t f2bf(float x) { return (bf16_t)(cvt_pk_bf16(x, x) & 0xffffu); }
; __device__ __forceinline__ float bf2f(bf16_t b) { return __uint_as_float(((unsigned)b) << 16); }
; __device__ __forceinline__ int crow(int r, int hi) { return (r & 3) + 8 * (r >> 2) + 4 * hi; }
; __device__ __forceinline__ int crow(int r, int hi) { return (r & 3) + 8 * (r >> 2) + 4 * hi; }
; __device__ __forceinline__ void attn_body256(const bf16_t* __restrict__ Qb, const bf16_t* __restrict__ Kh, const bf16_t* __restrict__ Vh,
;                                              bf16_t* Ob, int seq, unsigned char* lds, float lam, int MODE, bf16_t* Ab, const float* wsub) {
;     ...
;     bf16_t* Aw = Ab + (long)(wid * QBLK) * LDO;
;     float wv[8];
; #pragma unroll
;     for (int d0 = 0; d0 < 8; ++d0) wv[d0] = wsub[d0 * 32 + r32] * (1.f - LAMBDA_INIT);
; #pragma unroll
;     for (int r = 0; r < 16; ++r) { const int orow = crow(r, hi); float ss = 0.f;
; #pragma unroll
;       for (int d0 = 0; d0 < 8; ++d0) { const float v = bf2f(Ow[(long)orow * LDO + d0 * 32 + r32]) - lam * (o[d0][r] * rli[r]); o[d0][r] = v; ss += v * v; }
;       ss += __shfl_xor(ss, 1, 64); ss += __shfl_xor(ss, 2, 64); ss += __shfl_xor(ss, 4, 64); ss += __shfl_xor(ss, 8, 64); ss += __shfl_xor(ss, 16, 64);
;       const float rstd = rsqrtf(ss * (1.f / 256.f) + NORM_EPS);
; #pragma unroll
;       for (int d0 = 0; d0 < 8; ++d0) Aw[(long)orow * LDO + d0 * 32 + r32] = f2bf(o[d0][r] * rstd * wv[d0]); }
	v_mul_f32_e32 v179, 0x3f24fd5c, v148
	global_load_dword v148, v147, s[28:29] offset:128
	v_pk_mul_f32 v[166:167], v[166:167], v[178:179] op_sel_hi:[1,0]
	v_pk_mul_f32 v[182:183], v[182:183], v[178:179] op_sel_hi:[1,0]
	v_pk_mul_f32 v[186:187], v[186:187], v[178:179] op_sel_hi:[1,0]
	v_mov_b32_e32 v178, v143
	v_pk_mul_f32 v[200:201], v[200:201], v[178:179] op_sel_hi:[1,0]
	s_waitcnt vmcnt(0)
	v_mul_f32_e32 v188, 0x3f24fd5c, v148
	global_load_dword v148, v147, s[28:29] offset:256
	s_waitcnt vmcnt(0)
	v_mul_f32_e32 v189, 0x3f24fd5c, v148
	global_load_dword v148, v147, s[28:29] offset:384
	s_waitcnt vmcnt(0)
	v_mul_f32_e32 v190, 0x3f24fd5c, v148
	global_load_dword v148, v147, s[28:29] offset:512
	s_waitcnt vmcnt(0)
	v_mul_f32_e32 v191, 0x3f24fd5c, v148
	global_load_dword v148, v147, s[28:29] offset:640
	s_waitcnt vmcnt(0)
	v_mul_f32_e32 v192, 0x3f24fd5c, v148
	global_load_dword v148, v147, s[28:29] offset:768
	s_waitcnt vmcnt(0)
	v_mul_f32_e32 v193, 0x3f24fd5c, v148
	global_load_dword v147, v147, s[28:29] offset:896
	v_and_b32_e32 v148, 64, v235
	v_add_u32_e32 v148, 64, v148
	v_readlane_b32 s28, v255, 4
	v_readlane_b32 s29, v255, 5
	s_waitcnt vmcnt(0)
	v_mul_f32_e32 v194, 0x3f24fd5c, v147
	v_xor_b32_e32 v147, 1, v235
	v_cmp_lt_i32_e32 vcc, v147, v148
	s_nop 1
	v_cndmask_b32_e32 v147, v235, v147, vcc
	v_lshlrev_b32_e32 v199, 2, v147
	v_xor_b32_e32 v147, 2, v235
	v_cmp_lt_i32_e32 vcc, v147, v148
	s_nop 1
	v_cndmask_b32_e32 v147, v235, v147, vcc
	v_lshlrev_b32_e32 v198, 2, v147
	v_xor_b32_e32 v147, 4, v235
	v_cmp_lt_i32_e32 vcc, v147, v148
	s_nop 1
	v_cndmask_b32_e32 v147, v235, v147, vcc
	v_lshlrev_b32_e32 v197, 2, v147
	v_xor_b32_e32 v147, 8, v235
	v_cmp_lt_i32_e32 vcc, v147, v148
	s_nop 1
	v_cndmask_b32_e32 v147, v235, v147, vcc
	v_lshlrev_b32_e32 v196, 2, v147
	v_xor_b32_e32 v147, 16, v235
	v_cmp_lt_i32_e32 vcc, v147, v148
	v_lshl_add_u64 v[148:149], s[0:1], 0, v[0:1]
	s_mov_b32 s0, 0x3727c5ac
	v_cndmask_b32_e32 v147, v235, v147, vcc
	v_lshlrev_b32_e32 v195, 2, v147
	v_mov_b32_e32 v147, v1
	v_lshl_add_u64 v[158:159], v[150:151], 0, v[146:147]
	global_load_ushort v168, v[158:159], off
	global_load_ushort v174, v[158:159], off offset:64
	global_load_ushort v152, v[158:159], off offset:128
	global_load_ushort v153, v[158:159], off offset:192
	global_load_ushort v156, v[158:159], off offset:256
	global_load_ushort v157, v[158:159], off offset:320
	s_waitcnt vmcnt(3)
	v_lshlrev_b32_e32 v152, 16, v152
	s_waitcnt vmcnt(1)
	v_lshlrev_b32_e32 v156, 16, v156
	s_waitcnt vmcnt(0)
	v_lshlrev_b32_e32 v157, 16, v157
	v_pk_fma_f32 v[156:157], v[218:219], v[160:161], v[156:157] neg_lo:[1,0,0] neg_hi:[1,0,0]
	global_load_ushort v160, v[158:159], off offset:384
	s_nop 0
	global_load_ushort v158, v[158:159], off offset:448
	v_mov_b32_e32 v161, v18
	v_lshlrev_b32_e32 v153, 16, v153
	v_pk_fma_f32 v[154:155], v[218:219], v[154:155], v[152:153] neg_lo:[1,0,0] neg_hi:[1,0,0]
	v_pk_mul_f32 v[170:171], v[156:157], v[156:157]
	v_pk_mul_f32 v[152:153], v[154:155], v[154:155]
	s_waitcnt vmcnt(0)
	v_lshlrev_b32_e32 v159, 16, v158
	v_lshlrev_b32_e32 v158, 16, v160
	v_mov_b32_e32 v160, v34
	v_pk_mul_f32 v[160:161], v[160:161], v[144:145] op_sel_hi:[1,0]
	v_mov_b32_e32 v180, v152
	v_pk_fma_f32 v[160:161], v[218:219], v[160:161], v[158:159] neg_lo:[1,0,0] neg_hi:[1,0,0]
	v_lshl_add_u64 v[158:159], v[148:149], 0, v[146:147]
	global_load_ushort v147, v[184:185], off
	global_load_ushort v175, v[184:185], off offset:64
	global_load_ushort v164, v[184:185], off offset:128
	global_load_ushort v165, v[184:185], off offset:192
	v_pk_mul_f32 v[172:173], v[160:161], v[160:161]
	s_waitcnt vmcnt(1)
	v_lshlrev_b32_e32 v164, 16, v164
	s_waitcnt vmcnt(0)
	v_lshlrev_b32_e32 v165, 16, v165
	v_pk_fma_f32 v[164:165], v[218:219], v[166:167], v[164:165] neg_lo:[1,0,0] neg_hi:[1,0,0]
	v_lshlrev_b32_e32 v167, 16, v147
	global_load_ushort v147, v[184:185], off offset:256
	global_load_ushort v152, v[184:185], off offset:320
	v_lshlrev_b32_e32 v166, 16, v168
	v_pk_mul_f32 v[168:169], v[2:3], v[144:145]
	v_pk_mul_f32 v[176:177], v[164:165], v[164:165]
	v_pk_fma_f32 v[166:167], v[218:219], v[168:169], v[166:167] neg_lo:[1,0,0] neg_hi:[1,0,0]
	v_lshlrev_b32_e32 v169, 16, v175
	v_lshlrev_b32_e32 v168, 16, v174
	v_pk_mul_f32 v[174:175], v[114:115], v[144:145]
	v_mov_b32_e32 v181, v176
	v_pk_fma_f32 v[168:169], v[218:219], v[174:175], v[168:169] neg_lo:[1,0,0] neg_hi:[1,0,0]
	s_nop 0
	v_pk_mul_f32 v[174:175], v[168:169], v[168:169]
	s_nop 0
	v_pk_fma_f32 v[174:175], v[166:167], v[166:167], v[174:175]
	s_nop 0
	v_pk_add_f32 v[180:181], v[174:175], v[180:181]
	s_waitcnt vmcnt(1)
	v_lshlrev_b32_e32 v174, 16, v147
	s_waitcnt vmcnt(0)
	v_lshlrev_b32_e32 v175, 16, v152
	global_load_ushort v147, v[184:185], off offset:384
	global_load_ushort v152, v[184:185], off offset:448
	v_pk_fma_f32 v[174:175], v[218:219], v[182:183], v[174:175] neg_lo:[1,0,0] neg_hi:[1,0,0]
	s_waitcnt vmcnt(1)
	v_lshlrev_b32_e32 v184, 16, v147
	v_pk_mul_f32 v[182:183], v[174:175], v[174:175]
	s_waitcnt vmcnt(0)
	v_lshlrev_b32_e32 v185, 16, v152
	v_mov_b32_e32 v152, v177
	v_pk_fma_f32 v[184:185], v[218:219], v[186:187], v[184:185] neg_lo:[1,0,0] neg_hi:[1,0,0]
	v_pk_add_f32 v[152:153], v[180:181], v[152:153] op_sel:[1,0] op_sel_hi:[0,1]
	v_mov_b32_e32 v176, v182
	v_mov_b32_e32 v177, v170
	v_pk_mul_f32 v[186:187], v[184:185], v[184:185]
	v_pk_add_f32 v[152:153], v[152:153], v[176:177]
	v_mov_b32_e32 v170, v183
	v_pk_add_f32 v[152:153], v[152:153], v[170:171]
	v_mov_b32_e32 v170, v186
	v_mov_b32_e32 v171, v172
	v_pk_add_f32 v[152:153], v[152:153], v[170:171]
	v_mov_b32_e32 v172, v187
	v_pk_add_f32 v[152:153], v[152:153], v[172:173]
	ds_bpermute_b32 v171, v199, v153
	ds_bpermute_b32 v170, v199, v152
	s_waitcnt lgkmcnt(0)
; __device__ __forceinline__ bf16_t f2bf(float x) { return (bf16_t)(cvt_pk_bf16(x, x) & 0xffffu); }
; __device__ __forceinline__ float bf2f(bf16_t b) { return __uint_as_float(((unsigned)b) << 16); }
; __device__ __forceinline__ int crow(int r, int hi) { return (r & 3) + 8 * (r >> 2) + 4 * hi; }
; __device__ __forceinline__ int crow(int r, int hi) { return (r & 3) + 8 * (r >> 2) + 4 * hi; }
; __device__ __forceinline__ void attn_body256(const bf16_t* __restrict__ Qb, const bf16_t* __restrict__ Kh, const bf16_t* __restrict__ Vh,
;                                              bf16_t* Ob, int seq, unsigned char* lds, float lam, int MODE, bf16_t* Ab, const float* wsub) {
;     ...
;     bf16_t* Aw = Ab + (long)(wid * QBLK) * LDO;
;     float wv[8];
; #pragma unroll
;     for (int d0 = 0; d0 < 8; ++d0) wv[d0] = wsub[d0 * 32 + r32] * (1.f - LAMBDA_INIT);
; #pragma unroll
;     for (int r = 0; r < 16; ++r) { const int orow = crow(r, hi); float ss = 0.f;
; #pragma unroll
;       for (int d0 = 0; d0 < 8; ++d0) { const float v = bf2f(Ow[(long)orow * LDO + d0 * 32 + r32]) - lam * (o[d0][r] * rli[r]); o[d0][r] = v; ss += v * v; }
;       ss += __shfl_xor(ss, 1, 64); ss += __shfl_xor(ss, 2, 64); ss += __shfl_xor(ss, 4, 64); ss += __shfl_xor(ss, 8, 64); ss += __shfl_xor(ss, 16, 64);
;       const float rstd = rsqrtf(ss * (1.f / 256.f) + NORM_EPS);
; #pragma unroll
;       for (int d0 = 0; d0 < 8; ++d0) Aw[(long)orow * LDO + d0 * 32 + r32] = f2bf(o[d0][r] * rstd * wv[d0]); }
	v_pk_add_f32 v[152:153], v[152:153], v[170:171]
	ds_bpermute_b32 v171, v198, v153
	ds_bpermute_b32 v170, v198, v152
	s_waitcnt lgkmcnt(0)
	v_pk_add_f32 v[152:153], v[152:153], v[170:171]
	ds_bpermute_b32 v171, v197, v153
	ds_bpermute_b32 v170, v197, v152
	s_waitcnt lgkmcnt(0)
	v_pk_add_f32 v[152:153], v[152:153], v[170:171]
	ds_bpermute_b32 v171, v196, v153
	ds_bpermute_b32 v170, v196, v152
	s_waitcnt lgkmcnt(0)
	v_pk_add_f32 v[152:153], v[152:153], v[170:171]
	ds_bpermute_b32 v171, v195, v153
	ds_bpermute_b32 v170, v195, v152
	s_waitcnt lgkmcnt(0)
	v_pk_add_f32 v[170:171], v[152:153], v[170:171]
	v_mov_b64_e32 v[152:153], s[0:1]
	v_pk_fma_f32 v[170:171], v[170:171], s[2:3], v[152:153] op_sel_hi:[1,0,0]
	s_nop 0
	v_mul_f32_e32 v147, 0x4b800000, v171
	v_cmp_gt_f32_e64 s[0:1], s58, v171
	v_cmp_gt_f32_e32 vcc, s58, v170
	s_nop 0
	v_cndmask_b32_e64 v147, v171, v147, s[0:1]
	v_rsq_f32_e32 v147, v147
	s_nop 0
	v_mul_f32_e32 v171, 0x45800000, v147
	v_cndmask_b32_e64 v147, v147, v171, s[0:1]
	v_mul_f32_e32 v154, v154, v147
	v_mul_f32_e32 v154, v189, v154
	v_cvt_pk_bf16_f32 v154, v154, s0
	global_store_short v[158:159], v154, off offset:128
	v_mul_f32_e32 v154, v155, v147
	v_mul_f32_e32 v154, v190, v154
	v_cvt_pk_bf16_f32 v154, v154, s0
	global_store_short v[158:159], v154, off offset:192
	v_mul_f32_e32 v154, v156, v147
	v_mul_f32_e32 v154, v191, v154
	v_cvt_pk_bf16_f32 v154, v154, s0
	v_mul_f32_e32 v166, v166, v147
	global_store_short v[158:159], v154, off offset:256
	v_mul_f32_e32 v154, v157, v147
	v_mul_f32_e32 v166, v179, v166
	v_mul_f32_e32 v154, v192, v154
	v_cvt_pk_bf16_f32 v166, v166, s0
	v_cvt_pk_bf16_f32 v154, v154, s0
	global_store_short v[158:159], v166, off
	v_mul_f32_e32 v166, v168, v147
	global_store_short v[158:159], v154, off offset:320
	v_mul_f32_e32 v154, v160, v147
	v_mul_f32_e32 v147, v161, v147
	v_mul_f32_e32 v147, v194, v147
	v_cvt_pk_bf16_f32 v147, v147, s0
	global_store_short v[158:159], v147, off offset:448
	v_mul_f32_e32 v147, 0x4b800000, v170
	v_cndmask_b32_e32 v147, v170, v147, vcc
	v_rsq_f32_e32 v147, v147
	v_mul_f32_e32 v154, v193, v154
	v_cvt_pk_bf16_f32 v154, v154, s0
	global_store_short v[158:159], v154, off offset:384
	v_mul_f32_e32 v154, 0x45800000, v147
	v_cndmask_b32_e32 v147, v147, v154, vcc
	v_mul_f32_e32 v156, v167, v147
	v_mul_f32_e32 v156, v179, v156
	v_lshl_add_u64 v[154:155], v[148:149], 0, v[162:163]
	v_cvt_pk_bf16_f32 v156, v156, s0
	global_store_short v[154:155], v156, off
	v_mul_f32_e32 v156, v169, v147
	v_mul_f32_e32 v156, v188, v156
	v_cvt_pk_bf16_f32 v156, v156, s0
	global_store_short v[154:155], v156, off offset:64
	v_mul_f32_e32 v156, v164, v147
	v_mul_f32_e32 v156, v189, v156
	v_cvt_pk_bf16_f32 v156, v156, s0
	global_store_short v[154:155], v156, off offset:128
	v_mul_f32_e32 v156, v165, v147
	v_mul_f32_e32 v156, v190, v156
	v_cvt_pk_bf16_f32 v156, v156, s0
	global_store_short v[154:155], v156, off offset:192
	v_mul_f32_e32 v156, v174, v147
	v_mul_f32_e32 v156, v191, v156
	v_cvt_pk_bf16_f32 v156, v156, s0
	global_store_short v[154:155], v156, off offset:256
	v_mul_f32_e32 v156, v175, v147
	v_mul_f32_e32 v156, v192, v156
	v_cvt_pk_bf16_f32 v156, v156, s0
	v_mul_f32_e32 v166, v188, v166
	global_store_short v[154:155], v156, off offset:320
	v_mul_f32_e32 v156, v184, v147
	v_mul_f32_e32 v147, v185, v147
	v_cvt_pk_bf16_f32 v166, v166, s0
	v_mul_f32_e32 v156, v193, v156
	v_mul_f32_e32 v147, v194, v147
	global_store_short v[158:159], v166, off offset:64
	v_cvt_pk_bf16_f32 v156, v156, s0
	v_cvt_pk_bf16_f32 v147, v147, s0
	v_or_b32_e32 v158, 0x2000, v146
	v_mov_b32_e32 v159, v1
	global_store_short v[154:155], v156, off offset:384
	global_store_short v[154:155], v147, off offset:448
	v_lshl_add_u64 v[160:161], v[150:151], 0, v[158:159]
	global_load_ushort v147, v[160:161], off
	global_load_ushort v180, v[160:161], off offset:64
	global_load_ushort v154, v[160:161], off offset:128
	global_load_ushort v155, v[160:161], off offset:192
	v_mov_b32_e32 v156, v100
	v_mov_b32_e32 v157, v84
	v_pk_mul_f32 v[156:157], v[156:157], v[142:143] op_sel_hi:[1,0]
	v_mov_b32_e32 v164, v68
	v_mov_b32_e32 v165, v52
	v_pk_mul_f32 v[164:165], v[164:165], v[142:143] op_sel_hi:[1,0]
	v_mov_b32_e32 v168, v101
	v_mov_b32_e32 v169, v85
	v_pk_mul_f32 v[168:169], v[168:169], v[178:179] op_sel_hi:[1,0]
	v_mov_b32_e32 v184, v69
	v_mov_b32_e32 v185, v53
	v_pk_mul_f32 v[184:185], v[184:185], v[178:179] op_sel_hi:[1,0]
	v_lshl_add_u64 v[158:159], v[148:149], 0, v[158:159]
	v_mov_b32_e32 v178, v141
	s_waitcnt vmcnt(1)
	v_lshlrev_b32_e32 v154, 16, v154
	s_waitcnt vmcnt(0)
	v_lshlrev_b32_e32 v155, 16, v155
	v_pk_fma_f32 v[154:155], v[218:219], v[156:157], v[154:155] neg_lo:[1,0,0] neg_hi:[1,0,0]
	global_load_ushort v156, v[160:161], off offset:256
	global_load_ushort v157, v[160:161], off offset:320
	v_pk_mul_f32 v[162:163], v[154:155], v[154:155]
	s_waitcnt vmcnt(1)
	v_lshlrev_b32_e32 v156, 16, v156
	s_waitcnt vmcnt(0)
	v_lshlrev_b32_e32 v157, 16, v157
	v_pk_fma_f32 v[156:157], v[218:219], v[164:165], v[156:157] neg_lo:[1,0,0] neg_hi:[1,0,0]
	global_load_ushort v164, v[160:161], off offset:384
	s_nop 0
	global_load_ushort v160, v[160:161], off offset:448
	v_mov_b32_e32 v165, v20
	v_mov_b32_e32 v182, v162
	v_pk_mul_f32 v[172:173], v[156:157], v[156:157]
	s_waitcnt vmcnt(0)
	v_lshlrev_b32_e32 v161, 16, v160
	v_lshlrev_b32_e32 v160, 16, v164
	v_mov_b32_e32 v164, v36
	v_pk_mul_f32 v[164:165], v[164:165], v[142:143] op_sel_hi:[1,0]
	s_nop 0
	v_pk_fma_f32 v[160:161], v[218:219], v[164:165], v[160:161] neg_lo:[1,0,0] neg_hi:[1,0,0]
	v_or_b32_e32 v164, 0x3000, v146
	v_mov_b32_e32 v165, v1
	v_lshl_add_u64 v[186:187], v[150:151], 0, v[164:165]
	global_load_ushort v170, v[186:187], off
	global_load_ushort v181, v[186:187], off offset:64
	global_load_ushort v166, v[186:187], off offset:128
	global_load_ushort v167, v[186:187], off offset:192
	v_pk_mul_f32 v[174:175], v[160:161], v[160:161]
	s_waitcnt vmcnt(1)
; __device__ __forceinline__ bf16_t f2bf(float x) { return (bf16_t)(cvt_pk_bf16(x, x) & 0xffffu); }
; __device__ __forceinline__ float bf2f(bf16_t b) { return __uint_as_float(((unsigned)b) << 16); }
; __device__ __forceinline__ int crow(int r, int hi) { return (r & 3) + 8 * (r >> 2) + 4 * hi; }
; __device__ __forceinline__ int crow(int r, int hi) { return (r & 3) + 8 * (r >> 2) + 4 * hi; }
; __device__ __forceinline__ void attn_body256(const bf16_t* __restrict__ Qb, const bf16_t* __restrict__ Kh, const bf16_t* __restrict__ Vh,
;                                              bf16_t* Ob, int seq, unsigned char* lds, float lam, int MODE, bf16_t* Ab, const float* wsub) {
;     ...
;     bf16_t* Aw = Ab + (long)(wid * QBLK) * LDO;
;     float wv[8];
; #pragma unroll
;     for (int d0 = 0; d0 < 8; ++d0) wv[d0] = wsub[d0 * 32 + r32] * (1.f - LAMBDA_INIT);
; #pragma unroll
;     for (int r = 0; r < 16; ++r) { const int orow = crow(r, hi); float ss = 0.f;
; #pragma unroll
;       for (int d0 = 0; d0 < 8; ++d0) { const float v = bf2f(Ow[(long)orow * LDO + d0 * 32 + r32]) - lam * (o[d0][r] * rli[r]); o[d0][r] = v; ss += v * v; }
;       ss += __shfl_xor(ss, 1, 64); ss += __shfl_xor(ss, 2, 64); ss += __shfl_xor(ss, 4, 64); ss += __shfl_xor(ss, 8, 64); ss += __shfl_xor(ss, 16, 64);
;       const float rstd = rsqrtf(ss * (1.f / 256.f) + NORM_EPS);
; #pragma unroll
;       for (int d0 = 0; d0 < 8; ++d0) Aw[(long)orow * LDO + d0 * 32 + r32] = f2bf(o[d0][r] * rstd * wv[d0]); }
	v_lshlrev_b32_e32 v166, 16, v166
	s_waitcnt vmcnt(0)
	v_lshlrev_b32_e32 v167, 16, v167
	v_pk_fma_f32 v[166:167], v[218:219], v[168:169], v[166:167] neg_lo:[1,0,0] neg_hi:[1,0,0]
	v_lshlrev_b32_e32 v168, 16, v147
	global_load_ushort v147, v[186:187], off offset:256
	global_load_ushort v162, v[186:187], off offset:320
	v_lshlrev_b32_e32 v169, 16, v170
	v_pk_mul_f32 v[170:171], v[4:5], v[142:143]
	v_pk_mul_f32 v[176:177], v[166:167], v[166:167]
	v_pk_fma_f32 v[168:169], v[218:219], v[170:171], v[168:169] neg_lo:[1,0,0] neg_hi:[1,0,0]
	v_lshlrev_b32_e32 v171, 16, v181
	v_lshlrev_b32_e32 v170, 16, v180
	v_pk_mul_f32 v[180:181], v[116:117], v[142:143]
	v_mov_b32_e32 v183, v176
	v_pk_fma_f32 v[170:171], v[218:219], v[180:181], v[170:171] neg_lo:[1,0,0] neg_hi:[1,0,0]
	s_nop 0
	v_pk_mul_f32 v[180:181], v[170:171], v[170:171]
	s_nop 0
	v_pk_fma_f32 v[180:181], v[168:169], v[168:169], v[180:181]
	s_nop 0
	v_pk_add_f32 v[180:181], v[180:181], v[182:183]
	s_waitcnt vmcnt(1)
	v_lshlrev_b32_e32 v182, 16, v147
	s_waitcnt vmcnt(0)
	v_lshlrev_b32_e32 v183, 16, v162
	global_load_ushort v147, v[186:187], off offset:384
	global_load_ushort v162, v[186:187], off offset:448
	v_pk_fma_f32 v[182:183], v[218:219], v[184:185], v[182:183] neg_lo:[1,0,0] neg_hi:[1,0,0]
	s_waitcnt vmcnt(1)
	v_lshlrev_b32_e32 v186, 16, v147
	v_pk_mul_f32 v[184:185], v[182:183], v[182:183]
	s_waitcnt vmcnt(0)
	v_lshlrev_b32_e32 v187, 16, v162
	v_mov_b32_e32 v162, v177
	v_pk_fma_f32 v[186:187], v[218:219], v[200:201], v[186:187] neg_lo:[1,0,0] neg_hi:[1,0,0]
	v_pk_add_f32 v[162:163], v[180:181], v[162:163] op_sel:[1,0] op_sel_hi:[0,1]
	v_mov_b32_e32 v176, v184
	v_mov_b32_e32 v177, v172
	v_pk_mul_f32 v[200:201], v[186:187], v[186:187]
	v_pk_add_f32 v[162:163], v[162:163], v[176:177]
	v_mov_b32_e32 v172, v185
	v_pk_add_f32 v[162:163], v[162:163], v[172:173]
	v_mov_b32_e32 v172, v200
	v_mov_b32_e32 v173, v174
	v_pk_add_f32 v[162:163], v[162:163], v[172:173]
	v_mov_b32_e32 v174, v201
	v_pk_add_f32 v[162:163], v[162:163], v[174:175]
	ds_bpermute_b32 v173, v199, v163
	ds_bpermute_b32 v172, v199, v162
	v_mov_b32_e32 v184, v71
	v_mov_b32_e32 v185, v55
	v_pk_mul_f32 v[184:185], v[184:185], v[178:179] op_sel_hi:[1,0]
	v_mov_b32_e32 v200, v39
	s_waitcnt lgkmcnt(0)
	v_pk_add_f32 v[162:163], v[162:163], v[172:173]
	ds_bpermute_b32 v173, v198, v163
	ds_bpermute_b32 v172, v198, v162
	v_mov_b32_e32 v201, v23
	v_pk_mul_f32 v[200:201], v[200:201], v[178:179] op_sel_hi:[1,0]
	s_waitcnt lgkmcnt(0)
	v_pk_add_f32 v[162:163], v[162:163], v[172:173]
	ds_bpermute_b32 v173, v197, v163
	ds_bpermute_b32 v172, v197, v162
	s_waitcnt lgkmcnt(0)
	v_pk_add_f32 v[162:163], v[162:163], v[172:173]
	ds_bpermute_b32 v173, v196, v163
	ds_bpermute_b32 v172, v196, v162
	s_waitcnt lgkmcnt(0)
	v_pk_add_f32 v[162:163], v[162:163], v[172:173]
	ds_bpermute_b32 v173, v195, v163
	ds_bpermute_b32 v172, v195, v162
	s_waitcnt lgkmcnt(0)
	v_pk_add_f32 v[162:163], v[162:163], v[172:173]
	s_nop 0
	v_pk_fma_f32 v[162:163], v[162:163], s[2:3], v[152:153] op_sel_hi:[1,0,0]
	s_nop 0
	v_mul_f32_e32 v147, 0x4b800000, v163
	v_cmp_gt_f32_e64 s[0:1], s58, v163
	v_cmp_gt_f32_e32 vcc, s58, v162
	s_nop 0
	v_cndmask_b32_e64 v147, v163, v147, s[0:1]
	v_rsq_f32_e32 v147, v147
	s_nop 0
	v_mul_f32_e32 v163, 0x45800000, v147
	v_cndmask_b32_e64 v147, v147, v163, s[0:1]
	v_mul_f32_e32 v154, v154, v147
	v_mul_f32_e32 v154, v189, v154
	v_cvt_pk_bf16_f32 v154, v154, s0
	global_store_short v[158:159], v154, off offset:128
	v_mul_f32_e32 v154, v155, v147
	v_mul_f32_e32 v154, v190, v154
	v_cvt_pk_bf16_f32 v154, v154, s0
	global_store_short v[158:159], v154, off offset:192
	v_mul_f32_e32 v154, v156, v147
	v_mul_f32_e32 v154, v191, v154
	v_cvt_pk_bf16_f32 v154, v154, s0
	v_mul_f32_e32 v163, v168, v147
	global_store_short v[158:159], v154, off offset:256
	v_mul_f32_e32 v154, v157, v147
	v_mul_f32_e32 v163, v179, v163
	v_mul_f32_e32 v154, v192, v154
	v_cvt_pk_bf16_f32 v163, v163, s0
	v_cvt_pk_bf16_f32 v154, v154, s0
	global_store_short v[158:159], v163, off
	v_mul_f32_e32 v163, v170, v147
	global_store_short v[158:159], v154, off offset:320
	v_mul_f32_e32 v154, v160, v147
	v_mul_f32_e32 v147, v161, v147
	v_mul_f32_e32 v147, v194, v147
	v_cvt_pk_bf16_f32 v147, v147, s0
	global_store_short v[158:159], v147, off offset:448
	v_mul_f32_e32 v147, 0x4b800000, v162
	v_cndmask_b32_e32 v147, v162, v147, vcc
	v_rsq_f32_e32 v147, v147
	v_mul_f32_e32 v154, v193, v154
	v_cvt_pk_bf16_f32 v154, v154, s0
	global_store_short v[158:159], v154, off offset:384
	v_mul_f32_e32 v154, 0x45800000, v147
	v_cndmask_b32_e32 v147, v147, v154, vcc
	v_mul_f32_e32 v156, v169, v147
	v_mul_f32_e32 v156, v179, v156
	v_lshl_add_u64 v[154:155], v[148:149], 0, v[164:165]
	v_cvt_pk_bf16_f32 v156, v156, s0
	global_store_short v[154:155], v156, off
	v_mul_f32_e32 v156, v171, v147
	v_mul_f32_e32 v156, v188, v156
	v_cvt_pk_bf16_f32 v156, v156, s0
	global_store_short v[154:155], v156, off offset:64
	v_mul_f32_e32 v156, v166, v147
	v_mul_f32_e32 v156, v189, v156
	v_cvt_pk_bf16_f32 v156, v156, s0
	global_store_short v[154:155], v156, off offset:128
	v_mul_f32_e32 v156, v167, v147
	v_mul_f32_e32 v156, v190, v156
	v_cvt_pk_bf16_f32 v156, v156, s0
	global_store_short v[154:155], v156, off offset:192
	v_mul_f32_e32 v156, v182, v147
	v_mul_f32_e32 v156, v191, v156
	v_cvt_pk_bf16_f32 v156, v156, s0
	global_store_short v[154:155], v156, off offset:256
	v_mul_f32_e32 v156, v183, v147
	v_mul_f32_e32 v156, v192, v156
	v_cvt_pk_bf16_f32 v156, v156, s0
	v_mul_f32_e32 v163, v188, v163
	global_store_short v[154:155], v156, off offset:320
	v_mul_f32_e32 v156, v186, v147
	v_mul_f32_e32 v147, v187, v147
	v_cvt_pk_bf16_f32 v163, v163, s0
	v_mul_f32_e32 v156, v193, v156
	v_mul_f32_e32 v147, v194, v147
	global_store_short v[158:159], v163, off offset:64
	v_cvt_pk_bf16_f32 v156, v156, s0
	v_cvt_pk_bf16_f32 v147, v147, s0
	v_or_b32_e32 v158, 0x8000, v146
	v_mov_b32_e32 v159, v1
	global_store_short v[154:155], v156, off offset:384
	global_store_short v[154:155], v147, off offset:448
	v_lshl_add_u64 v[160:161], v[150:151], 0, v[158:159]
	global_load_ushort v147, v[160:161], off
	global_load_ushort v180, v[160:161], off offset:64
	global_load_ushort v154, v[160:161], off offset:128
	global_load_ushort v155, v[160:161], off offset:192
	v_mov_b32_e32 v156, v102
	v_mov_b32_e32 v157, v86
	v_pk_mul_f32 v[156:157], v[156:157], v[140:141] op_sel_hi:[1,0]
	v_mov_b32_e32 v164, v70
	v_mov_b32_e32 v165, v54
	v_pk_mul_f32 v[164:165], v[164:165], v[140:141] op_sel_hi:[1,0]
	v_mov_b32_e32 v168, v103
	v_mov_b32_e32 v169, v87
	v_pk_mul_f32 v[168:169], v[168:169], v[178:179] op_sel_hi:[1,0]
	v_lshl_add_u64 v[158:159], v[148:149], 0, v[158:159]
	v_mov_b32_e32 v178, v139
	s_waitcnt vmcnt(1)
; __device__ __forceinline__ bf16_t f2bf(float x) { return (bf16_t)(cvt_pk_bf16(x, x) & 0xffffu); }
; __device__ __forceinline__ float bf2f(bf16_t b) { return __uint_as_float(((unsigned)b) << 16); }
; __device__ __forceinline__ int crow(int r, int hi) { return (r & 3) + 8 * (r >> 2) + 4 * hi; }
; __device__ __forceinline__ int crow(int r, int hi) { return (r & 3) + 8 * (r >> 2) + 4 * hi; }
; __device__ __forceinline__ void attn_body256(const bf16_t* __restrict__ Qb, const bf16_t* __restrict__ Kh, const bf16_t* __restrict__ Vh,
;                                              bf16_t* Ob, int seq, unsigned char* lds, float lam, int MODE, bf16_t* Ab, const float* wsub) {
;     ...
;     bf16_t* Aw = Ab + (long)(wid * QBLK) * LDO;
;     float wv[8];
; #pragma unroll
;     for (int d0 = 0; d0 < 8; ++d0) wv[d0] = wsub[d0 * 32 + r32] * (1.f - LAMBDA_INIT);
; #pragma unroll
;     for (int r = 0; r < 16; ++r) { const int orow = crow(r, hi); float ss = 0.f;
; #pragma unroll
;       for (int d0 = 0; d0 < 8; ++d0) { const float v = bf2f(Ow[(long)orow * LDO + d0 * 32 + r32]) - lam * (o[d0][r] * rli[r]); o[d0][r] = v; ss += v * v; }
;       ss += __shfl_xor(ss, 1, 64); ss += __shfl_xor(ss, 2, 64); ss += __shfl_xor(ss, 4, 64); ss += __shfl_xor(ss, 8, 64); ss += __shfl_xor(ss, 16, 64);
;       const float rstd = rsqrtf(ss * (1.f / 256.f) + NORM_EPS);
; #pragma unroll
;       for (int d0 = 0; d0 < 8; ++d0) Aw[(long)orow * LDO + d0 * 32 + r32] = f2bf(o[d0][r] * rstd * wv[d0]); }
	v_lshlrev_b32_e32 v154, 16, v154
	s_waitcnt vmcnt(0)
	v_lshlrev_b32_e32 v155, 16, v155
	v_pk_fma_f32 v[154:155], v[218:219], v[156:157], v[154:155] neg_lo:[1,0,0] neg_hi:[1,0,0]
	global_load_ushort v156, v[160:161], off offset:256
	global_load_ushort v157, v[160:161], off offset:320
	v_pk_mul_f32 v[162:163], v[154:155], v[154:155]
	s_waitcnt vmcnt(1)
	v_lshlrev_b32_e32 v156, 16, v156
	s_waitcnt vmcnt(0)
	v_lshlrev_b32_e32 v157, 16, v157
	v_pk_fma_f32 v[156:157], v[218:219], v[164:165], v[156:157] neg_lo:[1,0,0] neg_hi:[1,0,0]
	global_load_ushort v164, v[160:161], off offset:384
	s_nop 0
	global_load_ushort v160, v[160:161], off offset:448
	v_mov_b32_e32 v165, v22
	v_mov_b32_e32 v182, v162
	v_pk_mul_f32 v[172:173], v[156:157], v[156:157]
	s_waitcnt vmcnt(0)
	v_lshlrev_b32_e32 v161, 16, v160
	v_lshlrev_b32_e32 v160, 16, v164
	v_mov_b32_e32 v164, v38
	v_pk_mul_f32 v[164:165], v[164:165], v[140:141] op_sel_hi:[1,0]
	s_nop 0
	v_pk_fma_f32 v[160:161], v[218:219], v[164:165], v[160:161] neg_lo:[1,0,0] neg_hi:[1,0,0]
	v_or_b32_e32 v164, 0x9000, v146
	v_mov_b32_e32 v165, v1
	v_lshl_add_u64 v[186:187], v[150:151], 0, v[164:165]
	global_load_ushort v170, v[186:187], off
	global_load_ushort v181, v[186:187], off offset:64
	global_load_ushort v166, v[186:187], off offset:128
	global_load_ushort v167, v[186:187], off offset:192
	v_pk_mul_f32 v[174:175], v[160:161], v[160:161]
	s_waitcnt vmcnt(1)
	v_lshlrev_b32_e32 v166, 16, v166
	s_waitcnt vmcnt(0)
	v_lshlrev_b32_e32 v167, 16, v167
	v_pk_fma_f32 v[166:167], v[218:219], v[168:169], v[166:167] neg_lo:[1,0,0] neg_hi:[1,0,0]
	v_lshlrev_b32_e32 v168, 16, v147
	global_load_ushort v147, v[186:187], off offset:256
	global_load_ushort v162, v[186:187], off offset:320
	v_lshlrev_b32_e32 v169, 16, v170
	v_pk_mul_f32 v[170:171], v[6:7], v[140:141]
	v_pk_mul_f32 v[176:177], v[166:167], v[166:167]
	v_pk_fma_f32 v[168:169], v[218:219], v[170:171], v[168:169] neg_lo:[1,0,0] neg_hi:[1,0,0]
	v_lshlrev_b32_e32 v171, 16, v181
	v_lshlrev_b32_e32 v170, 16, v180
	v_pk_mul_f32 v[180:181], v[118:119], v[140:141]
	v_mov_b32_e32 v183, v176
	v_pk_fma_f32 v[170:171], v[218:219], v[180:181], v[170:171] neg_lo:[1,0,0] neg_hi:[1,0,0]
	s_nop 0
	v_pk_mul_f32 v[180:181], v[170:171], v[170:171]
	s_nop 0
	v_pk_fma_f32 v[180:181], v[168:169], v[168:169], v[180:181]
	s_nop 0
	v_pk_add_f32 v[180:181], v[180:181], v[182:183]
	s_waitcnt vmcnt(1)
	v_lshlrev_b32_e32 v182, 16, v147
	s_waitcnt vmcnt(0)
	v_lshlrev_b32_e32 v183, 16, v162
	global_load_ushort v147, v[186:187], off offset:384
	global_load_ushort v162, v[186:187], off offset:448
	v_pk_fma_f32 v[182:183], v[218:219], v[184:185], v[182:183] neg_lo:[1,0,0] neg_hi:[1,0,0]
	s_waitcnt vmcnt(1)
	v_lshlrev_b32_e32 v186, 16, v147
	v_pk_mul_f32 v[184:185], v[182:183], v[182:183]
	s_waitcnt vmcnt(0)
	v_lshlrev_b32_e32 v187, 16, v162
	v_mov_b32_e32 v162, v177
	v_pk_fma_f32 v[186:187], v[218:219], v[200:201], v[186:187] neg_lo:[1,0,0] neg_hi:[1,0,0]
	v_pk_add_f32 v[162:163], v[180:181], v[162:163] op_sel:[1,0] op_sel_hi:[0,1]
	v_mov_b32_e32 v176, v184
	v_mov_b32_e32 v177, v172
	v_pk_mul_f32 v[200:201], v[186:187], v[186:187]
	v_pk_add_f32 v[162:163], v[162:163], v[176:177]
	v_mov_b32_e32 v172, v185
	v_pk_add_f32 v[162:163], v[162:163], v[172:173]
	v_mov_b32_e32 v172, v200
	v_mov_b32_e32 v173, v174
	v_pk_add_f32 v[162:163], v[162:163], v[172:173]
	v_mov_b32_e32 v174, v201
	v_pk_add_f32 v[162:163], v[162:163], v[174:175]
	ds_bpermute_b32 v173, v199, v163
	ds_bpermute_b32 v172, v199, v162
	v_mov_b32_e32 v184, v73
	v_mov_b32_e32 v185, v57
	v_pk_mul_f32 v[184:185], v[184:185], v[178:179] op_sel_hi:[1,0]
	v_mov_b32_e32 v200, v41
	s_waitcnt lgkmcnt(0)
	v_pk_add_f32 v[162:163], v[162:163], v[172:173]
	ds_bpermute_b32 v173, v198, v163
	ds_bpermute_b32 v172, v198, v162
	v_mov_b32_e32 v201, v25
	v_pk_mul_f32 v[200:201], v[200:201], v[178:179] op_sel_hi:[1,0]
	s_waitcnt lgkmcnt(0)
	v_pk_add_f32 v[162:163], v[162:163], v[172:173]
	ds_bpermute_b32 v173, v197, v163
	ds_bpermute_b32 v172, v197, v162
	s_waitcnt lgkmcnt(0)
	v_pk_add_f32 v[162:163], v[162:163], v[172:173]
	ds_bpermute_b32 v173, v196, v163
	ds_bpermute_b32 v172, v196, v162
	s_waitcnt lgkmcnt(0)
	v_pk_add_f32 v[162:163], v[162:163], v[172:173]
	ds_bpermute_b32 v173, v195, v163
	ds_bpermute_b32 v172, v195, v162
	s_waitcnt lgkmcnt(0)
; __device__ __forceinline__ bf16_t f2bf(float x) { return (bf16_t)(cvt_pk_bf16(x, x) & 0xffffu); }
; __device__ __forceinline__ float bf2f(bf16_t b) { return __uint_as_float(((unsigned)b) << 16); }
; __device__ __forceinline__ int crow(int r, int hi) { return (r & 3) + 8 * (r >> 2) + 4 * hi; }
; __device__ __forceinline__ int crow(int r, int hi) { return (r & 3) + 8 * (r >> 2) + 4 * hi; }
; __device__ __forceinline__ void attn_body256(const bf16_t* __restrict__ Qb, const bf16_t* __restrict__ Kh, const bf16_t* __restrict__ Vh,
;                                              bf16_t* Ob, int seq, unsigned char* lds, float lam, int MODE, bf16_t* Ab, const float* wsub) {
;     ...
;     bf16_t* Aw = Ab + (long)(wid * QBLK) * LDO;
;     float wv[8];
; #pragma unroll
;     for (int d0 = 0; d0 < 8; ++d0) wv[d0] = wsub[d0 * 32 + r32] * (1.f - LAMBDA_INIT);
; #pragma unroll
;     for (int r = 0; r < 16; ++r) { const int orow = crow(r, hi); float ss = 0.f;
; #pragma unroll
;       for (int d0 = 0; d0 < 8; ++d0) { const float v = bf2f(Ow[(long)orow * LDO + d0 * 32 + r32]) - lam * (o[d0][r] * rli[r]); o[d0][r] = v; ss += v * v; }
;       ss += __shfl_xor(ss, 1, 64); ss += __shfl_xor(ss, 2, 64); ss += __shfl_xor(ss, 4, 64); ss += __shfl_xor(ss, 8, 64); ss += __shfl_xor(ss, 16, 64);
;       const float rstd = rsqrtf(ss * (1.f / 256.f) + NORM_EPS);
; #pragma unroll
;       for (int d0 = 0; d0 < 8; ++d0) Aw[(long)orow * LDO + d0 * 32 + r32] = f2bf(o[d0][r] * rstd * wv[d0]); }
	v_pk_add_f32 v[162:163], v[162:163], v[172:173]
	s_nop 0
	v_pk_fma_f32 v[162:163], v[162:163], s[2:3], v[152:153] op_sel_hi:[1,0,0]
	s_nop 0
	v_mul_f32_e32 v147, 0x4b800000, v163
	v_cmp_gt_f32_e64 s[0:1], s58, v163
	v_cmp_gt_f32_e32 vcc, s58, v162
	s_nop 0
	v_cndmask_b32_e64 v147, v163, v147, s[0:1]
	v_rsq_f32_e32 v147, v147
	s_nop 0
	v_mul_f32_e32 v163, 0x45800000, v147
	v_cndmask_b32_e64 v147, v147, v163, s[0:1]
	v_mul_f32_e32 v154, v154, v147
	v_mul_f32_e32 v154, v189, v154
	v_cvt_pk_bf16_f32 v154, v154, s0
	global_store_short v[158:159], v154, off offset:128
	v_mul_f32_e32 v154, v155, v147
	v_mul_f32_e32 v154, v190, v154
	v_cvt_pk_bf16_f32 v154, v154, s0
	global_store_short v[158:159], v154, off offset:192
	v_mul_f32_e32 v154, v156, v147
	v_mul_f32_e32 v154, v191, v154
	v_cvt_pk_bf16_f32 v154, v154, s0
	v_mul_f32_e32 v163, v168, v147
	global_store_short v[158:159], v154, off offset:256
	v_mul_f32_e32 v154, v157, v147
	v_mul_f32_e32 v163, v179, v163
	v_mul_f32_e32 v154, v192, v154
	v_cvt_pk_bf16_f32 v163, v163, s0
	v_cvt_pk_bf16_f32 v154, v154, s0
	global_store_short v[158:159], v163, off
	v_mul_f32_e32 v163, v170, v147
	global_store_short v[158:159], v154, off offset:320
	v_mul_f32_e32 v154, v160, v147
	v_mul_f32_e32 v147, v161, v147
	v_mul_f32_e32 v147, v194, v147
	v_cvt_pk_bf16_f32 v147, v147, s0
	global_store_short v[158:159], v147, off offset:448
	v_mul_f32_e32 v147, 0x4b800000, v162
	v_cndmask_b32_e32 v147, v162, v147, vcc
	v_rsq_f32_e32 v147, v147
	v_mul_f32_e32 v154, v193, v154
	v_cvt_pk_bf16_f32 v154, v154, s0
	global_store_short v[158:159], v154, off offset:384
	v_mul_f32_e32 v154, 0x45800000, v147
	v_cndmask_b32_e32 v147, v147, v154, vcc
	v_mul_f32_e32 v156, v169, v147
	v_mul_f32_e32 v156, v179, v156
	v_lshl_add_u64 v[154:155], v[148:149], 0, v[164:165]
	v_cvt_pk_bf16_f32 v156, v156, s0
	global_store_short v[154:155], v156, off
	v_mul_f32_e32 v156, v171, v147
	v_mul_f32_e32 v156, v188, v156
	v_cvt_pk_bf16_f32 v156, v156, s0
	global_store_short v[154:155], v156, off offset:64
	v_mul_f32_e32 v156, v166, v147
	v_mul_f32_e32 v156, v189, v156
	v_cvt_pk_bf16_f32 v156, v156, s0
	global_store_short v[154:155], v156, off offset:128
	v_mul_f32_e32 v156, v167, v147
	v_mul_f32_e32 v156, v190, v156
	v_cvt_pk_bf16_f32 v156, v156, s0
	global_store_short v[154:155], v156, off offset:192
	v_mul_f32_e32 v156, v182, v147
	v_mul_f32_e32 v156, v191, v156
	v_cvt_pk_bf16_f32 v156, v156, s0
	global_store_short v[154:155], v156, off offset:256
	v_mul_f32_e32 v156, v183, v147
	v_mul_f32_e32 v156, v192, v156
	v_cvt_pk_bf16_f32 v156, v156, s0
	v_mul_f32_e32 v163, v188, v163
	global_store_short v[154:155], v156, off offset:320
	v_mul_f32_e32 v156, v186, v147
	v_mul_f32_e32 v147, v187, v147
	v_cvt_pk_bf16_f32 v163, v163, s0
	v_mul_f32_e32 v156, v193, v156
	v_mul_f32_e32 v147, v194, v147
	global_store_short v[158:159], v163, off offset:64
	v_cvt_pk_bf16_f32 v156, v156, s0
	v_cvt_pk_bf16_f32 v147, v147, s0
	v_or_b32_e32 v158, 0xa000, v146
	v_mov_b32_e32 v159, v1
	global_store_short v[154:155], v156, off offset:384
	global_store_short v[154:155], v147, off offset:448
	v_lshl_add_u64 v[160:161], v[150:151], 0, v[158:159]
	global_load_ushort v147, v[160:161], off
	global_load_ushort v180, v[160:161], off offset:64
	global_load_ushort v154, v[160:161], off offset:128
	global_load_ushort v155, v[160:161], off offset:192
	v_mov_b32_e32 v156, v104
	v_mov_b32_e32 v157, v88
	v_pk_mul_f32 v[156:157], v[156:157], v[138:139] op_sel_hi:[1,0]
	v_mov_b32_e32 v164, v72
	v_mov_b32_e32 v165, v56
	v_pk_mul_f32 v[164:165], v[164:165], v[138:139] op_sel_hi:[1,0]
	v_mov_b32_e32 v168, v105
	v_mov_b32_e32 v169, v89
	v_pk_mul_f32 v[168:169], v[168:169], v[178:179] op_sel_hi:[1,0]
	v_lshl_add_u64 v[158:159], v[148:149], 0, v[158:159]
	v_mov_b32_e32 v178, v137
	s_waitcnt vmcnt(1)
	v_lshlrev_b32_e32 v154, 16, v154
	s_waitcnt vmcnt(0)
	v_lshlrev_b32_e32 v155, 16, v155
	v_pk_fma_f32 v[154:155], v[218:219], v[156:157], v[154:155] neg_lo:[1,0,0] neg_hi:[1,0,0]
	global_load_ushort v156, v[160:161], off offset:256
	global_load_ushort v157, v[160:161], off offset:320
	v_pk_mul_f32 v[162:163], v[154:155], v[154:155]
	s_waitcnt vmcnt(1)
	v_lshlrev_b32_e32 v156, 16, v156
	s_waitcnt vmcnt(0)
	v_lshlrev_b32_e32 v157, 16, v157
	v_pk_fma_f32 v[156:157], v[218:219], v[164:165], v[156:157] neg_lo:[1,0,0] neg_hi:[1,0,0]
	global_load_ushort v164, v[160:161], off offset:384
	s_nop 0
	global_load_ushort v160, v[160:161], off offset:448
	v_mov_b32_e32 v165, v24
	v_mov_b32_e32 v182, v162
	v_pk_mul_f32 v[172:173], v[156:157], v[156:157]
	s_waitcnt vmcnt(0)
	v_lshlrev_b32_e32 v161, 16, v160
	v_lshlrev_b32_e32 v160, 16, v164
	v_mov_b32_e32 v164, v40
	v_pk_mul_f32 v[164:165], v[164:165], v[138:139] op_sel_hi:[1,0]
	s_nop 0
	v_pk_fma_f32 v[160:161], v[218:219], v[164:165], v[160:161] neg_lo:[1,0,0] neg_hi:[1,0,0]
	v_or_b32_e32 v164, 0xb000, v146
	v_mov_b32_e32 v165, v1
	v_lshl_add_u64 v[186:187], v[150:151], 0, v[164:165]
	global_load_ushort v170, v[186:187], off
	global_load_ushort v181, v[186:187], off offset:64
	global_load_ushort v166, v[186:187], off offset:128
	global_load_ushort v167, v[186:187], off offset:192
	v_pk_mul_f32 v[174:175], v[160:161], v[160:161]
	s_waitcnt vmcnt(1)
	v_lshlrev_b32_e32 v166, 16, v166
	s_waitcnt vmcnt(0)
; __device__ __forceinline__ bf16_t f2bf(float x) { return (bf16_t)(cvt_pk_bf16(x, x) & 0xffffu); }
; __device__ __forceinline__ float bf2f(bf16_t b) { return __uint_as_float(((unsigned)b) << 16); }
; __device__ __forceinline__ int crow(int r, int hi) { return (r & 3) + 8 * (r >> 2) + 4 * hi; }
; __device__ __forceinline__ int crow(int r, int hi) { return (r & 3) + 8 * (r >> 2) + 4 * hi; }
; __device__ __forceinline__ void attn_body256(const bf16_t* __restrict__ Qb, const bf16_t* __restrict__ Kh, const bf16_t* __restrict__ Vh,
;                                              bf16_t* Ob, int seq, unsigned char* lds, float lam, int MODE, bf16_t* Ab, const float* wsub) {
;     ...
;     bf16_t* Aw = Ab + (long)(wid * QBLK) * LDO;
;     float wv[8];
; #pragma unroll
;     for (int d0 = 0; d0 < 8; ++d0) wv[d0] = wsub[d0 * 32 + r32] * (1.f - LAMBDA_INIT);
; #pragma unroll
;     for (int r = 0; r < 16; ++r) { const int orow = crow(r, hi); float ss = 0.f;
; #pragma unroll
;       for (int d0 = 0; d0 < 8; ++d0) { const float v = bf2f(Ow[(long)orow * LDO + d0 * 32 + r32]) - lam * (o[d0][r] * rli[r]); o[d0][r] = v; ss += v * v; }
;       ss += __shfl_xor(ss, 1, 64); ss += __shfl_xor(ss, 2, 64); ss += __shfl_xor(ss, 4, 64); ss += __shfl_xor(ss, 8, 64); ss += __shfl_xor(ss, 16, 64);
;       const float rstd = rsqrtf(ss * (1.f / 256.f) + NORM_EPS);
; #pragma unroll
;       for (int d0 = 0; d0 < 8; ++d0) Aw[(long)orow * LDO + d0 * 32 + r32] = f2bf(o[d0][r] * rstd * wv[d0]); }
	v_lshlrev_b32_e32 v167, 16, v167
	v_pk_fma_f32 v[166:167], v[218:219], v[168:169], v[166:167] neg_lo:[1,0,0] neg_hi:[1,0,0]
	v_lshlrev_b32_e32 v168, 16, v147
	global_load_ushort v147, v[186:187], off offset:256
	global_load_ushort v162, v[186:187], off offset:320
	v_lshlrev_b32_e32 v169, 16, v170
	v_pk_mul_f32 v[170:171], v[8:9], v[138:139]
	v_pk_mul_f32 v[176:177], v[166:167], v[166:167]
	v_pk_fma_f32 v[168:169], v[218:219], v[170:171], v[168:169] neg_lo:[1,0,0] neg_hi:[1,0,0]
	v_lshlrev_b32_e32 v171, 16, v181
	v_lshlrev_b32_e32 v170, 16, v180
	v_pk_mul_f32 v[180:181], v[120:121], v[138:139]
	v_mov_b32_e32 v183, v176
	v_pk_fma_f32 v[170:171], v[218:219], v[180:181], v[170:171] neg_lo:[1,0,0] neg_hi:[1,0,0]
	s_nop 0
	v_pk_mul_f32 v[180:181], v[170:171], v[170:171]
	s_nop 0
	v_pk_fma_f32 v[180:181], v[168:169], v[168:169], v[180:181]
	s_nop 0
	v_pk_add_f32 v[180:181], v[180:181], v[182:183]
	s_waitcnt vmcnt(1)
	v_lshlrev_b32_e32 v182, 16, v147
	s_waitcnt vmcnt(0)
	v_lshlrev_b32_e32 v183, 16, v162
	global_load_ushort v147, v[186:187], off offset:384
	global_load_ushort v162, v[186:187], off offset:448
	v_pk_fma_f32 v[182:183], v[218:219], v[184:185], v[182:183] neg_lo:[1,0,0] neg_hi:[1,0,0]
	s_waitcnt vmcnt(1)
	v_lshlrev_b32_e32 v186, 16, v147
	v_pk_mul_f32 v[184:185], v[182:183], v[182:183]
	s_waitcnt vmcnt(0)
	v_lshlrev_b32_e32 v187, 16, v162
	v_mov_b32_e32 v162, v177
	v_pk_fma_f32 v[186:187], v[218:219], v[200:201], v[186:187] neg_lo:[1,0,0] neg_hi:[1,0,0]
	v_pk_add_f32 v[162:163], v[180:181], v[162:163] op_sel:[1,0] op_sel_hi:[0,1]
	v_mov_b32_e32 v176, v184
	v_mov_b32_e32 v177, v172
	v_pk_mul_f32 v[200:201], v[186:187], v[186:187]
	v_pk_add_f32 v[162:163], v[162:163], v[176:177]
	v_mov_b32_e32 v172, v185
	v_pk_add_f32 v[162:163], v[162:163], v[172:173]
	v_mov_b32_e32 v172, v200
	v_mov_b32_e32 v173, v174
	v_pk_add_f32 v[162:163], v[162:163], v[172:173]
	v_mov_b32_e32 v174, v201
	v_pk_add_f32 v[162:163], v[162:163], v[174:175]
	ds_bpermute_b32 v173, v199, v163
	ds_bpermute_b32 v172, v199, v162
	v_mov_b32_e32 v184, v75
	v_mov_b32_e32 v185, v59
	v_pk_mul_f32 v[184:185], v[184:185], v[178:179] op_sel_hi:[1,0]
	v_mov_b32_e32 v200, v43
	s_waitcnt lgkmcnt(0)
	v_pk_add_f32 v[162:163], v[162:163], v[172:173]
	ds_bpermute_b32 v173, v198, v163
	ds_bpermute_b32 v172, v198, v162
	v_mov_b32_e32 v201, v27
	v_pk_mul_f32 v[200:201], v[200:201], v[178:179] op_sel_hi:[1,0]
	s_waitcnt lgkmcnt(0)
	v_pk_add_f32 v[162:163], v[162:163], v[172:173]
	ds_bpermute_b32 v173, v197, v163
	ds_bpermute_b32 v172, v197, v162
	s_waitcnt lgkmcnt(0)
	v_pk_add_f32 v[162:163], v[162:163], v[172:173]
	ds_bpermute_b32 v173, v196, v163
	ds_bpermute_b32 v172, v196, v162
	s_waitcnt lgkmcnt(0)
	v_pk_add_f32 v[162:163], v[162:163], v[172:173]
	ds_bpermute_b32 v173, v195, v163
	ds_bpermute_b32 v172, v195, v162
	s_waitcnt lgkmcnt(0)
	v_pk_add_f32 v[162:163], v[162:163], v[172:173]
	s_nop 0
	v_pk_fma_f32 v[162:163], v[162:163], s[2:3], v[152:153] op_sel_hi:[1,0,0]
	s_nop 0
	v_mul_f32_e32 v147, 0x4b800000, v163
	v_cmp_gt_f32_e64 s[0:1], s58, v163
	v_cmp_gt_f32_e32 vcc, s58, v162
	s_nop 0
	v_cndmask_b32_e64 v147, v163, v147, s[0:1]
	v_rsq_f32_e32 v147, v147
	s_nop 0
	v_mul_f32_e32 v163, 0x45800000, v147
	v_cndmask_b32_e64 v147, v147, v163, s[0:1]
	v_mul_f32_e32 v154, v154, v147
	v_mul_f32_e32 v154, v189, v154
	v_cvt_pk_bf16_f32 v154, v154, s0
	global_store_short v[158:159], v154, off offset:128
	v_mul_f32_e32 v154, v155, v147
	v_mul_f32_e32 v154, v190, v154
	v_cvt_pk_bf16_f32 v154, v154, s0
	global_store_short v[158:159], v154, off offset:192
	v_mul_f32_e32 v154, v156, v147
	v_mul_f32_e32 v154, v191, v154
	v_cvt_pk_bf16_f32 v154, v154, s0
	v_mul_f32_e32 v163, v168, v147
	global_store_short v[158:159], v154, off offset:256
	v_mul_f32_e32 v154, v157, v147
	v_mul_f32_e32 v163, v179, v163
	v_mul_f32_e32 v154, v192, v154
	v_cvt_pk_bf16_f32 v163, v163, s0
	v_cvt_pk_bf16_f32 v154, v154, s0
	global_store_short v[158:159], v163, off
	v_mul_f32_e32 v163, v170, v147
	global_store_short v[158:159], v154, off offset:320
	v_mul_f32_e32 v154, v160, v147
	v_mul_f32_e32 v147, v161, v147
	v_mul_f32_e32 v147, v194, v147
	v_cvt_pk_bf16_f32 v147, v147, s0
	global_store_short v[158:159], v147, off offset:448
	v_mul_f32_e32 v147, 0x4b800000, v162
	v_cndmask_b32_e32 v147, v162, v147, vcc
	v_rsq_f32_e32 v147, v147
	v_mul_f32_e32 v154, v193, v154
	v_cvt_pk_bf16_f32 v154, v154, s0
	global_store_short v[158:159], v154, off offset:384
	v_mul_f32_e32 v154, 0x45800000, v147
	v_cndmask_b32_e32 v147, v147, v154, vcc
	v_mul_f32_e32 v156, v169, v147
	v_mul_f32_e32 v156, v179, v156
	v_lshl_add_u64 v[154:155], v[148:149], 0, v[164:165]
	v_cvt_pk_bf16_f32 v156, v156, s0
	global_store_short v[154:155], v156, off
	v_mul_f32_e32 v156, v171, v147
	v_mul_f32_e32 v156, v188, v156
	v_cvt_pk_bf16_f32 v156, v156, s0
	global_store_short v[154:155], v156, off offset:64
	v_mul_f32_e32 v156, v166, v147
	v_mul_f32_e32 v156, v189, v156
	v_cvt_pk_bf16_f32 v156, v156, s0
	global_store_short v[154:155], v156, off offset:128
	v_mul_f32_e32 v156, v167, v147
	v_mul_f32_e32 v156, v190, v156
	v_cvt_pk_bf16_f32 v156, v156, s0
	global_store_short v[154:155], v156, off offset:192
	v_mul_f32_e32 v156, v182, v147
	v_mul_f32_e32 v156, v191, v156
	v_cvt_pk_bf16_f32 v156, v156, s0
	global_store_short v[154:155], v156, off offset:256
	v_mul_f32_e32 v156, v183, v147
	v_mul_f32_e32 v156, v192, v156
	v_cvt_pk_bf16_f32 v156, v156, s0
	v_mul_f32_e32 v163, v188, v163
	global_store_short v[154:155], v156, off offset:320
	v_mul_f32_e32 v156, v186, v147
	v_mul_f32_e32 v147, v187, v147
	v_cvt_pk_bf16_f32 v163, v163, s0
	v_mul_f32_e32 v156, v193, v156
	v_mul_f32_e32 v147, v194, v147
	global_store_short v[158:159], v163, off offset:64
	v_cvt_pk_bf16_f32 v156, v156, s0
	v_cvt_pk_bf16_f32 v147, v147, s0
	v_or_b32_e32 v158, 0x10000, v146
	v_mov_b32_e32 v159, v1
	global_store_short v[154:155], v156, off offset:384
	global_store_short v[154:155], v147, off offset:448
	v_lshl_add_u64 v[160:161], v[150:151], 0, v[158:159]
	global_load_ushort v147, v[160:161], off
	global_load_ushort v180, v[160:161], off offset:64
	global_load_ushort v154, v[160:161], off offset:128
	global_load_ushort v155, v[160:161], off offset:192
	v_mov_b32_e32 v156, v106
	v_mov_b32_e32 v157, v90
	v_pk_mul_f32 v[156:157], v[156:157], v[136:137] op_sel_hi:[1,0]
	v_mov_b32_e32 v164, v74
	v_mov_b32_e32 v165, v58
	v_pk_mul_f32 v[164:165], v[164:165], v[136:137] op_sel_hi:[1,0]
	v_mov_b32_e32 v168, v107
	v_mov_b32_e32 v169, v91
	v_pk_mul_f32 v[168:169], v[168:169], v[178:179] op_sel_hi:[1,0]
	v_lshl_add_u64 v[158:159], v[148:149], 0, v[158:159]
	v_mov_b32_e32 v178, v135
	s_waitcnt vmcnt(1)
; __device__ __forceinline__ bf16_t f2bf(float x) { return (bf16_t)(cvt_pk_bf16(x, x) & 0xffffu); }
; __device__ __forceinline__ float bf2f(bf16_t b) { return __uint_as_float(((unsigned)b) << 16); }
; __device__ __forceinline__ int crow(int r, int hi) { return (r & 3) + 8 * (r >> 2) + 4 * hi; }
; __device__ __forceinline__ int crow(int r, int hi) { return (r & 3) + 8 * (r >> 2) + 4 * hi; }
; __device__ __forceinline__ void attn_body256(const bf16_t* __restrict__ Qb, const bf16_t* __restrict__ Kh, const bf16_t* __restrict__ Vh,
;                                              bf16_t* Ob, int seq, unsigned char* lds, float lam, int MODE, bf16_t* Ab, const float* wsub) {
;     ...
;     bf16_t* Aw = Ab + (long)(wid * QBLK) * LDO;
;     float wv[8];
; #pragma unroll
;     for (int d0 = 0; d0 < 8; ++d0) wv[d0] = wsub[d0 * 32 + r32] * (1.f - LAMBDA_INIT);
; #pragma unroll
;     for (int r = 0; r < 16; ++r) { const int orow = crow(r, hi); float ss = 0.f;
; #pragma unroll
;       for (int d0 = 0; d0 < 8; ++d0) { const float v = bf2f(Ow[(long)orow * LDO + d0 * 32 + r32]) - lam * (o[d0][r] * rli[r]); o[d0][r] = v; ss += v * v; }
;       ss += __shfl_xor(ss, 1, 64); ss += __shfl_xor(ss, 2, 64); ss += __shfl_xor(ss, 4, 64); ss += __shfl_xor(ss, 8, 64); ss += __shfl_xor(ss, 16, 64);
;       const float rstd = rsqrtf(ss * (1.f / 256.f) + NORM_EPS);
; #pragma unroll
;       for (int d0 = 0; d0 < 8; ++d0) Aw[(long)orow * LDO + d0 * 32 + r32] = f2bf(o[d0][r] * rstd * wv[d0]); }
	v_lshlrev_b32_e32 v154, 16, v154
	s_waitcnt vmcnt(0)
	v_lshlrev_b32_e32 v155, 16, v155
	v_pk_fma_f32 v[154:155], v[218:219], v[156:157], v[154:155] neg_lo:[1,0,0] neg_hi:[1,0,0]
	global_load_ushort v156, v[160:161], off offset:256
	global_load_ushort v157, v[160:161], off offset:320
	v_pk_mul_f32 v[162:163], v[154:155], v[154:155]
	s_waitcnt vmcnt(1)
	v_lshlrev_b32_e32 v156, 16, v156
	s_waitcnt vmcnt(0)
	v_lshlrev_b32_e32 v157, 16, v157
	v_pk_fma_f32 v[156:157], v[218:219], v[164:165], v[156:157] neg_lo:[1,0,0] neg_hi:[1,0,0]
	global_load_ushort v164, v[160:161], off offset:384
	s_nop 0
	global_load_ushort v160, v[160:161], off offset:448
	v_mov_b32_e32 v165, v26
	v_mov_b32_e32 v182, v162
	v_pk_mul_f32 v[172:173], v[156:157], v[156:157]
	s_waitcnt vmcnt(0)
	v_lshlrev_b32_e32 v161, 16, v160
	v_lshlrev_b32_e32 v160, 16, v164
	v_mov_b32_e32 v164, v42
	v_pk_mul_f32 v[164:165], v[164:165], v[136:137] op_sel_hi:[1,0]
	s_nop 0
	v_pk_fma_f32 v[160:161], v[218:219], v[164:165], v[160:161] neg_lo:[1,0,0] neg_hi:[1,0,0]
	v_or_b32_e32 v164, 0x11000, v146
	v_mov_b32_e32 v165, v1
	v_lshl_add_u64 v[186:187], v[150:151], 0, v[164:165]
	global_load_ushort v170, v[186:187], off
	global_load_ushort v181, v[186:187], off offset:64
	global_load_ushort v166, v[186:187], off offset:128
	global_load_ushort v167, v[186:187], off offset:192
	v_pk_mul_f32 v[174:175], v[160:161], v[160:161]
	s_waitcnt vmcnt(1)
	v_lshlrev_b32_e32 v166, 16, v166
	s_waitcnt vmcnt(0)
	v_lshlrev_b32_e32 v167, 16, v167
	v_pk_fma_f32 v[166:167], v[218:219], v[168:169], v[166:167] neg_lo:[1,0,0] neg_hi:[1,0,0]
	v_lshlrev_b32_e32 v168, 16, v147
	global_load_ushort v147, v[186:187], off offset:256
	global_load_ushort v162, v[186:187], off offset:320
	v_lshlrev_b32_e32 v169, 16, v170
	v_pk_mul_f32 v[170:171], v[10:11], v[136:137]
	v_pk_mul_f32 v[176:177], v[166:167], v[166:167]
	v_pk_fma_f32 v[168:169], v[218:219], v[170:171], v[168:169] neg_lo:[1,0,0] neg_hi:[1,0,0]
	v_lshlrev_b32_e32 v171, 16, v181
	v_lshlrev_b32_e32 v170, 16, v180
	v_pk_mul_f32 v[180:181], v[122:123], v[136:137]
	v_mov_b32_e32 v183, v176
	v_pk_fma_f32 v[170:171], v[218:219], v[180:181], v[170:171] neg_lo:[1,0,0] neg_hi:[1,0,0]
	s_nop 0
	v_pk_mul_f32 v[180:181], v[170:171], v[170:171]
	s_nop 0
	v_pk_fma_f32 v[180:181], v[168:169], v[168:169], v[180:181]
	s_nop 0
	v_pk_add_f32 v[180:181], v[180:181], v[182:183]
	s_waitcnt vmcnt(1)
	v_lshlrev_b32_e32 v182, 16, v147
	s_waitcnt vmcnt(0)
	v_lshlrev_b32_e32 v183, 16, v162
	global_load_ushort v147, v[186:187], off offset:384
	global_load_ushort v162, v[186:187], off offset:448
	v_pk_fma_f32 v[182:183], v[218:219], v[184:185], v[182:183] neg_lo:[1,0,0] neg_hi:[1,0,0]
	s_waitcnt vmcnt(1)
	v_lshlrev_b32_e32 v186, 16, v147
	v_pk_mul_f32 v[184:185], v[182:183], v[182:183]
	s_waitcnt vmcnt(0)
	v_lshlrev_b32_e32 v187, 16, v162
	v_mov_b32_e32 v162, v177
	v_pk_fma_f32 v[186:187], v[218:219], v[200:201], v[186:187] neg_lo:[1,0,0] neg_hi:[1,0,0]
	v_pk_add_f32 v[162:163], v[180:181], v[162:163] op_sel:[1,0] op_sel_hi:[0,1]
	v_mov_b32_e32 v176, v184
	v_mov_b32_e32 v177, v172
	v_pk_mul_f32 v[200:201], v[186:187], v[186:187]
	v_pk_add_f32 v[162:163], v[162:163], v[176:177]
	v_mov_b32_e32 v172, v185
	v_pk_add_f32 v[162:163], v[162:163], v[172:173]
	v_mov_b32_e32 v172, v200
	v_mov_b32_e32 v173, v174
	v_pk_add_f32 v[162:163], v[162:163], v[172:173]
	v_mov_b32_e32 v174, v201
	v_pk_add_f32 v[162:163], v[162:163], v[174:175]
	ds_bpermute_b32 v173, v199, v163
	ds_bpermute_b32 v172, v199, v162
	v_mov_b32_e32 v184, v77
	v_mov_b32_e32 v185, v61
	v_pk_mul_f32 v[184:185], v[184:185], v[178:179] op_sel_hi:[1,0]
	v_mov_b32_e32 v200, v45
	s_waitcnt lgkmcnt(0)
	v_pk_add_f32 v[162:163], v[162:163], v[172:173]
	ds_bpermute_b32 v173, v198, v163
	ds_bpermute_b32 v172, v198, v162
	v_mov_b32_e32 v201, v29
	v_pk_mul_f32 v[200:201], v[200:201], v[178:179] op_sel_hi:[1,0]
	s_waitcnt lgkmcnt(0)
	v_pk_add_f32 v[162:163], v[162:163], v[172:173]
	ds_bpermute_b32 v173, v197, v163
	ds_bpermute_b32 v172, v197, v162
	s_waitcnt lgkmcnt(0)
	v_pk_add_f32 v[162:163], v[162:163], v[172:173]
	ds_bpermute_b32 v173, v196, v163
	ds_bpermute_b32 v172, v196, v162
	s_waitcnt lgkmcnt(0)
	v_pk_add_f32 v[162:163], v[162:163], v[172:173]
	ds_bpermute_b32 v173, v195, v163
	ds_bpermute_b32 v172, v195, v162
	s_waitcnt lgkmcnt(0)
; __device__ __forceinline__ bf16_t f2bf(float x) { return (bf16_t)(cvt_pk_bf16(x, x) & 0xffffu); }
; __device__ __forceinline__ float bf2f(bf16_t b) { return __uint_as_float(((unsigned)b) << 16); }
; __device__ __forceinline__ int crow(int r, int hi) { return (r & 3) + 8 * (r >> 2) + 4 * hi; }
; __device__ __forceinline__ int crow(int r, int hi) { return (r & 3) + 8 * (r >> 2) + 4 * hi; }
; __device__ __forceinline__ void attn_body256(const bf16_t* __restrict__ Qb, const bf16_t* __restrict__ Kh, const bf16_t* __restrict__ Vh,
;                                              bf16_t* Ob, int seq, unsigned char* lds, float lam, int MODE, bf16_t* Ab, const float* wsub) {
;     ...
;     bf16_t* Aw = Ab + (long)(wid * QBLK) * LDO;
;     float wv[8];
; #pragma unroll
;     for (int d0 = 0; d0 < 8; ++d0) wv[d0] = wsub[d0 * 32 + r32] * (1.f - LAMBDA_INIT);
; #pragma unroll
;     for (int r = 0; r < 16; ++r) { const int orow = crow(r, hi); float ss = 0.f;
; #pragma unroll
;       for (int d0 = 0; d0 < 8; ++d0) { const float v = bf2f(Ow[(long)orow * LDO + d0 * 32 + r32]) - lam * (o[d0][r] * rli[r]); o[d0][r] = v; ss += v * v; }
;       ss += __shfl_xor(ss, 1, 64); ss += __shfl_xor(ss, 2, 64); ss += __shfl_xor(ss, 4, 64); ss += __shfl_xor(ss, 8, 64); ss += __shfl_xor(ss, 16, 64);
;       const float rstd = rsqrtf(ss * (1.f / 256.f) + NORM_EPS);
; #pragma unroll
;       for (int d0 = 0; d0 < 8; ++d0) Aw[(long)orow * LDO + d0 * 32 + r32] = f2bf(o[d0][r] * rstd * wv[d0]); }
	v_pk_add_f32 v[162:163], v[162:163], v[172:173]
	s_nop 0
	v_pk_fma_f32 v[162:163], v[162:163], s[2:3], v[152:153] op_sel_hi:[1,0,0]
	s_nop 0
	v_mul_f32_e32 v147, 0x4b800000, v163
	v_cmp_gt_f32_e64 s[0:1], s58, v163
	v_cmp_gt_f32_e32 vcc, s58, v162
	s_nop 0
	v_cndmask_b32_e64 v147, v163, v147, s[0:1]
	v_rsq_f32_e32 v147, v147
	s_nop 0
	v_mul_f32_e32 v163, 0x45800000, v147
	v_cndmask_b32_e64 v147, v147, v163, s[0:1]
	v_mul_f32_e32 v154, v154, v147
	v_mul_f32_e32 v154, v189, v154
	v_cvt_pk_bf16_f32 v154, v154, s0
	global_store_short v[158:159], v154, off offset:128
	v_mul_f32_e32 v154, v155, v147
	v_mul_f32_e32 v154, v190, v154
	v_cvt_pk_bf16_f32 v154, v154, s0
	global_store_short v[158:159], v154, off offset:192
	v_mul_f32_e32 v154, v156, v147
	v_mul_f32_e32 v154, v191, v154
	v_cvt_pk_bf16_f32 v154, v154, s0
	v_mul_f32_e32 v163, v168, v147
	global_store_short v[158:159], v154, off offset:256
	v_mul_f32_e32 v154, v157, v147
	v_mul_f32_e32 v163, v179, v163
	v_mul_f32_e32 v154, v192, v154
	v_cvt_pk_bf16_f32 v163, v163, s0
	v_cvt_pk_bf16_f32 v154, v154, s0
	global_store_short v[158:159], v163, off
	v_mul_f32_e32 v163, v170, v147
	global_store_short v[158:159], v154, off offset:320
	v_mul_f32_e32 v154, v160, v147
	v_mul_f32_e32 v147, v161, v147
	v_mul_f32_e32 v147, v194, v147
	v_cvt_pk_bf16_f32 v147, v147, s0
	global_store_short v[158:159], v147, off offset:448
	v_mul_f32_e32 v147, 0x4b800000, v162
	v_cndmask_b32_e32 v147, v162, v147, vcc
	v_rsq_f32_e32 v147, v147
	v_mul_f32_e32 v154, v193, v154
	v_cvt_pk_bf16_f32 v154, v154, s0
	global_store_short v[158:159], v154, off offset:384
	v_mul_f32_e32 v154, 0x45800000, v147
	v_cndmask_b32_e32 v147, v147, v154, vcc
	v_mul_f32_e32 v156, v169, v147
	v_mul_f32_e32 v156, v179, v156
	v_lshl_add_u64 v[154:155], v[148:149], 0, v[164:165]
	v_cvt_pk_bf16_f32 v156, v156, s0
	global_store_short v[154:155], v156, off
	v_mul_f32_e32 v156, v171, v147
	v_mul_f32_e32 v156, v188, v156
	v_cvt_pk_bf16_f32 v156, v156, s0
	global_store_short v[154:155], v156, off offset:64
	v_mul_f32_e32 v156, v166, v147
	v_mul_f32_e32 v156, v189, v156
	v_cvt_pk_bf16_f32 v156, v156, s0
	global_store_short v[154:155], v156, off offset:128
	v_mul_f32_e32 v156, v167, v147
	v_mul_f32_e32 v156, v190, v156
	v_cvt_pk_bf16_f32 v156, v156, s0
	global_store_short v[154:155], v156, off offset:192
	v_mul_f32_e32 v156, v182, v147
	v_mul_f32_e32 v156, v191, v156
	v_cvt_pk_bf16_f32 v156, v156, s0
	global_store_short v[154:155], v156, off offset:256
	v_mul_f32_e32 v156, v183, v147
	v_mul_f32_e32 v156, v192, v156
	v_cvt_pk_bf16_f32 v156, v156, s0
	v_mul_f32_e32 v163, v188, v163
	global_store_short v[154:155], v156, off offset:320
	v_mul_f32_e32 v156, v186, v147
	v_mul_f32_e32 v147, v187, v147
	v_cvt_pk_bf16_f32 v163, v163, s0
	v_mul_f32_e32 v156, v193, v156
	v_mul_f32_e32 v147, v194, v147
	global_store_short v[158:159], v163, off offset:64
	v_cvt_pk_bf16_f32 v156, v156, s0
	v_cvt_pk_bf16_f32 v147, v147, s0
	v_or_b32_e32 v158, 0x12000, v146
	v_mov_b32_e32 v159, v1
	global_store_short v[154:155], v156, off offset:384
	global_store_short v[154:155], v147, off offset:448
	v_lshl_add_u64 v[160:161], v[150:151], 0, v[158:159]
	global_load_ushort v147, v[160:161], off
	global_load_ushort v180, v[160:161], off offset:64
	global_load_ushort v154, v[160:161], off offset:128
	global_load_ushort v155, v[160:161], off offset:192
	v_mov_b32_e32 v156, v108
	v_mov_b32_e32 v157, v92
	v_pk_mul_f32 v[156:157], v[156:157], v[134:135] op_sel_hi:[1,0]
	v_mov_b32_e32 v164, v76
	v_mov_b32_e32 v165, v60
	v_pk_mul_f32 v[164:165], v[164:165], v[134:135] op_sel_hi:[1,0]
	v_mov_b32_e32 v168, v109
	v_mov_b32_e32 v169, v93
	v_pk_mul_f32 v[168:169], v[168:169], v[178:179] op_sel_hi:[1,0]
	v_lshl_add_u64 v[158:159], v[148:149], 0, v[158:159]
	v_mov_b32_e32 v178, v133
	s_waitcnt vmcnt(1)
	v_lshlrev_b32_e32 v154, 16, v154
	s_waitcnt vmcnt(0)
	v_lshlrev_b32_e32 v155, 16, v155
	v_pk_fma_f32 v[154:155], v[218:219], v[156:157], v[154:155] neg_lo:[1,0,0] neg_hi:[1,0,0]
	global_load_ushort v156, v[160:161], off offset:256
	global_load_ushort v157, v[160:161], off offset:320
	v_pk_mul_f32 v[162:163], v[154:155], v[154:155]
	s_waitcnt vmcnt(1)
	v_lshlrev_b32_e32 v156, 16, v156
	s_waitcnt vmcnt(0)
	v_lshlrev_b32_e32 v157, 16, v157
	v_pk_fma_f32 v[156:157], v[218:219], v[164:165], v[156:157] neg_lo:[1,0,0] neg_hi:[1,0,0]
	global_load_ushort v164, v[160:161], off offset:384
	s_nop 0
	global_load_ushort v160, v[160:161], off offset:448
	v_mov_b32_e32 v165, v28
	v_mov_b32_e32 v182, v162
	v_pk_mul_f32 v[172:173], v[156:157], v[156:157]
	s_waitcnt vmcnt(0)
	v_lshlrev_b32_e32 v161, 16, v160
	v_lshlrev_b32_e32 v160, 16, v164
	v_mov_b32_e32 v164, v44
	v_pk_mul_f32 v[164:165], v[164:165], v[134:135] op_sel_hi:[1,0]
	s_nop 0
	v_pk_fma_f32 v[160:161], v[218:219], v[164:165], v[160:161] neg_lo:[1,0,0] neg_hi:[1,0,0]
	v_or_b32_e32 v164, 0x13000, v146
	v_mov_b32_e32 v165, v1
	v_lshl_add_u64 v[186:187], v[150:151], 0, v[164:165]
	global_load_ushort v170, v[186:187], off
	global_load_ushort v181, v[186:187], off offset:64
	global_load_ushort v166, v[186:187], off offset:128
	global_load_ushort v167, v[186:187], off offset:192
	v_pk_mul_f32 v[174:175], v[160:161], v[160:161]
	s_waitcnt vmcnt(1)
	v_lshlrev_b32_e32 v166, 16, v166
	s_waitcnt vmcnt(0)
; __device__ __forceinline__ bf16_t f2bf(float x) { return (bf16_t)(cvt_pk_bf16(x, x) & 0xffffu); }
; __device__ __forceinline__ float bf2f(bf16_t b) { return __uint_as_float(((unsigned)b) << 16); }
; __device__ __forceinline__ int crow(int r, int hi) { return (r & 3) + 8 * (r >> 2) + 4 * hi; }
; __device__ __forceinline__ int crow(int r, int hi) { return (r & 3) + 8 * (r >> 2) + 4 * hi; }
; __device__ __forceinline__ void attn_body256(const bf16_t* __restrict__ Qb, const bf16_t* __restrict__ Kh, const bf16_t* __restrict__ Vh,
;                                              bf16_t* Ob, int seq, unsigned char* lds, float lam, int MODE, bf16_t* Ab, const float* wsub) {
;     ...
;     bf16_t* Aw = Ab + (long)(wid * QBLK) * LDO;
;     float wv[8];
; #pragma unroll
;     for (int d0 = 0; d0 < 8; ++d0) wv[d0] = wsub[d0 * 32 + r32] * (1.f - LAMBDA_INIT);
; #pragma unroll
;     for (int r = 0; r < 16; ++r) { const int orow = crow(r, hi); float ss = 0.f;
; #pragma unroll
;       for (int d0 = 0; d0 < 8; ++d0) { const float v = bf2f(Ow[(long)orow * LDO + d0 * 32 + r32]) - lam * (o[d0][r] * rli[r]); o[d0][r] = v; ss += v * v; }
;       ss += __shfl_xor(ss, 1, 64); ss += __shfl_xor(ss, 2, 64); ss += __shfl_xor(ss, 4, 64); ss += __shfl_xor(ss, 8, 64); ss += __shfl_xor(ss, 16, 64);
;       const float rstd = rsqrtf(ss * (1.f / 256.f) + NORM_EPS);
; #pragma unroll
;       for (int d0 = 0; d0 < 8; ++d0) Aw[(long)orow * LDO + d0 * 32 + r32] = f2bf(o[d0][r] * rstd * wv[d0]); }
	v_lshlrev_b32_e32 v167, 16, v167
	v_pk_fma_f32 v[166:167], v[218:219], v[168:169], v[166:167] neg_lo:[1,0,0] neg_hi:[1,0,0]
	v_lshlrev_b32_e32 v168, 16, v147
	global_load_ushort v147, v[186:187], off offset:256
	global_load_ushort v162, v[186:187], off offset:320
	v_lshlrev_b32_e32 v169, 16, v170
	v_pk_mul_f32 v[170:171], v[12:13], v[134:135]
	v_pk_mul_f32 v[176:177], v[166:167], v[166:167]
	v_pk_fma_f32 v[168:169], v[218:219], v[170:171], v[168:169] neg_lo:[1,0,0] neg_hi:[1,0,0]
	v_lshlrev_b32_e32 v171, 16, v181
	v_lshlrev_b32_e32 v170, 16, v180
	v_pk_mul_f32 v[180:181], v[124:125], v[134:135]
	v_mov_b32_e32 v183, v176
	v_pk_fma_f32 v[170:171], v[218:219], v[180:181], v[170:171] neg_lo:[1,0,0] neg_hi:[1,0,0]
	s_nop 0
	v_pk_mul_f32 v[180:181], v[170:171], v[170:171]
	s_nop 0
	v_pk_fma_f32 v[180:181], v[168:169], v[168:169], v[180:181]
	s_nop 0
	v_pk_add_f32 v[180:181], v[180:181], v[182:183]
	s_waitcnt vmcnt(1)
	v_lshlrev_b32_e32 v182, 16, v147
	s_waitcnt vmcnt(0)
	v_lshlrev_b32_e32 v183, 16, v162
	global_load_ushort v147, v[186:187], off offset:384
	global_load_ushort v162, v[186:187], off offset:448
	v_pk_fma_f32 v[182:183], v[218:219], v[184:185], v[182:183] neg_lo:[1,0,0] neg_hi:[1,0,0]
	s_waitcnt vmcnt(1)
	v_lshlrev_b32_e32 v186, 16, v147
	v_pk_mul_f32 v[184:185], v[182:183], v[182:183]
	s_waitcnt vmcnt(0)
	v_lshlrev_b32_e32 v187, 16, v162
	v_mov_b32_e32 v162, v177
	v_pk_fma_f32 v[186:187], v[218:219], v[200:201], v[186:187] neg_lo:[1,0,0] neg_hi:[1,0,0]
	v_pk_add_f32 v[162:163], v[180:181], v[162:163] op_sel:[1,0] op_sel_hi:[0,1]
	v_mov_b32_e32 v176, v184
	v_mov_b32_e32 v177, v172
	v_pk_mul_f32 v[200:201], v[186:187], v[186:187]
	v_pk_add_f32 v[162:163], v[162:163], v[176:177]
	v_mov_b32_e32 v172, v185
	v_pk_add_f32 v[162:163], v[162:163], v[172:173]
	v_mov_b32_e32 v172, v200
	v_mov_b32_e32 v173, v174
	v_pk_add_f32 v[162:163], v[162:163], v[172:173]
	v_mov_b32_e32 v174, v201
	v_pk_add_f32 v[162:163], v[162:163], v[174:175]
	ds_bpermute_b32 v173, v199, v163
	ds_bpermute_b32 v172, v199, v162
	v_mov_b32_e32 v184, v79
	v_mov_b32_e32 v185, v63
	v_pk_mul_f32 v[184:185], v[184:185], v[178:179] op_sel_hi:[1,0]
	v_mov_b32_e32 v200, v47
	s_waitcnt lgkmcnt(0)
	v_pk_add_f32 v[162:163], v[162:163], v[172:173]
	ds_bpermute_b32 v173, v198, v163
	ds_bpermute_b32 v172, v198, v162
	v_mov_b32_e32 v201, v31
	v_pk_mul_f32 v[200:201], v[200:201], v[178:179] op_sel_hi:[1,0]
	s_waitcnt lgkmcnt(0)
	v_pk_add_f32 v[162:163], v[162:163], v[172:173]
	ds_bpermute_b32 v173, v197, v163
	ds_bpermute_b32 v172, v197, v162
	s_waitcnt lgkmcnt(0)
	v_pk_add_f32 v[162:163], v[162:163], v[172:173]
	ds_bpermute_b32 v173, v196, v163
	ds_bpermute_b32 v172, v196, v162
	s_waitcnt lgkmcnt(0)
	v_pk_add_f32 v[162:163], v[162:163], v[172:173]
	ds_bpermute_b32 v173, v195, v163
	ds_bpermute_b32 v172, v195, v162
	s_waitcnt lgkmcnt(0)
	v_pk_add_f32 v[162:163], v[162:163], v[172:173]
	s_nop 0
	v_pk_fma_f32 v[162:163], v[162:163], s[2:3], v[152:153] op_sel_hi:[1,0,0]
	s_nop 0
	v_mul_f32_e32 v147, 0x4b800000, v163
	v_cmp_gt_f32_e64 s[0:1], s58, v163
	v_cmp_gt_f32_e32 vcc, s58, v162
	s_nop 0
	v_cndmask_b32_e64 v147, v163, v147, s[0:1]
	v_rsq_f32_e32 v147, v147
	s_nop 0
	v_mul_f32_e32 v163, 0x45800000, v147
	v_cndmask_b32_e64 v147, v147, v163, s[0:1]
	v_mul_f32_e32 v154, v154, v147
	v_mul_f32_e32 v154, v189, v154
	v_cvt_pk_bf16_f32 v154, v154, s0
	global_store_short v[158:159], v154, off offset:128
	v_mul_f32_e32 v154, v155, v147
	v_mul_f32_e32 v154, v190, v154
	v_cvt_pk_bf16_f32 v154, v154, s0
	global_store_short v[158:159], v154, off offset:192
	v_mul_f32_e32 v154, v156, v147
	v_mul_f32_e32 v154, v191, v154
	v_cvt_pk_bf16_f32 v154, v154, s0
	v_mul_f32_e32 v163, v168, v147
	global_store_short v[158:159], v154, off offset:256
	v_mul_f32_e32 v154, v157, v147
	v_mul_f32_e32 v163, v179, v163
	v_mul_f32_e32 v154, v192, v154
	v_cvt_pk_bf16_f32 v163, v163, s0
	v_cvt_pk_bf16_f32 v154, v154, s0
	global_store_short v[158:159], v163, off
	v_mul_f32_e32 v163, v170, v147
	global_store_short v[158:159], v154, off offset:320
	v_mul_f32_e32 v154, v160, v147
	v_mul_f32_e32 v147, v161, v147
	v_mul_f32_e32 v147, v194, v147
	v_cvt_pk_bf16_f32 v147, v147, s0
	global_store_short v[158:159], v147, off offset:448
	v_mul_f32_e32 v147, 0x4b800000, v162
	v_cndmask_b32_e32 v147, v162, v147, vcc
	v_rsq_f32_e32 v147, v147
	v_mul_f32_e32 v154, v193, v154
	v_cvt_pk_bf16_f32 v154, v154, s0
	global_store_short v[158:159], v154, off offset:384
	v_mul_f32_e32 v154, 0x45800000, v147
	v_cndmask_b32_e32 v147, v147, v154, vcc
	v_mul_f32_e32 v156, v169, v147
	v_mul_f32_e32 v156, v179, v156
	v_lshl_add_u64 v[154:155], v[148:149], 0, v[164:165]
	v_cvt_pk_bf16_f32 v156, v156, s0
	global_store_short v[154:155], v156, off
	v_mul_f32_e32 v156, v171, v147
	v_mul_f32_e32 v156, v188, v156
	v_cvt_pk_bf16_f32 v156, v156, s0
	global_store_short v[154:155], v156, off offset:64
	v_mul_f32_e32 v156, v166, v147
	v_mul_f32_e32 v156, v189, v156
	v_cvt_pk_bf16_f32 v156, v156, s0
	global_store_short v[154:155], v156, off offset:128
	v_mul_f32_e32 v156, v167, v147
	v_mul_f32_e32 v156, v190, v156
	v_cvt_pk_bf16_f32 v156, v156, s0
	global_store_short v[154:155], v156, off offset:192
	v_mul_f32_e32 v156, v182, v147
	v_mul_f32_e32 v156, v191, v156
	v_cvt_pk_bf16_f32 v156, v156, s0
	global_store_short v[154:155], v156, off offset:256
	v_mul_f32_e32 v156, v183, v147
	v_mul_f32_e32 v156, v192, v156
	v_cvt_pk_bf16_f32 v156, v156, s0
	v_mul_f32_e32 v163, v188, v163
	global_store_short v[154:155], v156, off offset:320
	v_mul_f32_e32 v156, v186, v147
	v_mul_f32_e32 v147, v187, v147
	v_cvt_pk_bf16_f32 v163, v163, s0
	v_mul_f32_e32 v156, v193, v156
	v_mul_f32_e32 v147, v194, v147
	global_store_short v[158:159], v163, off offset:64
	v_cvt_pk_bf16_f32 v156, v156, s0
	v_cvt_pk_bf16_f32 v147, v147, s0
	v_or_b32_e32 v158, 0x18000, v146
	v_mov_b32_e32 v159, v1
	global_store_short v[154:155], v156, off offset:384
	global_store_short v[154:155], v147, off offset:448
	v_lshl_add_u64 v[160:161], v[150:151], 0, v[158:159]
	global_load_ushort v147, v[160:161], off
	global_load_ushort v180, v[160:161], off offset:64
	global_load_ushort v154, v[160:161], off offset:128
	global_load_ushort v155, v[160:161], off offset:192
	v_mov_b32_e32 v156, v110
	v_mov_b32_e32 v157, v94
	v_pk_mul_f32 v[156:157], v[156:157], v[132:133] op_sel_hi:[1,0]
	v_mov_b32_e32 v164, v78
	v_mov_b32_e32 v165, v62
	v_pk_mul_f32 v[164:165], v[164:165], v[132:133] op_sel_hi:[1,0]
	v_mov_b32_e32 v168, v111
	v_mov_b32_e32 v169, v95
	v_pk_mul_f32 v[168:169], v[168:169], v[178:179] op_sel_hi:[1,0]
	v_lshl_add_u64 v[158:159], v[148:149], 0, v[158:159]
	v_mov_b32_e32 v178, v131
	s_waitcnt vmcnt(1)
; __device__ __forceinline__ bf16_t f2bf(float x) { return (bf16_t)(cvt_pk_bf16(x, x) & 0xffffu); }
; __device__ __forceinline__ float bf2f(bf16_t b) { return __uint_as_float(((unsigned)b) << 16); }
; __device__ __forceinline__ int crow(int r, int hi) { return (r & 3) + 8 * (r >> 2) + 4 * hi; }
; __device__ __forceinline__ int crow(int r, int hi) { return (r & 3) + 8 * (r >> 2) + 4 * hi; }
; __device__ __forceinline__ void attn_body256(const bf16_t* __restrict__ Qb, const bf16_t* __restrict__ Kh, const bf16_t* __restrict__ Vh,
;                                              bf16_t* Ob, int seq, unsigned char* lds, float lam, int MODE, bf16_t* Ab, const float* wsub) {
;     ...
;     bf16_t* Aw = Ab + (long)(wid * QBLK) * LDO;
;     float wv[8];
; #pragma unroll
;     for (int d0 = 0; d0 < 8; ++d0) wv[d0] = wsub[d0 * 32 + r32] * (1.f - LAMBDA_INIT);
; #pragma unroll
;     for (int r = 0; r < 16; ++r) { const int orow = crow(r, hi); float ss = 0.f;
; #pragma unroll
;       for (int d0 = 0; d0 < 8; ++d0) { const float v = bf2f(Ow[(long)orow * LDO + d0 * 32 + r32]) - lam * (o[d0][r] * rli[r]); o[d0][r] = v; ss += v * v; }
;       ss += __shfl_xor(ss, 1, 64); ss += __shfl_xor(ss, 2, 64); ss += __shfl_xor(ss, 4, 64); ss += __shfl_xor(ss, 8, 64); ss += __shfl_xor(ss, 16, 64);
;       const float rstd = rsqrtf(ss * (1.f / 256.f) + NORM_EPS);
; #pragma unroll
;       for (int d0 = 0; d0 < 8; ++d0) Aw[(long)orow * LDO + d0 * 32 + r32] = f2bf(o[d0][r] * rstd * wv[d0]); }
	v_lshlrev_b32_e32 v154, 16, v154
	s_waitcnt vmcnt(0)
	v_lshlrev_b32_e32 v155, 16, v155
	v_pk_fma_f32 v[154:155], v[218:219], v[156:157], v[154:155] neg_lo:[1,0,0] neg_hi:[1,0,0]
	global_load_ushort v156, v[160:161], off offset:256
	global_load_ushort v157, v[160:161], off offset:320
	v_pk_mul_f32 v[162:163], v[154:155], v[154:155]
	s_waitcnt vmcnt(1)
	v_lshlrev_b32_e32 v156, 16, v156
	s_waitcnt vmcnt(0)
	v_lshlrev_b32_e32 v157, 16, v157
	v_pk_fma_f32 v[156:157], v[218:219], v[164:165], v[156:157] neg_lo:[1,0,0] neg_hi:[1,0,0]
	global_load_ushort v164, v[160:161], off offset:384
	s_nop 0
	global_load_ushort v160, v[160:161], off offset:448
	v_mov_b32_e32 v165, v30
	v_mov_b32_e32 v182, v162
	v_pk_mul_f32 v[172:173], v[156:157], v[156:157]
	s_waitcnt vmcnt(0)
	v_lshlrev_b32_e32 v161, 16, v160
	v_lshlrev_b32_e32 v160, 16, v164
	v_mov_b32_e32 v164, v46
	v_pk_mul_f32 v[164:165], v[164:165], v[132:133] op_sel_hi:[1,0]
	s_nop 0
	v_pk_fma_f32 v[160:161], v[218:219], v[164:165], v[160:161] neg_lo:[1,0,0] neg_hi:[1,0,0]
	v_or_b32_e32 v164, 0x19000, v146
	v_mov_b32_e32 v165, v1
	v_lshl_add_u64 v[186:187], v[150:151], 0, v[164:165]
	global_load_ushort v170, v[186:187], off
	global_load_ushort v181, v[186:187], off offset:64
	global_load_ushort v166, v[186:187], off offset:128
	global_load_ushort v167, v[186:187], off offset:192
	v_pk_mul_f32 v[174:175], v[160:161], v[160:161]
	s_waitcnt vmcnt(1)
	v_lshlrev_b32_e32 v166, 16, v166
	s_waitcnt vmcnt(0)
	v_lshlrev_b32_e32 v167, 16, v167
	v_pk_fma_f32 v[166:167], v[218:219], v[168:169], v[166:167] neg_lo:[1,0,0] neg_hi:[1,0,0]
	v_lshlrev_b32_e32 v168, 16, v147
	global_load_ushort v147, v[186:187], off offset:256
	global_load_ushort v162, v[186:187], off offset:320
	v_lshlrev_b32_e32 v169, 16, v170
	v_pk_mul_f32 v[170:171], v[14:15], v[132:133]
	v_pk_mul_f32 v[176:177], v[166:167], v[166:167]
	v_pk_fma_f32 v[168:169], v[218:219], v[170:171], v[168:169] neg_lo:[1,0,0] neg_hi:[1,0,0]
	v_lshlrev_b32_e32 v171, 16, v181
	v_lshlrev_b32_e32 v170, 16, v180
	v_pk_mul_f32 v[180:181], v[126:127], v[132:133]
	v_mov_b32_e32 v183, v176
	v_pk_fma_f32 v[170:171], v[218:219], v[180:181], v[170:171] neg_lo:[1,0,0] neg_hi:[1,0,0]
	s_nop 0
	v_pk_mul_f32 v[180:181], v[170:171], v[170:171]
	s_nop 0
	v_pk_fma_f32 v[180:181], v[168:169], v[168:169], v[180:181]
	s_nop 0
	v_pk_add_f32 v[180:181], v[180:181], v[182:183]
	s_waitcnt vmcnt(1)
	v_lshlrev_b32_e32 v182, 16, v147
	s_waitcnt vmcnt(0)
	v_lshlrev_b32_e32 v183, 16, v162
	global_load_ushort v147, v[186:187], off offset:384
	global_load_ushort v162, v[186:187], off offset:448
	v_pk_fma_f32 v[182:183], v[218:219], v[184:185], v[182:183] neg_lo:[1,0,0] neg_hi:[1,0,0]
	s_waitcnt vmcnt(1)
	v_lshlrev_b32_e32 v186, 16, v147
	v_pk_mul_f32 v[184:185], v[182:183], v[182:183]
	s_waitcnt vmcnt(0)
	v_lshlrev_b32_e32 v187, 16, v162
	v_mov_b32_e32 v162, v177
	v_pk_fma_f32 v[186:187], v[218:219], v[200:201], v[186:187] neg_lo:[1,0,0] neg_hi:[1,0,0]
	v_pk_add_f32 v[162:163], v[180:181], v[162:163] op_sel:[1,0] op_sel_hi:[0,1]
	v_mov_b32_e32 v176, v184
	v_mov_b32_e32 v177, v172
	v_pk_mul_f32 v[200:201], v[186:187], v[186:187]
	v_pk_add_f32 v[162:163], v[162:163], v[176:177]
	v_mov_b32_e32 v172, v185
	v_pk_add_f32 v[162:163], v[162:163], v[172:173]
	v_mov_b32_e32 v172, v200
	v_mov_b32_e32 v173, v174
	v_pk_add_f32 v[162:163], v[162:163], v[172:173]
	v_mov_b32_e32 v174, v201
	v_pk_add_f32 v[162:163], v[162:163], v[174:175]
	ds_bpermute_b32 v173, v199, v163
	ds_bpermute_b32 v172, v199, v162
	s_waitcnt lgkmcnt(0)
	v_pk_add_f32 v[162:163], v[162:163], v[172:173]
	ds_bpermute_b32 v173, v198, v163
	ds_bpermute_b32 v172, v198, v162
	s_waitcnt lgkmcnt(0)
	v_pk_add_f32 v[162:163], v[162:163], v[172:173]
	ds_bpermute_b32 v173, v197, v163
	ds_bpermute_b32 v172, v197, v162
	s_waitcnt lgkmcnt(0)
	v_pk_add_f32 v[162:163], v[162:163], v[172:173]
	ds_bpermute_b32 v173, v196, v163
	ds_bpermute_b32 v172, v196, v162
	s_waitcnt lgkmcnt(0)
	v_pk_add_f32 v[162:163], v[162:163], v[172:173]
	ds_bpermute_b32 v173, v195, v163
	ds_bpermute_b32 v172, v195, v162
	s_waitcnt lgkmcnt(0)
	v_pk_add_f32 v[162:163], v[162:163], v[172:173]
	s_nop 0
	v_pk_fma_f32 v[162:163], v[162:163], s[2:3], v[152:153] op_sel_hi:[1,0,0]
	s_nop 0
	v_mul_f32_e32 v147, 0x4b800000, v163
	v_cmp_gt_f32_e64 s[0:1], s58, v163
	v_cmp_gt_f32_e32 vcc, s58, v162
	s_nop 0
	v_cndmask_b32_e64 v147, v163, v147, s[0:1]
	v_rsq_f32_e32 v147, v147
	s_nop 0
	v_mul_f32_e32 v163, 0x45800000, v147
	v_cndmask_b32_e64 v147, v147, v163, s[0:1]
	v_mul_f32_e32 v154, v154, v147
	v_mul_f32_e32 v154, v189, v154
	v_cvt_pk_bf16_f32 v154, v154, s0
	global_store_short v[158:159], v154, off offset:128
	v_mul_f32_e32 v154, v155, v147
	v_mul_f32_e32 v154, v190, v154
	v_cvt_pk_bf16_f32 v154, v154, s0
	global_store_short v[158:159], v154, off offset:192
	v_mul_f32_e32 v154, v156, v147
	v_mul_f32_e32 v154, v191, v154
	v_cvt_pk_bf16_f32 v154, v154, s0
	v_mul_f32_e32 v163, v168, v147
	global_store_short v[158:159], v154, off offset:256
	v_mul_f32_e32 v154, v157, v147
	v_mul_f32_e32 v163, v179, v163
	v_mul_f32_e32 v154, v192, v154
	v_cvt_pk_bf16_f32 v163, v163, s0
	v_cvt_pk_bf16_f32 v154, v154, s0
	global_store_short v[158:159], v163, off
	v_mul_f32_e32 v163, v170, v147
	global_store_short v[158:159], v154, off offset:320
	v_mul_f32_e32 v154, v160, v147
	v_mul_f32_e32 v147, v161, v147
	v_mul_f32_e32 v147, v194, v147
	v_cvt_pk_bf16_f32 v147, v147, s0
	global_store_short v[158:159], v147, off offset:448
	v_mul_f32_e32 v147, 0x4b800000, v162
	v_cndmask_b32_e32 v147, v162, v147, vcc
	v_rsq_f32_e32 v147, v147
	v_mul_f32_e32 v154, v193, v154
	v_cvt_pk_bf16_f32 v154, v154, s0
; __device__ __forceinline__ bf16_t f2bf(float x) { return (bf16_t)(cvt_pk_bf16(x, x) & 0xffffu); }
; __device__ __forceinline__ float bf2f(bf16_t b) { return __uint_as_float(((unsigned)b) << 16); }
; __device__ __forceinline__ int crow(int r, int hi) { return (r & 3) + 8 * (r >> 2) + 4 * hi; }
; __device__ __forceinline__ int crow(int r, int hi) { return (r & 3) + 8 * (r >> 2) + 4 * hi; }
; __device__ __forceinline__ void attn_body256(const bf16_t* __restrict__ Qb, const bf16_t* __restrict__ Kh, const bf16_t* __restrict__ Vh,
;                                              bf16_t* Ob, int seq, unsigned char* lds, float lam, int MODE, bf16_t* Ab, const float* wsub) {
;     ...
;     bf16_t* Aw = Ab + (long)(wid * QBLK) * LDO;
;     float wv[8];
; #pragma unroll
;     for (int d0 = 0; d0 < 8; ++d0) wv[d0] = wsub[d0 * 32 + r32] * (1.f - LAMBDA_INIT);
; #pragma unroll
;     for (int r = 0; r < 16; ++r) { const int orow = crow(r, hi); float ss = 0.f;
; #pragma unroll
;       for (int d0 = 0; d0 < 8; ++d0) { const float v = bf2f(Ow[(long)orow * LDO + d0 * 32 + r32]) - lam * (o[d0][r] * rli[r]); o[d0][r] = v; ss += v * v; }
;       ss += __shfl_xor(ss, 1, 64); ss += __shfl_xor(ss, 2, 64); ss += __shfl_xor(ss, 4, 64); ss += __shfl_xor(ss, 8, 64); ss += __shfl_xor(ss, 16, 64);
;       const float rstd = rsqrtf(ss * (1.f / 256.f) + NORM_EPS);
; #pragma unroll
;       for (int d0 = 0; d0 < 8; ++d0) Aw[(long)orow * LDO + d0 * 32 + r32] = f2bf(o[d0][r] * rstd * wv[d0]); }
	global_store_short v[158:159], v154, off offset:384
	v_mul_f32_e32 v154, 0x45800000, v147
	v_cndmask_b32_e32 v147, v147, v154, vcc
	v_mul_f32_e32 v156, v169, v147
	v_mul_f32_e32 v156, v179, v156
	v_lshl_add_u64 v[154:155], v[148:149], 0, v[164:165]
	v_cvt_pk_bf16_f32 v156, v156, s0
	global_store_short v[154:155], v156, off
	v_mul_f32_e32 v156, v171, v147
	v_mul_f32_e32 v156, v188, v156
	v_cvt_pk_bf16_f32 v156, v156, s0
	global_store_short v[154:155], v156, off offset:64
	v_mul_f32_e32 v156, v166, v147
	v_mul_f32_e32 v156, v189, v156
	v_cvt_pk_bf16_f32 v156, v156, s0
	global_store_short v[154:155], v156, off offset:128
	v_mul_f32_e32 v156, v167, v147
	v_mul_f32_e32 v156, v190, v156
	v_cvt_pk_bf16_f32 v156, v156, s0
	global_store_short v[154:155], v156, off offset:192
	v_mul_f32_e32 v156, v182, v147
	v_mul_f32_e32 v156, v191, v156
	v_cvt_pk_bf16_f32 v156, v156, s0
	global_store_short v[154:155], v156, off offset:256
	v_mul_f32_e32 v156, v183, v147
	v_mul_f32_e32 v156, v192, v156
	v_cvt_pk_bf16_f32 v156, v156, s0
	v_mul_f32_e32 v163, v188, v163
	global_store_short v[154:155], v156, off offset:320
	v_mul_f32_e32 v156, v186, v147
	v_mul_f32_e32 v147, v187, v147
	v_cvt_pk_bf16_f32 v163, v163, s0
	v_mul_f32_e32 v156, v193, v156
	v_mul_f32_e32 v147, v194, v147
	global_store_short v[158:159], v163, off offset:64
	v_cvt_pk_bf16_f32 v156, v156, s0
	v_cvt_pk_bf16_f32 v147, v147, s0
	v_or_b32_e32 v158, 0x1a000, v146
	v_mov_b32_e32 v159, v1
	global_store_short v[154:155], v156, off offset:384
	global_store_short v[154:155], v147, off offset:448
	v_lshl_add_u64 v[160:161], v[150:151], 0, v[158:159]
	global_load_ushort v147, v[160:161], off
	global_load_ushort v174, v[160:161], off offset:64
	global_load_ushort v154, v[160:161], off offset:128
	global_load_ushort v155, v[160:161], off offset:192
	v_mov_b32_e32 v156, v112
	v_mov_b32_e32 v157, v96
	v_pk_mul_f32 v[156:157], v[156:157], v[130:131] op_sel_hi:[1,0]
	v_mov_b32_e32 v162, v80
	v_mov_b32_e32 v163, v64
	v_pk_mul_f32 v[162:163], v[162:163], v[130:131] op_sel_hi:[1,0]
	v_mov_b32_e32 v164, v113
	v_mov_b32_e32 v165, v97
	v_pk_mul_f32 v[164:165], v[164:165], v[178:179] op_sel_hi:[1,0]
	v_mov_b32_e32 v182, v81
	v_mov_b32_e32 v183, v65
	v_pk_mul_f32 v[182:183], v[182:183], v[178:179] op_sel_hi:[1,0]
	v_mov_b32_e32 v186, v49
	v_mov_b32_e32 v187, v33
	v_pk_mul_f32 v[186:187], v[186:187], v[178:179] op_sel_hi:[1,0]
	v_lshl_add_u64 v[158:159], v[148:149], 0, v[158:159]
	s_waitcnt vmcnt(1)
	v_lshlrev_b32_e32 v154, 16, v154
	s_waitcnt vmcnt(0)
	v_lshlrev_b32_e32 v155, 16, v155
	v_pk_fma_f32 v[154:155], v[218:219], v[156:157], v[154:155] neg_lo:[1,0,0] neg_hi:[1,0,0]
	global_load_ushort v156, v[160:161], off offset:256
	global_load_ushort v157, v[160:161], off offset:320
	v_pk_mul_f32 v[168:169], v[154:155], v[154:155]
	s_waitcnt vmcnt(1)
	v_lshlrev_b32_e32 v156, 16, v156
	s_waitcnt vmcnt(0)
	v_lshlrev_b32_e32 v157, 16, v157
	v_pk_fma_f32 v[156:157], v[218:219], v[162:163], v[156:157] neg_lo:[1,0,0] neg_hi:[1,0,0]
	global_load_ushort v162, v[160:161], off offset:384
	s_nop 0
	global_load_ushort v160, v[160:161], off offset:448
	v_mov_b32_e32 v163, v32
	v_mov_b32_e32 v180, v168
	v_pk_mul_f32 v[170:171], v[156:157], v[156:157]
	s_waitcnt vmcnt(0)
	v_lshlrev_b32_e32 v161, 16, v160
	v_lshlrev_b32_e32 v160, 16, v162
	v_mov_b32_e32 v162, v48
	v_pk_mul_f32 v[162:163], v[162:163], v[130:131] op_sel_hi:[1,0]
	s_nop 0
	v_pk_fma_f32 v[160:161], v[218:219], v[162:163], v[160:161] neg_lo:[1,0,0] neg_hi:[1,0,0]
	v_or_b32_e32 v162, 0x1b000, v146
	v_mov_b32_e32 v163, v1
	v_lshl_add_u64 v[184:185], v[150:151], 0, v[162:163]
	global_load_ushort v166, v[184:185], off
	global_load_ushort v175, v[184:185], off offset:64
	global_load_ushort v150, v[184:185], off offset:128
	global_load_ushort v151, v[184:185], off offset:192
	v_pk_mul_f32 v[172:173], v[160:161], v[160:161]
	v_lshl_add_u64 v[148:149], v[148:149], 0, v[162:163]
	s_waitcnt vmcnt(1)
	v_lshlrev_b32_e32 v150, 16, v150
	s_waitcnt vmcnt(0)
	v_lshlrev_b32_e32 v151, 16, v151
	v_pk_fma_f32 v[150:151], v[218:219], v[164:165], v[150:151] neg_lo:[1,0,0] neg_hi:[1,0,0]
	v_lshlrev_b32_e32 v164, 16, v147
	global_load_ushort v147, v[184:185], off offset:256
	global_load_ushort v168, v[184:185], off offset:320
	v_lshlrev_b32_e32 v165, 16, v166
	v_pk_mul_f32 v[166:167], v[16:17], v[130:131]
	v_pk_mul_f32 v[176:177], v[150:151], v[150:151]
	v_pk_fma_f32 v[164:165], v[218:219], v[166:167], v[164:165] neg_lo:[1,0,0] neg_hi:[1,0,0]
	v_lshlrev_b32_e32 v167, 16, v175
	v_lshlrev_b32_e32 v166, 16, v174
	v_pk_mul_f32 v[174:175], v[128:129], v[130:131]
	v_mov_b32_e32 v181, v176
	v_pk_fma_f32 v[166:167], v[218:219], v[174:175], v[166:167] neg_lo:[1,0,0] neg_hi:[1,0,0]
	s_nop 0
	v_pk_mul_f32 v[174:175], v[166:167], v[166:167]
	s_nop 0
	v_pk_fma_f32 v[174:175], v[164:165], v[164:165], v[174:175]
	s_nop 0
	v_pk_add_f32 v[180:181], v[174:175], v[180:181]
	s_waitcnt vmcnt(1)
; __device__ __forceinline__ bf16_t f2bf(float x) { return (bf16_t)(cvt_pk_bf16(x, x) & 0xffffu); }
; __device__ __forceinline__ float bf2f(bf16_t b) { return __uint_as_float(((unsigned)b) << 16); }
; __device__ __forceinline__ int crow(int r, int hi) { return (r & 3) + 8 * (r >> 2) + 4 * hi; }
; __device__ __forceinline__ int crow(int r, int hi) { return (r & 3) + 8 * (r >> 2) + 4 * hi; }
; __device__ __forceinline__ void attn_body256(const bf16_t* __restrict__ Qb, const bf16_t* __restrict__ Kh, const bf16_t* __restrict__ Vh,
;                                              bf16_t* Ob, int seq, unsigned char* lds, float lam, int MODE, bf16_t* Ab, const float* wsub) {
;     ...
;     bf16_t* Aw = Ab + (long)(wid * QBLK) * LDO;
;     float wv[8];
; #pragma unroll
;     for (int d0 = 0; d0 < 8; ++d0) wv[d0] = wsub[d0 * 32 + r32] * (1.f - LAMBDA_INIT);
; #pragma unroll
;     for (int r = 0; r < 16; ++r) { const int orow = crow(r, hi); float ss = 0.f;
; #pragma unroll
;       for (int d0 = 0; d0 < 8; ++d0) { const float v = bf2f(Ow[(long)orow * LDO + d0 * 32 + r32]) - lam * (o[d0][r] * rli[r]); o[d0][r] = v; ss += v * v; }
;       ss += __shfl_xor(ss, 1, 64); ss += __shfl_xor(ss, 2, 64); ss += __shfl_xor(ss, 4, 64); ss += __shfl_xor(ss, 8, 64); ss += __shfl_xor(ss, 16, 64);
;       const float rstd = rsqrtf(ss * (1.f / 256.f) + NORM_EPS);
; #pragma unroll
;       for (int d0 = 0; d0 < 8; ++d0) Aw[(long)orow * LDO + d0 * 32 + r32] = f2bf(o[d0][r] * rstd * wv[d0]); }
	v_lshlrev_b32_e32 v174, 16, v147
	s_waitcnt vmcnt(0)
	v_lshlrev_b32_e32 v175, 16, v168
	global_load_ushort v147, v[184:185], off offset:384
	global_load_ushort v168, v[184:185], off offset:448
	v_pk_fma_f32 v[174:175], v[218:219], v[182:183], v[174:175] neg_lo:[1,0,0] neg_hi:[1,0,0]
	s_waitcnt vmcnt(1)
	v_lshlrev_b32_e32 v184, 16, v147
	v_pk_mul_f32 v[182:183], v[174:175], v[174:175]
	s_waitcnt vmcnt(0)
	v_lshlrev_b32_e32 v185, 16, v168
	v_mov_b32_e32 v168, v177
	v_pk_fma_f32 v[184:185], v[218:219], v[186:187], v[184:185] neg_lo:[1,0,0] neg_hi:[1,0,0]
	v_pk_add_f32 v[168:169], v[180:181], v[168:169] op_sel:[1,0] op_sel_hi:[0,1]
	v_mov_b32_e32 v176, v182
	v_mov_b32_e32 v177, v170
	v_pk_mul_f32 v[186:187], v[184:185], v[184:185]
	v_pk_add_f32 v[168:169], v[168:169], v[176:177]
	v_mov_b32_e32 v170, v183
	v_pk_add_f32 v[168:169], v[168:169], v[170:171]
	v_mov_b32_e32 v170, v186
	v_mov_b32_e32 v171, v172
	v_pk_add_f32 v[168:169], v[168:169], v[170:171]
	v_mov_b32_e32 v172, v187
	v_pk_add_f32 v[168:169], v[168:169], v[172:173]
	ds_bpermute_b32 v171, v199, v169
	ds_bpermute_b32 v170, v199, v168
	s_waitcnt lgkmcnt(0)
	v_pk_add_f32 v[168:169], v[168:169], v[170:171]
	ds_bpermute_b32 v171, v198, v169
	ds_bpermute_b32 v170, v198, v168
	s_waitcnt lgkmcnt(0)
	v_pk_add_f32 v[168:169], v[168:169], v[170:171]
	ds_bpermute_b32 v171, v197, v169
	ds_bpermute_b32 v170, v197, v168
	s_waitcnt lgkmcnt(0)
	v_pk_add_f32 v[168:169], v[168:169], v[170:171]
	ds_bpermute_b32 v171, v196, v169
	ds_bpermute_b32 v170, v196, v168
	s_waitcnt lgkmcnt(0)
	v_pk_add_f32 v[168:169], v[168:169], v[170:171]
	ds_bpermute_b32 v171, v195, v169
	ds_bpermute_b32 v170, v195, v168
	s_waitcnt lgkmcnt(0)
	v_pk_add_f32 v[168:169], v[168:169], v[170:171]
	s_nop 0
	v_pk_fma_f32 v[152:153], v[168:169], s[2:3], v[152:153] op_sel_hi:[1,0,0]
	s_nop 0
	v_mul_f32_e32 v147, 0x4b800000, v153
	v_cmp_gt_f32_e64 s[0:1], s58, v153
	v_cmp_gt_f32_e32 vcc, s58, v152
	s_nop 0
	v_cndmask_b32_e64 v147, v153, v147, s[0:1]
	v_rsq_f32_e32 v147, v147
	s_nop 0
	v_mul_f32_e32 v153, 0x45800000, v147
	v_cndmask_b32_e64 v147, v147, v153, s[0:1]
	v_mul_f32_e32 v153, v164, v147
	v_mul_f32_e32 v153, v179, v153
	v_cvt_pk_bf16_f32 v153, v153, s0
	global_store_short v[158:159], v153, off
	v_mul_f32_e32 v153, v166, v147
	v_mul_f32_e32 v153, v188, v153
	v_cvt_pk_bf16_f32 v153, v153, s0
	global_store_short v[158:159], v153, off offset:64
	v_mul_f32_e32 v153, v154, v147
	v_mul_f32_e32 v153, v189, v153
	v_cvt_pk_bf16_f32 v153, v153, s0
	global_store_short v[158:159], v153, off offset:128
	v_mul_f32_e32 v153, v155, v147
	v_mul_f32_e32 v153, v190, v153
	v_cvt_pk_bf16_f32 v153, v153, s0
	global_store_short v[158:159], v153, off offset:192
	v_mul_f32_e32 v153, v156, v147
	v_mul_f32_e32 v153, v191, v153
	v_cvt_pk_bf16_f32 v153, v153, s0
	global_store_short v[158:159], v153, off offset:256
	v_mul_f32_e32 v153, v157, v147
	v_mul_f32_e32 v153, v192, v153
	v_cvt_pk_bf16_f32 v153, v153, s0
	global_store_short v[158:159], v153, off offset:320
	v_mul_f32_e32 v153, v160, v147
	v_mul_f32_e32 v147, v161, v147
	v_mul_f32_e32 v147, v194, v147
	v_cvt_pk_bf16_f32 v147, v147, s0
	global_store_short v[158:159], v147, off offset:448
	v_mul_f32_e32 v147, 0x4b800000, v152
	v_cndmask_b32_e32 v147, v152, v147, vcc
	v_rsq_f32_e32 v147, v147
	v_mul_f32_e32 v153, v193, v153
	v_cvt_pk_bf16_f32 v153, v153, s0
	global_store_short v[158:159], v153, off offset:384
	v_mul_f32_e32 v152, 0x45800000, v147
	v_cndmask_b32_e32 v147, v147, v152, vcc
	v_mul_f32_e32 v150, v150, v147
	v_mul_f32_e32 v150, v189, v150
	v_cvt_pk_bf16_f32 v150, v150, s0
	global_store_short v[148:149], v150, off offset:128
	v_mul_f32_e32 v150, v151, v147
	v_mul_f32_e32 v150, v190, v150
	v_cvt_pk_bf16_f32 v150, v150, s0
	global_store_short v[148:149], v150, off offset:192
	v_mul_f32_e32 v150, v174, v147
	v_mul_f32_e32 v150, v191, v150
	v_cvt_pk_bf16_f32 v150, v150, s0
	v_mul_f32_e32 v152, v165, v147
	global_store_short v[148:149], v150, off offset:256
	v_mul_f32_e32 v150, v175, v147
	v_mul_f32_e32 v152, v179, v152
	v_mul_f32_e32 v150, v192, v150
	v_cvt_pk_bf16_f32 v152, v152, s0
	v_cvt_pk_bf16_f32 v150, v150, s0
	global_store_short v[148:149], v152, off
	v_mul_f32_e32 v152, v167, v147
	global_store_short v[148:149], v150, off offset:320
	v_mul_f32_e32 v150, v184, v147
	v_mul_f32_e32 v147, v185, v147
	v_mul_f32_e32 v152, v188, v152
	v_mul_f32_e32 v150, v193, v150
	v_mul_f32_e32 v147, v194, v147
	v_cvt_pk_bf16_f32 v152, v152, s0
	v_cvt_pk_bf16_f32 v150, v150, s0
	v_cvt_pk_bf16_f32 v147, v147, s0
	global_store_short v[148:149], v152, off offset:64
	global_store_short v[148:149], v150, off offset:384
	global_store_short v[148:149], v147, off offset:448

; __device__ __forceinline__ void xcd_barrier(const XcdBarrier& b) {
;     asm volatile("s_waitcnt vmcnt(0)" ::: "memory");
;     __syncthreads();
;     if (threadIdx.x == 0) {
;         unsigned* bar = b.bar;
;         __builtin_amdgcn_s_waitcnt(0);
;         unsigned nloc = b.st[0], nx = b.st[1];
;         if (nloc == 0u) { xcd_barrier_complete(bar, b.x, nloc, nx); b.st[0] = nloc; b.st[1] = nx; }
.LBB0_684:
	v_mov_b64_e32 v[210:211], 0x3ff
	v_mov_b64_e32 v[212:213], 0x400
	v_mov_b32_e32 v244, 0x3727c5ac
	s_getreg_b32 s2, hwreg(HW_REG_XCC_ID, 0, 4)
	s_waitcnt vmcnt(0)
	s_barrier
	s_mov_b64 s[0:1], exec
	v_readlane_b32 s6, v252, 0
	v_readlane_b32 s7, v252, 1
	s_and_b64 s[6:7], s[0:1], s[6:7]
	s_mov_b64 exec, s[6:7]
	s_cbranch_execz .LBB0_736
	v_readlane_b32 s6, v254, 43
	s_waitcnt vmcnt(0) expcnt(0) lgkmcnt(0)
	s_and_b32 s2, s2, 15
	v_mov_b32_e32 v0, s6
	ds_read_b32 v3, v0
	v_readlane_b32 s6, v254, 44
	s_waitcnt lgkmcnt(0)
	v_cmp_ne_u32_e32 vcc, 0, v3
	v_mov_b32_e32 v0, s6
	ds_read_b32 v2, v0
	s_cbranch_vccnz .LBB0_700
	s_mov_b32 s12, 1
	s_branch .LBB0_688
